# redundant mid-block s_setprio 0/1 pairs removed from all GEMM loops (on v6)
# baseline (speedup 1.0000x reference)
; #define PG8_STAGE(bufoff, gbase, voff) do { _Pragma("unroll") for (int _i = 0; _i < 2; ++_i) \
;         __builtin_amdgcn_global_load_lds((const unsigned*)((const char*)(gbase) + (voff)[_i]), (LAS unsigned*)(lds + (bufoff) + ldsw + _i * 8192), 16, 0, 0); } while (0)
; #define PG8_LDA(dst, b, h) do { _Pragma("unroll") for (int m = 0; m < 4; ++m) _Pragma("unroll") for (int k = 0; k < 2; ++k) dst[m][k] = *(const LAS bf16x8*)(lds + PG8_SA(b, h) + aoff + m * 2048 + k * 1024); } while (0)
; #define PG8_LDB(dst, b, h) do { _Pragma("unroll") for (int n = 0; n < 2; ++n) _Pragma("unroll") for (int k = 0; k < 2; ++k) dst[n][k] = *(const LAS bf16x8*)(lds + PG8_SB(b, h) + boff + n * 2048 + k * 1024); } while (0)
; #define PG8_MMA(ai, bj, At, Bt) do { __builtin_amdgcn_s_setprio(1); _Pragma("unroll") for (int m = 0; m < 4; ++m) _Pragma("unroll") for (int n = 0; n < 2; ++n) _Pragma("unroll") for (int k = 0; k < 2; ++k) \
;         acc[ai][bj][m][n] = __builtin_amdgcn_mfma_f32_16x16x32_bf16(Bt[n][k], At[m][k], acc[ai][bj][m][n], 0, 0, 0); __builtin_amdgcn_s_setprio(0); } while (0)
; #define PG8_WAIT_V(n) asm volatile("s_waitcnt vmcnt(" #n ")" ::: "memory")
; #define PG8_WAIT_L(n) asm volatile("s_waitcnt lgkmcnt(" #n ")" ::: "memory")
; #define PG8_BAR __builtin_amdgcn_s_barrier()
; #define PG8_SCHED __builtin_amdgcn_sched_barrier(0)
; template <class Epi>
; __device__ __forceinline__ void gemm_phase(LAS unsigned char* lds, const Gemm g, const Order& S, const Epi& E) {
;     ...
;         for (int t = 0; t < nt; t += 2) {
;             const bool last = (t == nt - 2);
;             const char* a1 = cA + (size_t)(t + 1) * kstep;
;             const char* a2 = last ? nA : cA + (size_t)(t + 2) * kstep; const char* b2 = last ? nB : cB + (size_t)(t + 2) * kstep;
;             const char* a3 = a2 + kstep; const char* b3 = b2 + kstep;
;             PG8_LDB(B0, 0, 0); PG8_LDB(B1, 0, 1); PG8_SCHED; PG8_LDA(At, 0, 0); PG8_STAGE(PG8_SA(1, 1), a1 + hstepA, voffA);
;             PG8_WAIT_V(8); PG8_WAIT_L(0); PG8_BAR; PG8_MMA(0, 0, At, B0); PG8_MMA(0, 1, At, B1); PG8_BAR; PG8_SCHED;
;             PG8_LDA(At, 0, 1); PG8_STAGE(PG8_SB(0, 0), b2, voffB); PG8_STAGE(PG8_SB(0, 1), b2 + hstepB, voffB); PG8_STAGE(PG8_SA(0, 0), a2, voffA);
.LBB0_136:
	ds_read_b128 v[128:131], v163
	ds_read_b128 v[132:135], v163 offset:1024
	ds_read_b128 v[154:157], v163 offset:2048
	ds_read_b128 v[168:171], v163 offset:3072
	ds_read_b128 v[172:175], v164
	ds_read_b128 v[178:181], v164 offset:1024
	ds_read_b128 v[182:185], v164 offset:2048
	ds_read_b128 v[186:189], v164 offset:3072
	s_add_u32 s10, s8, 0xfff80080
	s_addc_u32 s11, s9, -1
	s_cmp_eq_u32 s52, 28
	s_cselect_b32 s13, s1, s11
	s_cselect_b32 s12, s2, s10
	s_cselect_b32 s11, s7, s33
	s_cselect_b32 s10, s29, s31
	v_lshl_add_u64 v[158:159], s[8:9], 0, v[146:147]
	s_add_i32 m0, s46, 0xc000
	ds_read_b128 v[190:193], v165
	ds_read_b128 v[194:197], v165 offset:1024
	ds_read_b128 v[198:201], v165 offset:2048
	ds_read_b128 v[202:205], v165 offset:3072
	ds_read_b128 v[208:211], v165 offset:4096
	ds_read_b128 v[212:215], v165 offset:5120
	ds_read_b128 v[216:219], v165 offset:6144
	ds_read_b128 v[220:223], v165 offset:7168
	global_load_lds_dwordx4 v[158:159], off
	v_lshl_add_u64 v[158:159], s[8:9], 0, v[148:149]
	s_add_i32 m0, s46, 0xe000
	s_nop 0
	global_load_lds_dwordx4 v[158:159], off
	s_waitcnt vmcnt(8)
	s_waitcnt lgkmcnt(0)
	s_barrier
	s_setprio 1
	s_waitcnt lgkmcnt(0)
	v_mfma_f32_16x16x32_bf16 v[124:127], v[128:131], v[190:193], v[124:127]
	v_mfma_f32_16x16x32_bf16 v[120:123], v[154:157], v[190:193], v[120:123]
	v_mfma_f32_16x16x32_bf16 v[116:119], v[128:131], v[198:201], v[116:119]
	v_mfma_f32_16x16x32_bf16 v[112:115], v[154:157], v[198:201], v[112:115]
	v_mfma_f32_16x16x32_bf16 v[108:111], v[128:131], v[208:211], v[108:111]
	v_mfma_f32_16x16x32_bf16 v[104:107], v[154:157], v[208:211], v[104:107]
	v_mfma_f32_16x16x32_bf16 v[100:103], v[128:131], v[216:219], v[100:103]
	v_mfma_f32_16x16x32_bf16 v[96:99], v[154:157], v[216:219], v[96:99]
	v_mfma_f32_16x16x32_bf16 v[124:127], v[132:135], v[194:197], v[124:127]
	v_mfma_f32_16x16x32_bf16 v[120:123], v[168:171], v[194:197], v[120:123]
	v_mfma_f32_16x16x32_bf16 v[116:119], v[132:135], v[202:205], v[116:119]
	v_mfma_f32_16x16x32_bf16 v[112:115], v[168:171], v[202:205], v[112:115]
	v_mfma_f32_16x16x32_bf16 v[108:111], v[132:135], v[212:215], v[108:111]
	v_mfma_f32_16x16x32_bf16 v[104:107], v[168:171], v[212:215], v[104:107]
	v_mfma_f32_16x16x32_bf16 v[100:103], v[132:135], v[220:223], v[100:103]
	v_mfma_f32_16x16x32_bf16 v[96:99], v[168:171], v[220:223], v[96:99]
	v_mfma_f32_16x16x32_bf16 v[60:63], v[172:175], v[190:193], v[60:63]
	v_mfma_f32_16x16x32_bf16 v[56:59], v[182:185], v[190:193], v[56:59]
	v_mfma_f32_16x16x32_bf16 v[52:55], v[172:175], v[198:201], v[52:55]
	v_mfma_f32_16x16x32_bf16 v[48:51], v[182:185], v[198:201], v[48:51]
	v_mfma_f32_16x16x32_bf16 v[44:47], v[172:175], v[208:211], v[44:47]
	v_mfma_f32_16x16x32_bf16 v[40:43], v[182:185], v[208:211], v[40:43]
	v_mfma_f32_16x16x32_bf16 v[36:39], v[172:175], v[216:219], v[36:39]
	v_mfma_f32_16x16x32_bf16 v[32:35], v[182:185], v[216:219], v[32:35]
	v_mfma_f32_16x16x32_bf16 v[60:63], v[178:181], v[194:197], v[60:63]
	v_mfma_f32_16x16x32_bf16 v[56:59], v[186:189], v[194:197], v[56:59]
	v_mfma_f32_16x16x32_bf16 v[52:55], v[178:181], v[202:205], v[52:55]
	v_mfma_f32_16x16x32_bf16 v[48:51], v[186:189], v[202:205], v[48:51]
	v_mfma_f32_16x16x32_bf16 v[44:47], v[178:181], v[212:215], v[44:47]
	v_mfma_f32_16x16x32_bf16 v[40:43], v[186:189], v[212:215], v[40:43]
	v_mfma_f32_16x16x32_bf16 v[36:39], v[178:181], v[220:223], v[36:39]
	v_mfma_f32_16x16x32_bf16 v[32:35], v[186:189], v[220:223], v[32:35]
	s_setprio 0
	s_barrier
	s_add_i32 s53, s57, s43
	v_lshl_add_u64 v[158:159], s[10:11], 0, v[138:139]
	s_mov_b32 m0, s53
	ds_read_b128 v[190:193], v165 offset:16384
	ds_read_b128 v[194:197], v165 offset:17408
	ds_read_b128 v[198:201], v165 offset:18432
	ds_read_b128 v[202:205], v165 offset:19456
	ds_read_b128 v[208:211], v165 offset:20480
	ds_read_b128 v[212:215], v165 offset:21504
	ds_read_b128 v[216:219], v165 offset:22528
	ds_read_b128 v[220:223], v165 offset:23552
	global_load_lds_dwordx4 v[158:159], off
	s_add_i32 m0, s53, 0x2000
	s_add_u32 s62, s10, 0x80000
	v_lshl_add_u64 v[224:225], s[10:11], 0, v[142:143]
	s_addc_u32 s63, s11, 0
	s_add_i32 s53, s58, s43
	global_load_lds_dwordx4 v[224:225], off
	v_lshl_add_u64 v[226:227], s[62:63], 0, v[138:139]
	s_mov_b32 m0, s53
	v_lshl_add_u64 v[228:229], s[12:13], 0, v[140:141]
	global_load_lds_dwordx4 v[226:227], off
	v_lshl_add_u64 v[226:227], s[62:63], 0, v[142:143]
	s_add_i32 m0, s53, 0x2000
	s_nop 0
	global_load_lds_dwordx4 v[226:227], off
	v_lshl_add_u64 v[226:227], s[12:13], 0, v[136:137]
	s_mov_b32 m0, s46
	s_nop 0
	global_load_lds_dwordx4 v[226:227], off
	s_mov_b32 m0, s47
	s_nop 0
	global_load_lds_dwordx4 v[228:229], off
	s_waitcnt vmcnt(8)
	s_waitcnt lgkmcnt(0)
	s_barrier
; #define PG8_STAGE(bufoff, gbase, voff) do { _Pragma("unroll") for (int _i = 0; _i < 2; ++_i) \
;         __builtin_amdgcn_global_load_lds((const unsigned*)((const char*)(gbase) + (voff)[_i]), (LAS unsigned*)(lds + (bufoff) + ldsw + _i * 8192), 16, 0, 0); } while (0)
; #define PG8_LDA(dst, b, h) do { _Pragma("unroll") for (int m = 0; m < 4; ++m) _Pragma("unroll") for (int k = 0; k < 2; ++k) dst[m][k] = *(const LAS bf16x8*)(lds + PG8_SA(b, h) + aoff + m * 2048 + k * 1024); } while (0)
; #define PG8_LDB(dst, b, h) do { _Pragma("unroll") for (int n = 0; n < 2; ++n) _Pragma("unroll") for (int k = 0; k < 2; ++k) dst[n][k] = *(const LAS bf16x8*)(lds + PG8_SB(b, h) + boff + n * 2048 + k * 1024); } while (0)
; #define PG8_MMA(ai, bj, At, Bt) do { __builtin_amdgcn_s_setprio(1); _Pragma("unroll") for (int m = 0; m < 4; ++m) _Pragma("unroll") for (int n = 0; n < 2; ++n) _Pragma("unroll") for (int k = 0; k < 2; ++k) \
;         acc[ai][bj][m][n] = __builtin_amdgcn_mfma_f32_16x16x32_bf16(Bt[n][k], At[m][k], acc[ai][bj][m][n], 0, 0, 0); __builtin_amdgcn_s_setprio(0); } while (0)
; #define PG8_WAIT_V(n) asm volatile("s_waitcnt vmcnt(" #n ")" ::: "memory")
; #define PG8_WAIT_L(n) asm volatile("s_waitcnt lgkmcnt(" #n ")" ::: "memory")
; #define PG8_BAR __builtin_amdgcn_s_barrier()
; #define PG8_SCHED __builtin_amdgcn_sched_barrier(0)
; template <class Epi>
; __device__ __forceinline__ void gemm_phase(LAS unsigned char* lds, const Gemm g, const Order& S, const Epi& E) {
;     ...
;             PG8_WAIT_V(8); PG8_WAIT_L(0); PG8_BAR; PG8_MMA(1, 0, At, B0); PG8_MMA(1, 1, At, B1); PG8_BAR; PG8_SCHED;
;             PG8_LDB(B0, 1, 0); PG8_LDB(B1, 1, 1); PG8_SCHED; PG8_LDA(At, 1, 0); PG8_STAGE(PG8_SA(0, 1), a2 + hstepA, voffA);
;             PG8_WAIT_V(8); PG8_WAIT_L(0); PG8_BAR; PG8_MMA(0, 0, At, B0); PG8_MMA(0, 1, At, B1); PG8_BAR; PG8_SCHED;
	s_setprio 1
	s_waitcnt lgkmcnt(0)
	v_mfma_f32_16x16x32_bf16 v[92:95], v[128:131], v[190:193], v[92:95]
	v_mfma_f32_16x16x32_bf16 v[88:91], v[154:157], v[190:193], v[88:91]
	v_mfma_f32_16x16x32_bf16 v[84:87], v[128:131], v[198:201], v[84:87]
	v_mfma_f32_16x16x32_bf16 v[80:83], v[154:157], v[198:201], v[80:83]
	v_mfma_f32_16x16x32_bf16 v[76:79], v[128:131], v[208:211], v[76:79]
	v_mfma_f32_16x16x32_bf16 v[72:75], v[154:157], v[208:211], v[72:75]
	v_mfma_f32_16x16x32_bf16 v[68:71], v[128:131], v[216:219], v[68:71]
	v_mfma_f32_16x16x32_bf16 v[64:67], v[154:157], v[216:219], v[64:67]
	v_mfma_f32_16x16x32_bf16 v[92:95], v[132:135], v[194:197], v[92:95]
	v_mfma_f32_16x16x32_bf16 v[88:91], v[168:171], v[194:197], v[88:91]
	v_mfma_f32_16x16x32_bf16 v[84:87], v[132:135], v[202:205], v[84:87]
	v_mfma_f32_16x16x32_bf16 v[80:83], v[168:171], v[202:205], v[80:83]
	v_mfma_f32_16x16x32_bf16 v[76:79], v[132:135], v[212:215], v[76:79]
	v_mfma_f32_16x16x32_bf16 v[72:75], v[168:171], v[212:215], v[72:75]
	v_mfma_f32_16x16x32_bf16 v[68:71], v[132:135], v[220:223], v[68:71]
	v_mfma_f32_16x16x32_bf16 v[64:67], v[168:171], v[220:223], v[64:67]
	v_mfma_f32_16x16x32_bf16 v[28:31], v[172:175], v[190:193], v[28:31]
	v_mfma_f32_16x16x32_bf16 v[24:27], v[182:185], v[190:193], v[24:27]
	v_mfma_f32_16x16x32_bf16 v[20:23], v[172:175], v[198:201], v[20:23]
	v_mfma_f32_16x16x32_bf16 v[16:19], v[182:185], v[198:201], v[16:19]
	v_mfma_f32_16x16x32_bf16 v[12:15], v[172:175], v[208:211], v[12:15]
	v_mfma_f32_16x16x32_bf16 v[8:11], v[182:185], v[208:211], v[8:11]
	v_mfma_f32_16x16x32_bf16 v[4:7], v[172:175], v[216:219], v[4:7]
	v_mfma_f32_16x16x32_bf16 v[0:3], v[182:185], v[216:219], v[0:3]
	v_mfma_f32_16x16x32_bf16 v[28:31], v[178:181], v[194:197], v[28:31]
	v_mfma_f32_16x16x32_bf16 v[24:27], v[186:189], v[194:197], v[24:27]
	v_mfma_f32_16x16x32_bf16 v[20:23], v[178:181], v[202:205], v[20:23]
	v_mfma_f32_16x16x32_bf16 v[16:19], v[186:189], v[202:205], v[16:19]
	v_mfma_f32_16x16x32_bf16 v[12:15], v[178:181], v[212:215], v[12:15]
	v_mfma_f32_16x16x32_bf16 v[8:11], v[186:189], v[212:215], v[8:11]
	v_mfma_f32_16x16x32_bf16 v[4:7], v[178:181], v[220:223], v[4:7]
	v_mfma_f32_16x16x32_bf16 v[0:3], v[186:189], v[220:223], v[0:3]
	s_setprio 0
	s_barrier
	s_add_i32 s53, 0, 0x18000
	v_add_u32_e32 v144, s53, v161
	s_add_i32 s62, 0, 0x1c000
	ds_read_b128 v[128:131], v144
	ds_read_b128 v[132:135], v144 offset:1024
	ds_read_b128 v[154:157], v144 offset:2048
	ds_read_b128 v[168:171], v144 offset:3072
	v_add_u32_e32 v144, s62, v161
	ds_read_b128 v[172:175], v144
	ds_read_b128 v[178:181], v144 offset:1024
	ds_read_b128 v[182:185], v144 offset:2048
	ds_read_b128 v[186:189], v144 offset:3072
	s_add_u32 s12, s12, 0x80000
	s_addc_u32 s13, s13, 0
	s_mov_b32 m0, s48
	v_lshl_add_u64 v[230:231], s[12:13], 0, v[136:137]
	ds_read_b128 v[190:193], v165 offset:32768
	ds_read_b128 v[194:197], v165 offset:33792
	ds_read_b128 v[198:201], v165 offset:34816
	ds_read_b128 v[202:205], v165 offset:35840
	ds_read_b128 v[208:211], v165 offset:36864
	ds_read_b128 v[212:215], v165 offset:37888
	ds_read_b128 v[216:219], v165 offset:38912
	ds_read_b128 v[220:223], v165 offset:39936
	global_load_lds_dwordx4 v[230:231], off
	v_lshl_add_u64 v[230:231], s[12:13], 0, v[140:141]
	s_mov_b32 m0, s49
	s_nop 0
	global_load_lds_dwordx4 v[230:231], off
	s_waitcnt vmcnt(8)
	s_waitcnt lgkmcnt(0)
	s_barrier
	s_setprio 1
	s_waitcnt lgkmcnt(0)
	v_mfma_f32_16x16x32_bf16 v[124:127], v[128:131], v[190:193], v[124:127]
	v_mfma_f32_16x16x32_bf16 v[120:123], v[154:157], v[190:193], v[120:123]
	v_mfma_f32_16x16x32_bf16 v[116:119], v[128:131], v[198:201], v[116:119]
	v_mfma_f32_16x16x32_bf16 v[112:115], v[154:157], v[198:201], v[112:115]
	v_mfma_f32_16x16x32_bf16 v[108:111], v[128:131], v[208:211], v[108:111]
	v_mfma_f32_16x16x32_bf16 v[104:107], v[154:157], v[208:211], v[104:107]
	v_mfma_f32_16x16x32_bf16 v[100:103], v[128:131], v[216:219], v[100:103]
	v_mfma_f32_16x16x32_bf16 v[96:99], v[154:157], v[216:219], v[96:99]
	v_mfma_f32_16x16x32_bf16 v[124:127], v[132:135], v[194:197], v[124:127]
	v_mfma_f32_16x16x32_bf16 v[120:123], v[168:171], v[194:197], v[120:123]
	v_mfma_f32_16x16x32_bf16 v[116:119], v[132:135], v[202:205], v[116:119]
	v_mfma_f32_16x16x32_bf16 v[112:115], v[168:171], v[202:205], v[112:115]
	v_mfma_f32_16x16x32_bf16 v[108:111], v[132:135], v[212:215], v[108:111]
	v_mfma_f32_16x16x32_bf16 v[104:107], v[168:171], v[212:215], v[104:107]
	v_mfma_f32_16x16x32_bf16 v[100:103], v[132:135], v[220:223], v[100:103]
	v_mfma_f32_16x16x32_bf16 v[96:99], v[168:171], v[220:223], v[96:99]
	v_mfma_f32_16x16x32_bf16 v[60:63], v[172:175], v[190:193], v[60:63]
	v_mfma_f32_16x16x32_bf16 v[56:59], v[182:185], v[190:193], v[56:59]
	v_mfma_f32_16x16x32_bf16 v[52:55], v[172:175], v[198:201], v[52:55]
	v_mfma_f32_16x16x32_bf16 v[48:51], v[182:185], v[198:201], v[48:51]
	v_mfma_f32_16x16x32_bf16 v[44:47], v[172:175], v[208:211], v[44:47]
	v_mfma_f32_16x16x32_bf16 v[40:43], v[182:185], v[208:211], v[40:43]
	v_mfma_f32_16x16x32_bf16 v[36:39], v[172:175], v[216:219], v[36:39]
	v_mfma_f32_16x16x32_bf16 v[32:35], v[182:185], v[216:219], v[32:35]
	v_mfma_f32_16x16x32_bf16 v[60:63], v[178:181], v[194:197], v[60:63]
	v_mfma_f32_16x16x32_bf16 v[56:59], v[186:189], v[194:197], v[56:59]
	v_mfma_f32_16x16x32_bf16 v[52:55], v[178:181], v[202:205], v[52:55]
	v_mfma_f32_16x16x32_bf16 v[48:51], v[186:189], v[202:205], v[48:51]
	v_mfma_f32_16x16x32_bf16 v[44:47], v[178:181], v[212:215], v[44:47]
	v_mfma_f32_16x16x32_bf16 v[40:43], v[186:189], v[212:215], v[40:43]
	v_mfma_f32_16x16x32_bf16 v[36:39], v[178:181], v[220:223], v[36:39]
	v_mfma_f32_16x16x32_bf16 v[32:35], v[186:189], v[220:223], v[32:35]
	s_setprio 0
	s_barrier
; #define PG8_STAGE(bufoff, gbase, voff) do { _Pragma("unroll") for (int _i = 0; _i < 2; ++_i) \
;         __builtin_amdgcn_global_load_lds((const unsigned*)((const char*)(gbase) + (voff)[_i]), (LAS unsigned*)(lds + (bufoff) + ldsw + _i * 8192), 16, 0, 0); } while (0)
; #define PG8_LDA(dst, b, h) do { _Pragma("unroll") for (int m = 0; m < 4; ++m) _Pragma("unroll") for (int k = 0; k < 2; ++k) dst[m][k] = *(const LAS bf16x8*)(lds + PG8_SA(b, h) + aoff + m * 2048 + k * 1024); } while (0)
; #define PG8_MMA(ai, bj, At, Bt) do { __builtin_amdgcn_s_setprio(1); _Pragma("unroll") for (int m = 0; m < 4; ++m) _Pragma("unroll") for (int n = 0; n < 2; ++n) _Pragma("unroll") for (int k = 0; k < 2; ++k) \
;         acc[ai][bj][m][n] = __builtin_amdgcn_mfma_f32_16x16x32_bf16(Bt[n][k], At[m][k], acc[ai][bj][m][n], 0, 0, 0); __builtin_amdgcn_s_setprio(0); } while (0)
; #define PG8_WAIT_V(n) asm volatile("s_waitcnt vmcnt(" #n ")" ::: "memory")
; #define PG8_WAIT_L(n) asm volatile("s_waitcnt lgkmcnt(" #n ")" ::: "memory")
; #define PG8_BAR __builtin_amdgcn_s_barrier()
; #define PG8_SCHED __builtin_amdgcn_sched_barrier(0)
; template <class Epi>
; __device__ __forceinline__ void gemm_phase(LAS unsigned char* lds, const Gemm g, const Order& S, const Epi& E) {
;     ...
;             PG8_LDA(At, 1, 1); PG8_STAGE(PG8_SB(1, 0), b3, voffB); PG8_STAGE(PG8_SB(1, 1), b3 + hstepB, voffB); PG8_STAGE(PG8_SA(1, 0), a3, voffA);
;             PG8_WAIT_V(8); PG8_WAIT_L(0); PG8_BAR; PG8_MMA(1, 0, At, B0); PG8_MMA(1, 1, At, B1); PG8_BAR; PG8_SCHED;
;         }
;         if (wr == 0) PG8_BAR;
	s_add_i32 s12, s53, s43
	v_lshl_add_u64 v[158:159], v[158:159], 0, s[22:23]
	s_mov_b32 m0, s12
	ds_read_b128 v[190:193], v165 offset:49152
	ds_read_b128 v[194:197], v165 offset:50176
	ds_read_b128 v[198:201], v165 offset:51200
	ds_read_b128 v[202:205], v165 offset:52224
	ds_read_b128 v[208:211], v165 offset:53248
	ds_read_b128 v[212:215], v165 offset:54272
	ds_read_b128 v[216:219], v165 offset:55296
	ds_read_b128 v[220:223], v165 offset:56320
	global_load_lds_dwordx4 v[158:159], off
	s_add_i32 m0, s12, 0x2000
	s_add_u32 s10, s10, 0x80080
	v_lshl_add_u64 v[158:159], v[224:225], 0, s[22:23]
	s_addc_u32 s11, s11, 0
	s_add_i32 s12, s62, s43
	global_load_lds_dwordx4 v[158:159], off
	v_lshl_add_u64 v[158:159], s[10:11], 0, v[138:139]
	s_mov_b32 m0, s12
	s_nop 0
	global_load_lds_dwordx4 v[158:159], off
	v_lshl_add_u64 v[158:159], s[10:11], 0, v[142:143]
	s_add_i32 m0, s12, 0x2000
	s_nop 0
	global_load_lds_dwordx4 v[158:159], off
	v_lshl_add_u64 v[158:159], v[226:227], 0, s[22:23]
	s_mov_b32 m0, s51
	s_nop 0
	global_load_lds_dwordx4 v[158:159], off
	v_lshl_add_u64 v[158:159], v[228:229], 0, s[22:23]
	s_mov_b32 m0, s54
	s_nop 0
	global_load_lds_dwordx4 v[158:159], off
	s_waitcnt vmcnt(8)
	s_waitcnt lgkmcnt(0)
	s_barrier
	s_setprio 1
	s_waitcnt lgkmcnt(0)
	v_mfma_f32_16x16x32_bf16 v[92:95], v[128:131], v[190:193], v[92:95]
	v_mfma_f32_16x16x32_bf16 v[88:91], v[154:157], v[190:193], v[88:91]
	v_mfma_f32_16x16x32_bf16 v[84:87], v[128:131], v[198:201], v[84:87]
	v_mfma_f32_16x16x32_bf16 v[80:83], v[154:157], v[198:201], v[80:83]
	v_mfma_f32_16x16x32_bf16 v[76:79], v[128:131], v[208:211], v[76:79]
	v_mfma_f32_16x16x32_bf16 v[72:75], v[154:157], v[208:211], v[72:75]
	v_mfma_f32_16x16x32_bf16 v[68:71], v[128:131], v[216:219], v[68:71]
	v_mfma_f32_16x16x32_bf16 v[64:67], v[154:157], v[216:219], v[64:67]
	v_mfma_f32_16x16x32_bf16 v[92:95], v[132:135], v[194:197], v[92:95]
	v_mfma_f32_16x16x32_bf16 v[88:91], v[168:171], v[194:197], v[88:91]
	v_mfma_f32_16x16x32_bf16 v[84:87], v[132:135], v[202:205], v[84:87]
	v_mfma_f32_16x16x32_bf16 v[80:83], v[168:171], v[202:205], v[80:83]
	v_mfma_f32_16x16x32_bf16 v[76:79], v[132:135], v[212:215], v[76:79]
	v_mfma_f32_16x16x32_bf16 v[72:75], v[168:171], v[212:215], v[72:75]
	v_mfma_f32_16x16x32_bf16 v[68:71], v[132:135], v[220:223], v[68:71]
	v_mfma_f32_16x16x32_bf16 v[64:67], v[168:171], v[220:223], v[64:67]
	v_mfma_f32_16x16x32_bf16 v[28:31], v[172:175], v[190:193], v[28:31]
	v_mfma_f32_16x16x32_bf16 v[24:27], v[182:185], v[190:193], v[24:27]
	v_mfma_f32_16x16x32_bf16 v[20:23], v[172:175], v[198:201], v[20:23]
	v_mfma_f32_16x16x32_bf16 v[16:19], v[182:185], v[198:201], v[16:19]
	v_mfma_f32_16x16x32_bf16 v[12:15], v[172:175], v[208:211], v[12:15]
	v_mfma_f32_16x16x32_bf16 v[8:11], v[182:185], v[208:211], v[8:11]
	v_mfma_f32_16x16x32_bf16 v[4:7], v[172:175], v[216:219], v[4:7]
	v_mfma_f32_16x16x32_bf16 v[0:3], v[182:185], v[216:219], v[0:3]
	v_mfma_f32_16x16x32_bf16 v[28:31], v[178:181], v[194:197], v[28:31]
	v_mfma_f32_16x16x32_bf16 v[24:27], v[186:189], v[194:197], v[24:27]
	v_mfma_f32_16x16x32_bf16 v[20:23], v[178:181], v[202:205], v[20:23]
	v_mfma_f32_16x16x32_bf16 v[16:19], v[186:189], v[202:205], v[16:19]
	v_mfma_f32_16x16x32_bf16 v[12:15], v[178:181], v[212:215], v[12:15]
	v_mfma_f32_16x16x32_bf16 v[8:11], v[186:189], v[212:215], v[8:11]
	v_mfma_f32_16x16x32_bf16 v[4:7], v[178:181], v[220:223], v[4:7]
	v_mfma_f32_16x16x32_bf16 v[0:3], v[186:189], v[220:223], v[0:3]
	s_setprio 0
	s_barrier
	s_add_i32 s52, s52, 2
	s_add_u32 s8, s8, 0x100
	s_addc_u32 s9, s9, 0
	s_add_u32 s31, s31, 0x100
	s_addc_u32 s33, s33, 0
	s_cmp_gt_u32 s52, 29
	s_cbranch_scc0 .LBB0_136
	s_and_b64 vcc, exec, s[24:25]
	s_cbranch_vccz .LBB0_139
	s_barrier

; #define PG8_STAGE(bufoff, gbase, voff) do { _Pragma("unroll") for (int _i = 0; _i < 2; ++_i) \
;         __builtin_amdgcn_global_load_lds((const unsigned*)((const char*)(gbase) + (voff)[_i]), (LAS unsigned*)(lds + (bufoff) + ldsw + _i * 8192), 16, 0, 0); } while (0)
; #define PG8_LDA(dst, b, h) do { _Pragma("unroll") for (int m = 0; m < 4; ++m) _Pragma("unroll") for (int k = 0; k < 2; ++k) dst[m][k] = *(const LAS bf16x8*)(lds + PG8_SA(b, h) + aoff + m * 2048 + k * 1024); } while (0)
; #define PG8_LDB(dst, b, h) do { _Pragma("unroll") for (int n = 0; n < 2; ++n) _Pragma("unroll") for (int k = 0; k < 2; ++k) dst[n][k] = *(const LAS bf16x8*)(lds + PG8_SB(b, h) + boff + n * 2048 + k * 1024); } while (0)
; #define PG8_MMA(ai, bj, At, Bt) do { __builtin_amdgcn_s_setprio(1); _Pragma("unroll") for (int m = 0; m < 4; ++m) _Pragma("unroll") for (int n = 0; n < 2; ++n) _Pragma("unroll") for (int k = 0; k < 2; ++k) \
;         acc[ai][bj][m][n] = __builtin_amdgcn_mfma_f32_16x16x32_bf16(Bt[n][k], At[m][k], acc[ai][bj][m][n], 0, 0, 0); __builtin_amdgcn_s_setprio(0); } while (0)
; #define PG8_WAIT_V(n) asm volatile("s_waitcnt vmcnt(" #n ")" ::: "memory")
; #define PG8_WAIT_L(n) asm volatile("s_waitcnt lgkmcnt(" #n ")" ::: "memory")
; #define PG8_BAR __builtin_amdgcn_s_barrier()
; #define PG8_SCHED __builtin_amdgcn_sched_barrier(0)
; template <class Epi>
; __device__ __forceinline__ void gemm_phase(LAS unsigned char* lds, const Gemm g, const Order& S, const Epi& E) {
;     ...
;         for (int t = 0; t < nt; t += 2) {
;             const bool last = (t == nt - 2);
;             const char* a1 = cA + (size_t)(t + 1) * kstep;
;             const char* a2 = last ? nA : cA + (size_t)(t + 2) * kstep; const char* b2 = last ? nB : cB + (size_t)(t + 2) * kstep;
;             const char* a3 = a2 + kstep; const char* b3 = b2 + kstep;
;             PG8_LDB(B0, 0, 0); PG8_LDB(B1, 0, 1); PG8_SCHED; PG8_LDA(At, 0, 0); PG8_STAGE(PG8_SA(1, 1), a1 + hstepA, voffA);
;             PG8_WAIT_V(8); PG8_WAIT_L(0); PG8_BAR; PG8_MMA(0, 0, At, B0); PG8_MMA(0, 1, At, B1); PG8_BAR; PG8_SCHED;
;             PG8_LDA(At, 0, 1); PG8_STAGE(PG8_SB(0, 0), b2, voffB); PG8_STAGE(PG8_SB(0, 1), b2 + hstepB, voffB); PG8_STAGE(PG8_SA(0, 0), a2, voffA);
.LBB0_251:
	ds_read_b128 v[150:153], v146
	ds_read_b128 v[154:157], v146 offset:1024
	ds_read_b128 v[158:161], v146 offset:2048
	ds_read_b128 v[162:165], v146 offset:3072
	ds_read_b128 v[166:169], v147
	ds_read_b128 v[170:173], v147 offset:1024
	ds_read_b128 v[178:181], v147 offset:2048
	ds_read_b128 v[182:185], v147 offset:3072
	s_add_u32 s36, s34, 0xfff80080
	s_addc_u32 s37, s35, -1
	s_cmp_eq_u32 s61, 28
	s_cselect_b32 s39, s17, s37
	s_cselect_b32 s38, s19, s36
	s_cselect_b32 s37, s57, s60
	s_cselect_b32 s36, s58, s59
	v_lshl_add_u64 v[140:141], s[34:35], 0, v[136:137]
	s_add_i32 m0, s31, 0xc000
	ds_read_b128 v[186:189], v148
	ds_read_b128 v[190:193], v148 offset:1024
	ds_read_b128 v[194:197], v148 offset:2048
	ds_read_b128 v[198:201], v148 offset:3072
	ds_read_b128 v[202:205], v148 offset:4096
	ds_read_b128 v[208:211], v148 offset:5120
	ds_read_b128 v[212:215], v148 offset:6144
	ds_read_b128 v[216:219], v148 offset:7168
	global_load_lds_dwordx4 v[140:141], off
	v_lshl_add_u64 v[140:141], s[34:35], 0, v[138:139]
	s_add_i32 m0, s31, 0xe000
	s_nop 0
	global_load_lds_dwordx4 v[140:141], off
	s_waitcnt vmcnt(8)
	s_waitcnt lgkmcnt(0)
	s_barrier
	s_setprio 1
	s_waitcnt lgkmcnt(0)
	v_mfma_f32_16x16x32_bf16 v[124:127], v[150:153], v[186:189], v[124:127]
	v_mfma_f32_16x16x32_bf16 v[120:123], v[158:161], v[186:189], v[120:123]
	v_mfma_f32_16x16x32_bf16 v[116:119], v[150:153], v[194:197], v[116:119]
	v_mfma_f32_16x16x32_bf16 v[108:111], v[158:161], v[194:197], v[108:111]
	v_mfma_f32_16x16x32_bf16 v[100:103], v[150:153], v[202:205], v[100:103]
	v_mfma_f32_16x16x32_bf16 v[92:95], v[158:161], v[202:205], v[92:95]
	v_mfma_f32_16x16x32_bf16 v[84:87], v[150:153], v[212:215], v[84:87]
	v_mfma_f32_16x16x32_bf16 v[76:79], v[158:161], v[212:215], v[76:79]
	v_mfma_f32_16x16x32_bf16 v[124:127], v[154:157], v[190:193], v[124:127]
	v_mfma_f32_16x16x32_bf16 v[120:123], v[162:165], v[190:193], v[120:123]
	v_mfma_f32_16x16x32_bf16 v[116:119], v[154:157], v[198:201], v[116:119]
	v_mfma_f32_16x16x32_bf16 v[108:111], v[162:165], v[198:201], v[108:111]
	v_mfma_f32_16x16x32_bf16 v[100:103], v[154:157], v[208:211], v[100:103]
	v_mfma_f32_16x16x32_bf16 v[92:95], v[162:165], v[208:211], v[92:95]
	v_mfma_f32_16x16x32_bf16 v[84:87], v[154:157], v[216:219], v[84:87]
	v_mfma_f32_16x16x32_bf16 v[76:79], v[162:165], v[216:219], v[76:79]
	v_mfma_f32_16x16x32_bf16 v[112:115], v[166:169], v[186:189], v[112:115]
	v_mfma_f32_16x16x32_bf16 v[104:107], v[178:181], v[186:189], v[104:107]
	v_mfma_f32_16x16x32_bf16 v[96:99], v[166:169], v[194:197], v[96:99]
	v_mfma_f32_16x16x32_bf16 v[88:91], v[178:181], v[194:197], v[88:91]
	v_mfma_f32_16x16x32_bf16 v[80:83], v[166:169], v[202:205], v[80:83]
	v_mfma_f32_16x16x32_bf16 v[72:75], v[178:181], v[202:205], v[72:75]
	v_mfma_f32_16x16x32_bf16 v[68:71], v[166:169], v[212:215], v[68:71]
	v_mfma_f32_16x16x32_bf16 v[64:67], v[178:181], v[212:215], v[64:67]
	v_mfma_f32_16x16x32_bf16 v[112:115], v[170:173], v[190:193], v[112:115]
	v_mfma_f32_16x16x32_bf16 v[104:107], v[182:185], v[190:193], v[104:107]
	v_mfma_f32_16x16x32_bf16 v[96:99], v[170:173], v[198:201], v[96:99]
	v_mfma_f32_16x16x32_bf16 v[88:91], v[182:185], v[198:201], v[88:91]
	v_mfma_f32_16x16x32_bf16 v[80:83], v[170:173], v[208:211], v[80:83]
	v_mfma_f32_16x16x32_bf16 v[72:75], v[182:185], v[208:211], v[72:75]
	v_mfma_f32_16x16x32_bf16 v[68:71], v[170:173], v[216:219], v[68:71]
	v_mfma_f32_16x16x32_bf16 v[64:67], v[182:185], v[216:219], v[64:67]
	s_setprio 0
	s_barrier
	s_add_i32 s62, s52, s42
	v_lshl_add_u64 v[140:141], s[36:37], 0, v[130:131]
	s_mov_b32 m0, s62
	ds_read_b128 v[186:189], v148 offset:16384
	ds_read_b128 v[190:193], v148 offset:17408
	ds_read_b128 v[194:197], v148 offset:18432
	ds_read_b128 v[198:201], v148 offset:19456
	ds_read_b128 v[202:205], v148 offset:20480
	ds_read_b128 v[208:211], v148 offset:21504
	ds_read_b128 v[212:215], v148 offset:22528
	ds_read_b128 v[216:219], v148 offset:23552
	global_load_lds_dwordx4 v[140:141], off
	s_add_i32 m0, s62, 0x2000
	s_add_u32 s62, s36, 0x80000
	v_lshl_add_u64 v[174:175], s[36:37], 0, v[134:135]
	s_addc_u32 s63, s37, 0
	s_add_i32 s64, s53, s42
	global_load_lds_dwordx4 v[174:175], off
	v_lshl_add_u64 v[220:221], s[62:63], 0, v[130:131]
	s_mov_b32 m0, s64
	v_lshl_add_u64 v[222:223], s[38:39], 0, v[132:133]
	global_load_lds_dwordx4 v[220:221], off
	v_lshl_add_u64 v[220:221], s[62:63], 0, v[134:135]
	s_add_i32 m0, s64, 0x2000
	s_nop 0
	global_load_lds_dwordx4 v[220:221], off
	v_lshl_add_u64 v[220:221], s[38:39], 0, v[128:129]
	s_mov_b32 m0, s31
	s_nop 0
	global_load_lds_dwordx4 v[220:221], off
	s_mov_b32 m0, s43
	s_nop 0
	global_load_lds_dwordx4 v[222:223], off
	s_waitcnt vmcnt(8)
	s_waitcnt lgkmcnt(0)
	s_barrier
; #define PG8_STAGE(bufoff, gbase, voff) do { _Pragma("unroll") for (int _i = 0; _i < 2; ++_i) \
;         __builtin_amdgcn_global_load_lds((const unsigned*)((const char*)(gbase) + (voff)[_i]), (LAS unsigned*)(lds + (bufoff) + ldsw + _i * 8192), 16, 0, 0); } while (0)
; #define PG8_LDA(dst, b, h) do { _Pragma("unroll") for (int m = 0; m < 4; ++m) _Pragma("unroll") for (int k = 0; k < 2; ++k) dst[m][k] = *(const LAS bf16x8*)(lds + PG8_SA(b, h) + aoff + m * 2048 + k * 1024); } while (0)
; #define PG8_LDB(dst, b, h) do { _Pragma("unroll") for (int n = 0; n < 2; ++n) _Pragma("unroll") for (int k = 0; k < 2; ++k) dst[n][k] = *(const LAS bf16x8*)(lds + PG8_SB(b, h) + boff + n * 2048 + k * 1024); } while (0)
; #define PG8_MMA(ai, bj, At, Bt) do { __builtin_amdgcn_s_setprio(1); _Pragma("unroll") for (int m = 0; m < 4; ++m) _Pragma("unroll") for (int n = 0; n < 2; ++n) _Pragma("unroll") for (int k = 0; k < 2; ++k) \
;         acc[ai][bj][m][n] = __builtin_amdgcn_mfma_f32_16x16x32_bf16(Bt[n][k], At[m][k], acc[ai][bj][m][n], 0, 0, 0); __builtin_amdgcn_s_setprio(0); } while (0)
; #define PG8_WAIT_V(n) asm volatile("s_waitcnt vmcnt(" #n ")" ::: "memory")
; #define PG8_WAIT_L(n) asm volatile("s_waitcnt lgkmcnt(" #n ")" ::: "memory")
; #define PG8_BAR __builtin_amdgcn_s_barrier()
; #define PG8_SCHED __builtin_amdgcn_sched_barrier(0)
; template <class Epi>
; __device__ __forceinline__ void gemm_phase(LAS unsigned char* lds, const Gemm g, const Order& S, const Epi& E) {
;     ...
;             PG8_WAIT_V(8); PG8_WAIT_L(0); PG8_BAR; PG8_MMA(1, 0, At, B0); PG8_MMA(1, 1, At, B1); PG8_BAR; PG8_SCHED;
;             PG8_LDB(B0, 1, 0); PG8_LDB(B1, 1, 1); PG8_SCHED; PG8_LDA(At, 1, 0); PG8_STAGE(PG8_SA(0, 1), a2 + hstepA, voffA);
;             PG8_WAIT_V(8); PG8_WAIT_L(0); PG8_BAR; PG8_MMA(0, 0, At, B0); PG8_MMA(0, 1, At, B1); PG8_BAR; PG8_SCHED;
	s_setprio 1
	s_waitcnt lgkmcnt(0)
	v_mfma_f32_16x16x32_bf16 v[60:63], v[150:153], v[186:189], v[60:63]
	v_mfma_f32_16x16x32_bf16 v[56:59], v[158:161], v[186:189], v[56:59]
	v_mfma_f32_16x16x32_bf16 v[52:55], v[150:153], v[194:197], v[52:55]
	v_mfma_f32_16x16x32_bf16 v[44:47], v[158:161], v[194:197], v[44:47]
	v_mfma_f32_16x16x32_bf16 v[36:39], v[150:153], v[202:205], v[36:39]
	v_mfma_f32_16x16x32_bf16 v[28:31], v[158:161], v[202:205], v[28:31]
	v_mfma_f32_16x16x32_bf16 v[20:23], v[150:153], v[212:215], v[20:23]
	v_mfma_f32_16x16x32_bf16 v[12:15], v[158:161], v[212:215], v[12:15]
	v_mfma_f32_16x16x32_bf16 v[60:63], v[154:157], v[190:193], v[60:63]
	v_mfma_f32_16x16x32_bf16 v[56:59], v[162:165], v[190:193], v[56:59]
	v_mfma_f32_16x16x32_bf16 v[52:55], v[154:157], v[198:201], v[52:55]
	v_mfma_f32_16x16x32_bf16 v[44:47], v[162:165], v[198:201], v[44:47]
	v_mfma_f32_16x16x32_bf16 v[36:39], v[154:157], v[208:211], v[36:39]
	v_mfma_f32_16x16x32_bf16 v[28:31], v[162:165], v[208:211], v[28:31]
	v_mfma_f32_16x16x32_bf16 v[20:23], v[154:157], v[216:219], v[20:23]
	v_mfma_f32_16x16x32_bf16 v[12:15], v[162:165], v[216:219], v[12:15]
	v_mfma_f32_16x16x32_bf16 v[48:51], v[166:169], v[186:189], v[48:51]
	v_mfma_f32_16x16x32_bf16 v[40:43], v[178:181], v[186:189], v[40:43]
	v_mfma_f32_16x16x32_bf16 v[32:35], v[166:169], v[194:197], v[32:35]
	v_mfma_f32_16x16x32_bf16 v[24:27], v[178:181], v[194:197], v[24:27]
	v_mfma_f32_16x16x32_bf16 v[16:19], v[166:169], v[202:205], v[16:19]
	v_mfma_f32_16x16x32_bf16 v[8:11], v[178:181], v[202:205], v[8:11]
	v_mfma_f32_16x16x32_bf16 v[4:7], v[166:169], v[212:215], v[4:7]
	v_mfma_f32_16x16x32_bf16 v[0:3], v[178:181], v[212:215], v[0:3]
	v_mfma_f32_16x16x32_bf16 v[48:51], v[170:173], v[190:193], v[48:51]
	v_mfma_f32_16x16x32_bf16 v[40:43], v[182:185], v[190:193], v[40:43]
	v_mfma_f32_16x16x32_bf16 v[32:35], v[170:173], v[198:201], v[32:35]
	v_mfma_f32_16x16x32_bf16 v[24:27], v[182:185], v[198:201], v[24:27]
	v_mfma_f32_16x16x32_bf16 v[16:19], v[170:173], v[208:211], v[16:19]
	v_mfma_f32_16x16x32_bf16 v[8:11], v[182:185], v[208:211], v[8:11]
	v_mfma_f32_16x16x32_bf16 v[4:7], v[170:173], v[216:219], v[4:7]
	v_mfma_f32_16x16x32_bf16 v[0:3], v[182:185], v[216:219], v[0:3]
	s_setprio 0
	s_barrier
	s_add_i32 s62, 0, 0x18000
	v_add_u32_e32 v149, s62, v144
	s_add_i32 s63, 0, 0x1c000
	ds_read_b128 v[150:153], v149
	ds_read_b128 v[154:157], v149 offset:1024
	ds_read_b128 v[158:161], v149 offset:2048
	ds_read_b128 v[162:165], v149 offset:3072
	v_add_u32_e32 v149, s63, v144
	ds_read_b128 v[166:169], v149
	ds_read_b128 v[170:173], v149 offset:1024
	ds_read_b128 v[178:181], v149 offset:2048
	ds_read_b128 v[182:185], v149 offset:3072
	s_add_u32 s38, s38, 0x80000
	s_addc_u32 s39, s39, 0
	s_mov_b32 m0, s46
	v_lshl_add_u64 v[224:225], s[38:39], 0, v[128:129]
	ds_read_b128 v[186:189], v148 offset:32768
	ds_read_b128 v[190:193], v148 offset:33792
	ds_read_b128 v[194:197], v148 offset:34816
	ds_read_b128 v[198:201], v148 offset:35840
	ds_read_b128 v[202:205], v148 offset:36864
	ds_read_b128 v[208:211], v148 offset:37888
	ds_read_b128 v[212:215], v148 offset:38912
	ds_read_b128 v[216:219], v148 offset:39936
	global_load_lds_dwordx4 v[224:225], off
	v_lshl_add_u64 v[224:225], s[38:39], 0, v[132:133]
	s_mov_b32 m0, s47
	s_nop 0
	global_load_lds_dwordx4 v[224:225], off
	s_waitcnt vmcnt(8)
	s_waitcnt lgkmcnt(0)
	s_barrier
	s_setprio 1
	s_waitcnt lgkmcnt(0)
	v_mfma_f32_16x16x32_bf16 v[124:127], v[150:153], v[186:189], v[124:127]
	v_mfma_f32_16x16x32_bf16 v[120:123], v[158:161], v[186:189], v[120:123]
	v_mfma_f32_16x16x32_bf16 v[116:119], v[150:153], v[194:197], v[116:119]
	v_mfma_f32_16x16x32_bf16 v[108:111], v[158:161], v[194:197], v[108:111]
	v_mfma_f32_16x16x32_bf16 v[100:103], v[150:153], v[202:205], v[100:103]
	v_mfma_f32_16x16x32_bf16 v[92:95], v[158:161], v[202:205], v[92:95]
	v_mfma_f32_16x16x32_bf16 v[84:87], v[150:153], v[212:215], v[84:87]
	v_mfma_f32_16x16x32_bf16 v[76:79], v[158:161], v[212:215], v[76:79]
	v_mfma_f32_16x16x32_bf16 v[124:127], v[154:157], v[190:193], v[124:127]
	v_mfma_f32_16x16x32_bf16 v[120:123], v[162:165], v[190:193], v[120:123]
	v_mfma_f32_16x16x32_bf16 v[116:119], v[154:157], v[198:201], v[116:119]
	v_mfma_f32_16x16x32_bf16 v[108:111], v[162:165], v[198:201], v[108:111]
	v_mfma_f32_16x16x32_bf16 v[100:103], v[154:157], v[208:211], v[100:103]
	v_mfma_f32_16x16x32_bf16 v[92:95], v[162:165], v[208:211], v[92:95]
	v_mfma_f32_16x16x32_bf16 v[84:87], v[154:157], v[216:219], v[84:87]
	v_mfma_f32_16x16x32_bf16 v[76:79], v[162:165], v[216:219], v[76:79]
	v_mfma_f32_16x16x32_bf16 v[112:115], v[166:169], v[186:189], v[112:115]
	v_mfma_f32_16x16x32_bf16 v[104:107], v[178:181], v[186:189], v[104:107]
	v_mfma_f32_16x16x32_bf16 v[96:99], v[166:169], v[194:197], v[96:99]
	v_mfma_f32_16x16x32_bf16 v[88:91], v[178:181], v[194:197], v[88:91]
	v_mfma_f32_16x16x32_bf16 v[80:83], v[166:169], v[202:205], v[80:83]
	v_mfma_f32_16x16x32_bf16 v[72:75], v[178:181], v[202:205], v[72:75]
	v_mfma_f32_16x16x32_bf16 v[68:71], v[166:169], v[212:215], v[68:71]
	v_mfma_f32_16x16x32_bf16 v[64:67], v[178:181], v[212:215], v[64:67]
	v_mfma_f32_16x16x32_bf16 v[112:115], v[170:173], v[190:193], v[112:115]
	v_mfma_f32_16x16x32_bf16 v[104:107], v[182:185], v[190:193], v[104:107]
	v_mfma_f32_16x16x32_bf16 v[96:99], v[170:173], v[198:201], v[96:99]
	v_mfma_f32_16x16x32_bf16 v[88:91], v[182:185], v[198:201], v[88:91]
	v_mfma_f32_16x16x32_bf16 v[80:83], v[170:173], v[208:211], v[80:83]
	v_mfma_f32_16x16x32_bf16 v[72:75], v[182:185], v[208:211], v[72:75]
	v_mfma_f32_16x16x32_bf16 v[68:71], v[170:173], v[216:219], v[68:71]
	v_mfma_f32_16x16x32_bf16 v[64:67], v[182:185], v[216:219], v[64:67]
	s_setprio 0
	s_barrier
; #define PG8_STAGE(bufoff, gbase, voff) do { _Pragma("unroll") for (int _i = 0; _i < 2; ++_i) \
;         __builtin_amdgcn_global_load_lds((const unsigned*)((const char*)(gbase) + (voff)[_i]), (LAS unsigned*)(lds + (bufoff) + ldsw + _i * 8192), 16, 0, 0); } while (0)
; #define PG8_LDA(dst, b, h) do { _Pragma("unroll") for (int m = 0; m < 4; ++m) _Pragma("unroll") for (int k = 0; k < 2; ++k) dst[m][k] = *(const LAS bf16x8*)(lds + PG8_SA(b, h) + aoff + m * 2048 + k * 1024); } while (0)
; #define PG8_MMA(ai, bj, At, Bt) do { __builtin_amdgcn_s_setprio(1); _Pragma("unroll") for (int m = 0; m < 4; ++m) _Pragma("unroll") for (int n = 0; n < 2; ++n) _Pragma("unroll") for (int k = 0; k < 2; ++k) \
;         acc[ai][bj][m][n] = __builtin_amdgcn_mfma_f32_16x16x32_bf16(Bt[n][k], At[m][k], acc[ai][bj][m][n], 0, 0, 0); __builtin_amdgcn_s_setprio(0); } while (0)
; #define PG8_WAIT_V(n) asm volatile("s_waitcnt vmcnt(" #n ")" ::: "memory")
; #define PG8_WAIT_L(n) asm volatile("s_waitcnt lgkmcnt(" #n ")" ::: "memory")
; #define PG8_BAR __builtin_amdgcn_s_barrier()
; #define PG8_SCHED __builtin_amdgcn_sched_barrier(0)
; template <class Epi>
; __device__ __forceinline__ void gemm_phase(LAS unsigned char* lds, const Gemm g, const Order& S, const Epi& E) {
;     ...
;             PG8_LDA(At, 1, 1); PG8_STAGE(PG8_SB(1, 0), b3, voffB); PG8_STAGE(PG8_SB(1, 1), b3 + hstepB, voffB); PG8_STAGE(PG8_SA(1, 0), a3, voffA);
;             PG8_WAIT_V(8); PG8_WAIT_L(0); PG8_BAR; PG8_MMA(1, 0, At, B0); PG8_MMA(1, 1, At, B1); PG8_BAR; PG8_SCHED;
;         }
;         if (wr == 0) PG8_BAR;
	s_add_i32 s38, s62, s42
	v_lshl_add_u64 v[140:141], v[140:141], 0, s[8:9]
	s_mov_b32 m0, s38
	ds_read_b128 v[186:189], v148 offset:49152
	ds_read_b128 v[190:193], v148 offset:50176
	ds_read_b128 v[194:197], v148 offset:51200
	ds_read_b128 v[198:201], v148 offset:52224
	ds_read_b128 v[202:205], v148 offset:53248
	ds_read_b128 v[208:211], v148 offset:54272
	ds_read_b128 v[212:215], v148 offset:55296
	ds_read_b128 v[216:219], v148 offset:56320
	global_load_lds_dwordx4 v[140:141], off
	s_add_i32 m0, s38, 0x2000
	s_add_u32 s36, s36, 0x80080
	v_lshl_add_u64 v[140:141], v[174:175], 0, s[8:9]
	s_addc_u32 s37, s37, 0
	s_add_i32 s38, s63, s42
	global_load_lds_dwordx4 v[140:141], off
	v_lshl_add_u64 v[140:141], s[36:37], 0, v[130:131]
	s_mov_b32 m0, s38
	s_nop 0
	global_load_lds_dwordx4 v[140:141], off
	v_lshl_add_u64 v[140:141], s[36:37], 0, v[134:135]
	s_add_i32 m0, s38, 0x2000
	s_nop 0
	global_load_lds_dwordx4 v[140:141], off
	v_lshl_add_u64 v[140:141], v[220:221], 0, s[8:9]
	s_mov_b32 m0, s49
	s_nop 0
	global_load_lds_dwordx4 v[140:141], off
	v_lshl_add_u64 v[140:141], v[222:223], 0, s[8:9]
	s_mov_b32 m0, s50
	s_nop 0
	global_load_lds_dwordx4 v[140:141], off
	s_waitcnt vmcnt(8)
	s_waitcnt lgkmcnt(0)
	s_barrier
	s_setprio 1
	s_waitcnt lgkmcnt(0)
	v_mfma_f32_16x16x32_bf16 v[60:63], v[150:153], v[186:189], v[60:63]
	v_mfma_f32_16x16x32_bf16 v[56:59], v[158:161], v[186:189], v[56:59]
	v_mfma_f32_16x16x32_bf16 v[52:55], v[150:153], v[194:197], v[52:55]
	v_mfma_f32_16x16x32_bf16 v[44:47], v[158:161], v[194:197], v[44:47]
	v_mfma_f32_16x16x32_bf16 v[36:39], v[150:153], v[202:205], v[36:39]
	v_mfma_f32_16x16x32_bf16 v[28:31], v[158:161], v[202:205], v[28:31]
	v_mfma_f32_16x16x32_bf16 v[20:23], v[150:153], v[212:215], v[20:23]
	v_mfma_f32_16x16x32_bf16 v[12:15], v[158:161], v[212:215], v[12:15]
	v_mfma_f32_16x16x32_bf16 v[60:63], v[154:157], v[190:193], v[60:63]
	v_mfma_f32_16x16x32_bf16 v[56:59], v[162:165], v[190:193], v[56:59]
	v_mfma_f32_16x16x32_bf16 v[52:55], v[154:157], v[198:201], v[52:55]
	v_mfma_f32_16x16x32_bf16 v[44:47], v[162:165], v[198:201], v[44:47]
	v_mfma_f32_16x16x32_bf16 v[36:39], v[154:157], v[208:211], v[36:39]
	v_mfma_f32_16x16x32_bf16 v[28:31], v[162:165], v[208:211], v[28:31]
	v_mfma_f32_16x16x32_bf16 v[20:23], v[154:157], v[216:219], v[20:23]
	v_mfma_f32_16x16x32_bf16 v[12:15], v[162:165], v[216:219], v[12:15]
	v_mfma_f32_16x16x32_bf16 v[48:51], v[166:169], v[186:189], v[48:51]
	v_mfma_f32_16x16x32_bf16 v[40:43], v[178:181], v[186:189], v[40:43]
	v_mfma_f32_16x16x32_bf16 v[32:35], v[166:169], v[194:197], v[32:35]
	v_mfma_f32_16x16x32_bf16 v[24:27], v[178:181], v[194:197], v[24:27]
	v_mfma_f32_16x16x32_bf16 v[16:19], v[166:169], v[202:205], v[16:19]
	v_mfma_f32_16x16x32_bf16 v[8:11], v[178:181], v[202:205], v[8:11]
	v_mfma_f32_16x16x32_bf16 v[4:7], v[166:169], v[212:215], v[4:7]
	v_mfma_f32_16x16x32_bf16 v[0:3], v[178:181], v[212:215], v[0:3]
	v_mfma_f32_16x16x32_bf16 v[48:51], v[170:173], v[190:193], v[48:51]
	v_mfma_f32_16x16x32_bf16 v[40:43], v[182:185], v[190:193], v[40:43]
	v_mfma_f32_16x16x32_bf16 v[32:35], v[170:173], v[198:201], v[32:35]
	v_mfma_f32_16x16x32_bf16 v[24:27], v[182:185], v[198:201], v[24:27]
	v_mfma_f32_16x16x32_bf16 v[16:19], v[170:173], v[208:211], v[16:19]
	v_mfma_f32_16x16x32_bf16 v[8:11], v[182:185], v[208:211], v[8:11]
	v_mfma_f32_16x16x32_bf16 v[4:7], v[170:173], v[216:219], v[4:7]
	v_mfma_f32_16x16x32_bf16 v[0:3], v[182:185], v[216:219], v[0:3]
	s_setprio 0
	s_barrier
	s_add_i32 s61, s61, 2
	s_add_u32 s34, s34, 0x100
	s_addc_u32 s35, s35, 0
	s_add_u32 s59, s59, 0x100
	s_addc_u32 s60, s60, 0
	s_cmp_gt_u32 s61, 29
	s_cbranch_scc0 .LBB0_251
	s_and_b64 vcc, exec, s[10:11]
	s_cbranch_vccz .LBB0_254
	s_barrier

; #define PG8_STAGE(bufoff, gbase, voff) do { _Pragma("unroll") for (int _i = 0; _i < 2; ++_i) \
;         __builtin_amdgcn_global_load_lds((const unsigned*)((const char*)(gbase) + (voff)[_i]), (LAS unsigned*)(lds + (bufoff) + ldsw + _i * 8192), 16, 0, 0); } while (0)
; #define PG8_LDA(dst, b, h) do { _Pragma("unroll") for (int m = 0; m < 4; ++m) _Pragma("unroll") for (int k = 0; k < 2; ++k) dst[m][k] = *(const LAS bf16x8*)(lds + PG8_SA(b, h) + aoff + m * 2048 + k * 1024); } while (0)
; #define PG8_LDB(dst, b, h) do { _Pragma("unroll") for (int n = 0; n < 2; ++n) _Pragma("unroll") for (int k = 0; k < 2; ++k) dst[n][k] = *(const LAS bf16x8*)(lds + PG8_SB(b, h) + boff + n * 2048 + k * 1024); } while (0)
; #define PG8_MMA(ai, bj, At, Bt) do { __builtin_amdgcn_s_setprio(1); _Pragma("unroll") for (int m = 0; m < 4; ++m) _Pragma("unroll") for (int n = 0; n < 2; ++n) _Pragma("unroll") for (int k = 0; k < 2; ++k) \
;         acc[ai][bj][m][n] = __builtin_amdgcn_mfma_f32_16x16x32_bf16(Bt[n][k], At[m][k], acc[ai][bj][m][n], 0, 0, 0); __builtin_amdgcn_s_setprio(0); } while (0)
; #define PG8_WAIT_V(n) asm volatile("s_waitcnt vmcnt(" #n ")" ::: "memory")
; #define PG8_WAIT_L(n) asm volatile("s_waitcnt lgkmcnt(" #n ")" ::: "memory")
; #define PG8_BAR __builtin_amdgcn_s_barrier()
; #define PG8_SCHED __builtin_amdgcn_sched_barrier(0)
; template <class Epi>
; __device__ __forceinline__ void gemm_phase(LAS unsigned char* lds, const Gemm g, const Order& S, const Epi& E) {
;     ...
;         for (int t = 0; t < nt; t += 2) {
;             const bool last = (t == nt - 2);
;             const char* a1 = cA + (size_t)(t + 1) * kstep;
;             const char* a2 = last ? nA : cA + (size_t)(t + 2) * kstep; const char* b2 = last ? nB : cB + (size_t)(t + 2) * kstep;
;             const char* a3 = a2 + kstep; const char* b3 = b2 + kstep;
;             PG8_LDB(B0, 0, 0); PG8_LDB(B1, 0, 1); PG8_SCHED; PG8_LDA(At, 0, 0); PG8_STAGE(PG8_SA(1, 1), a1 + hstepA, voffA);
;             PG8_WAIT_V(8); PG8_WAIT_L(0); PG8_BAR; PG8_MMA(0, 0, At, B0); PG8_MMA(0, 1, At, B1); PG8_BAR; PG8_SCHED;
;             PG8_LDA(At, 0, 1); PG8_STAGE(PG8_SB(0, 0), b2, voffB); PG8_STAGE(PG8_SB(0, 1), b2 + hstepB, voffB); PG8_STAGE(PG8_SA(0, 0), a2, voffA);
.LBB0_358:
	ds_read_b128 v[166:169], v163
	ds_read_b128 v[170:173], v163 offset:1024
	ds_read_b128 v[178:181], v163 offset:2048
	ds_read_b128 v[182:185], v163 offset:3072
	ds_read_b128 v[186:189], v164
	ds_read_b128 v[190:193], v164 offset:1024
	ds_read_b128 v[194:197], v164 offset:2048
	ds_read_b128 v[198:201], v164 offset:3072
	s_add_u32 s30, s28, 0xfff00080
	s_addc_u32 s31, s29, -1
	s_cmp_eq_u32 s62, 4
	s_cselect_b32 s35, s19, s31
	s_cselect_b32 s34, s57, s30
	s_cselect_b32 s31, s58, s61
	s_cselect_b32 s30, s59, s60
	v_lshl_add_u64 v[144:145], s[28:29], 0, v[136:137]
	s_add_i32 m0, s40, 0xc000
	ds_read_b128 v[202:205], v165
	ds_read_b128 v[208:211], v165 offset:1024
	ds_read_b128 v[212:215], v165 offset:2048
	ds_read_b128 v[216:219], v165 offset:3072
	ds_read_b128 v[220:223], v165 offset:4096
	ds_read_b128 v[224:227], v165 offset:5120
	ds_read_b128 v[228:231], v165 offset:6144
	ds_read_b128 v[232:235], v165 offset:7168
	global_load_lds_dwordx4 v[144:145], off
	v_lshl_add_u64 v[144:145], s[28:29], 0, v[138:139]
	s_add_i32 m0, s40, 0xe000
	s_nop 0
	global_load_lds_dwordx4 v[144:145], off
	s_waitcnt vmcnt(8)
	s_waitcnt lgkmcnt(0)
	s_barrier
	s_setprio 1
	s_waitcnt lgkmcnt(0)
	v_mfma_f32_16x16x32_bf16 v[124:127], v[166:169], v[202:205], v[124:127]
	v_mfma_f32_16x16x32_bf16 v[120:123], v[178:181], v[202:205], v[120:123]
	v_mfma_f32_16x16x32_bf16 v[116:119], v[166:169], v[212:215], v[116:119]
	v_mfma_f32_16x16x32_bf16 v[108:111], v[178:181], v[212:215], v[108:111]
	v_mfma_f32_16x16x32_bf16 v[100:103], v[166:169], v[220:223], v[100:103]
	v_mfma_f32_16x16x32_bf16 v[92:95], v[178:181], v[220:223], v[92:95]
	v_mfma_f32_16x16x32_bf16 v[84:87], v[166:169], v[228:231], v[84:87]
	v_mfma_f32_16x16x32_bf16 v[76:79], v[178:181], v[228:231], v[76:79]
	v_mfma_f32_16x16x32_bf16 v[124:127], v[170:173], v[208:211], v[124:127]
	v_mfma_f32_16x16x32_bf16 v[120:123], v[182:185], v[208:211], v[120:123]
	v_mfma_f32_16x16x32_bf16 v[116:119], v[170:173], v[216:219], v[116:119]
	v_mfma_f32_16x16x32_bf16 v[108:111], v[182:185], v[216:219], v[108:111]
	v_mfma_f32_16x16x32_bf16 v[100:103], v[170:173], v[224:227], v[100:103]
	v_mfma_f32_16x16x32_bf16 v[92:95], v[182:185], v[224:227], v[92:95]
	v_mfma_f32_16x16x32_bf16 v[84:87], v[170:173], v[232:235], v[84:87]
	v_mfma_f32_16x16x32_bf16 v[76:79], v[182:185], v[232:235], v[76:79]
	v_mfma_f32_16x16x32_bf16 v[112:115], v[186:189], v[202:205], v[112:115]
	v_mfma_f32_16x16x32_bf16 v[104:107], v[194:197], v[202:205], v[104:107]
	v_mfma_f32_16x16x32_bf16 v[96:99], v[186:189], v[212:215], v[96:99]
	v_mfma_f32_16x16x32_bf16 v[88:91], v[194:197], v[212:215], v[88:91]
	v_mfma_f32_16x16x32_bf16 v[80:83], v[186:189], v[220:223], v[80:83]
	v_mfma_f32_16x16x32_bf16 v[72:75], v[194:197], v[220:223], v[72:75]
	v_mfma_f32_16x16x32_bf16 v[68:71], v[186:189], v[228:231], v[68:71]
	v_mfma_f32_16x16x32_bf16 v[64:67], v[194:197], v[228:231], v[64:67]
	v_mfma_f32_16x16x32_bf16 v[112:115], v[190:193], v[208:211], v[112:115]
	v_mfma_f32_16x16x32_bf16 v[104:107], v[198:201], v[208:211], v[104:107]
	v_mfma_f32_16x16x32_bf16 v[96:99], v[190:193], v[216:219], v[96:99]
	v_mfma_f32_16x16x32_bf16 v[88:91], v[198:201], v[216:219], v[88:91]
	v_mfma_f32_16x16x32_bf16 v[80:83], v[190:193], v[224:227], v[80:83]
	v_mfma_f32_16x16x32_bf16 v[72:75], v[198:201], v[224:227], v[72:75]
	v_mfma_f32_16x16x32_bf16 v[68:71], v[190:193], v[232:235], v[68:71]
	v_mfma_f32_16x16x32_bf16 v[64:67], v[198:201], v[232:235], v[64:67]
	s_setprio 0
	s_barrier
	s_add_i32 s63, s50, s37
	v_lshl_add_u64 v[144:145], s[30:31], 0, v[130:131]
	s_mov_b32 m0, s63
	ds_read_b128 v[202:205], v165 offset:16384
	ds_read_b128 v[208:211], v165 offset:17408
	ds_read_b128 v[212:215], v165 offset:18432
	ds_read_b128 v[216:219], v165 offset:19456
	ds_read_b128 v[220:223], v165 offset:20480
	ds_read_b128 v[224:227], v165 offset:21504
	ds_read_b128 v[228:231], v165 offset:22528
	ds_read_b128 v[232:235], v165 offset:23552
	global_load_lds_dwordx4 v[144:145], off
	s_add_i32 m0, s63, 0x2000
	s_add_u32 s64, s30, 0x80000
	v_lshl_add_u64 v[174:175], s[30:31], 0, v[134:135]
	s_addc_u32 s65, s31, 0
	s_add_i32 s63, s51, s37
	global_load_lds_dwordx4 v[174:175], off
	v_lshl_add_u64 v[236:237], s[64:65], 0, v[130:131]
	s_mov_b32 m0, s63
	v_lshl_add_u64 v[238:239], s[34:35], 0, v[132:133]
	global_load_lds_dwordx4 v[236:237], off
	v_lshl_add_u64 v[236:237], s[64:65], 0, v[134:135]
	s_add_i32 m0, s63, 0x2000
	s_nop 0
	global_load_lds_dwordx4 v[236:237], off
	v_lshl_add_u64 v[236:237], s[34:35], 0, v[128:129]
	s_mov_b32 m0, s40
	s_nop 0
	global_load_lds_dwordx4 v[236:237], off
	s_mov_b32 m0, s41
	s_nop 0
	global_load_lds_dwordx4 v[238:239], off
	s_waitcnt vmcnt(8)
	s_waitcnt lgkmcnt(0)
	s_barrier
; #define PG8_STAGE(bufoff, gbase, voff) do { _Pragma("unroll") for (int _i = 0; _i < 2; ++_i) \
;         __builtin_amdgcn_global_load_lds((const unsigned*)((const char*)(gbase) + (voff)[_i]), (LAS unsigned*)(lds + (bufoff) + ldsw + _i * 8192), 16, 0, 0); } while (0)
; #define PG8_LDA(dst, b, h) do { _Pragma("unroll") for (int m = 0; m < 4; ++m) _Pragma("unroll") for (int k = 0; k < 2; ++k) dst[m][k] = *(const LAS bf16x8*)(lds + PG8_SA(b, h) + aoff + m * 2048 + k * 1024); } while (0)
; #define PG8_LDB(dst, b, h) do { _Pragma("unroll") for (int n = 0; n < 2; ++n) _Pragma("unroll") for (int k = 0; k < 2; ++k) dst[n][k] = *(const LAS bf16x8*)(lds + PG8_SB(b, h) + boff + n * 2048 + k * 1024); } while (0)
; #define PG8_MMA(ai, bj, At, Bt) do { __builtin_amdgcn_s_setprio(1); _Pragma("unroll") for (int m = 0; m < 4; ++m) _Pragma("unroll") for (int n = 0; n < 2; ++n) _Pragma("unroll") for (int k = 0; k < 2; ++k) \
;         acc[ai][bj][m][n] = __builtin_amdgcn_mfma_f32_16x16x32_bf16(Bt[n][k], At[m][k], acc[ai][bj][m][n], 0, 0, 0); __builtin_amdgcn_s_setprio(0); } while (0)
; #define PG8_WAIT_V(n) asm volatile("s_waitcnt vmcnt(" #n ")" ::: "memory")
; #define PG8_WAIT_L(n) asm volatile("s_waitcnt lgkmcnt(" #n ")" ::: "memory")
; #define PG8_BAR __builtin_amdgcn_s_barrier()
; #define PG8_SCHED __builtin_amdgcn_sched_barrier(0)
; template <class Epi>
; __device__ __forceinline__ void gemm_phase(LAS unsigned char* lds, const Gemm g, const Order& S, const Epi& E) {
;     ...
;             PG8_WAIT_V(8); PG8_WAIT_L(0); PG8_BAR; PG8_MMA(1, 0, At, B0); PG8_MMA(1, 1, At, B1); PG8_BAR; PG8_SCHED;
;             PG8_LDB(B0, 1, 0); PG8_LDB(B1, 1, 1); PG8_SCHED; PG8_LDA(At, 1, 0); PG8_STAGE(PG8_SA(0, 1), a2 + hstepA, voffA);
;             PG8_WAIT_V(8); PG8_WAIT_L(0); PG8_BAR; PG8_MMA(0, 0, At, B0); PG8_MMA(0, 1, At, B1); PG8_BAR; PG8_SCHED;
	s_setprio 1
	s_waitcnt lgkmcnt(0)
	v_mfma_f32_16x16x32_bf16 v[60:63], v[166:169], v[202:205], v[60:63]
	v_mfma_f32_16x16x32_bf16 v[56:59], v[178:181], v[202:205], v[56:59]
	v_mfma_f32_16x16x32_bf16 v[52:55], v[166:169], v[212:215], v[52:55]
	v_mfma_f32_16x16x32_bf16 v[44:47], v[178:181], v[212:215], v[44:47]
	v_mfma_f32_16x16x32_bf16 v[36:39], v[166:169], v[220:223], v[36:39]
	v_mfma_f32_16x16x32_bf16 v[28:31], v[178:181], v[220:223], v[28:31]
	v_mfma_f32_16x16x32_bf16 v[20:23], v[166:169], v[228:231], v[20:23]
	v_mfma_f32_16x16x32_bf16 v[12:15], v[178:181], v[228:231], v[12:15]
	v_mfma_f32_16x16x32_bf16 v[60:63], v[170:173], v[208:211], v[60:63]
	v_mfma_f32_16x16x32_bf16 v[56:59], v[182:185], v[208:211], v[56:59]
	v_mfma_f32_16x16x32_bf16 v[52:55], v[170:173], v[216:219], v[52:55]
	v_mfma_f32_16x16x32_bf16 v[44:47], v[182:185], v[216:219], v[44:47]
	v_mfma_f32_16x16x32_bf16 v[36:39], v[170:173], v[224:227], v[36:39]
	v_mfma_f32_16x16x32_bf16 v[28:31], v[182:185], v[224:227], v[28:31]
	v_mfma_f32_16x16x32_bf16 v[20:23], v[170:173], v[232:235], v[20:23]
	v_mfma_f32_16x16x32_bf16 v[12:15], v[182:185], v[232:235], v[12:15]
	v_mfma_f32_16x16x32_bf16 v[48:51], v[186:189], v[202:205], v[48:51]
	v_mfma_f32_16x16x32_bf16 v[40:43], v[194:197], v[202:205], v[40:43]
	v_mfma_f32_16x16x32_bf16 v[32:35], v[186:189], v[212:215], v[32:35]
	v_mfma_f32_16x16x32_bf16 v[24:27], v[194:197], v[212:215], v[24:27]
	v_mfma_f32_16x16x32_bf16 v[16:19], v[186:189], v[220:223], v[16:19]
	v_mfma_f32_16x16x32_bf16 v[8:11], v[194:197], v[220:223], v[8:11]
	v_mfma_f32_16x16x32_bf16 v[4:7], v[186:189], v[228:231], v[4:7]
	v_mfma_f32_16x16x32_bf16 v[0:3], v[194:197], v[228:231], v[0:3]
	v_mfma_f32_16x16x32_bf16 v[48:51], v[190:193], v[208:211], v[48:51]
	v_mfma_f32_16x16x32_bf16 v[40:43], v[198:201], v[208:211], v[40:43]
	v_mfma_f32_16x16x32_bf16 v[32:35], v[190:193], v[216:219], v[32:35]
	v_mfma_f32_16x16x32_bf16 v[24:27], v[198:201], v[216:219], v[24:27]
	v_mfma_f32_16x16x32_bf16 v[16:19], v[190:193], v[224:227], v[16:19]
	v_mfma_f32_16x16x32_bf16 v[8:11], v[198:201], v[224:227], v[8:11]
	v_mfma_f32_16x16x32_bf16 v[4:7], v[190:193], v[232:235], v[4:7]
	v_mfma_f32_16x16x32_bf16 v[0:3], v[198:201], v[232:235], v[0:3]
	s_setprio 0
	s_barrier
	s_add_i32 s63, 0, 0x18000
	v_add_u32_e32 v177, s63, v161
	s_add_i32 s64, 0, 0x1c000
	ds_read_b128 v[166:169], v177
	ds_read_b128 v[170:173], v177 offset:1024
	ds_read_b128 v[178:181], v177 offset:2048
	ds_read_b128 v[182:185], v177 offset:3072
	v_add_u32_e32 v177, s64, v161
	ds_read_b128 v[186:189], v177
	ds_read_b128 v[190:193], v177 offset:1024
	ds_read_b128 v[194:197], v177 offset:2048
	ds_read_b128 v[198:201], v177 offset:3072
	s_add_u32 s34, s34, 0x100000
	s_addc_u32 s35, s35, 0
	s_mov_b32 m0, s42
	v_lshl_add_u64 v[240:241], s[34:35], 0, v[128:129]
	ds_read_b128 v[202:205], v165 offset:32768
	ds_read_b128 v[208:211], v165 offset:33792
	ds_read_b128 v[212:215], v165 offset:34816
	ds_read_b128 v[216:219], v165 offset:35840
	ds_read_b128 v[220:223], v165 offset:36864
	ds_read_b128 v[224:227], v165 offset:37888
	ds_read_b128 v[228:231], v165 offset:38912
	ds_read_b128 v[232:235], v165 offset:39936
	global_load_lds_dwordx4 v[240:241], off
	v_lshl_add_u64 v[240:241], s[34:35], 0, v[132:133]
	s_mov_b32 m0, s43
	s_nop 0
	global_load_lds_dwordx4 v[240:241], off
	s_waitcnt vmcnt(8)
	s_waitcnt lgkmcnt(0)
	s_barrier
	s_setprio 1
	s_waitcnt lgkmcnt(0)
	v_mfma_f32_16x16x32_bf16 v[124:127], v[166:169], v[202:205], v[124:127]
	v_mfma_f32_16x16x32_bf16 v[120:123], v[178:181], v[202:205], v[120:123]
	v_mfma_f32_16x16x32_bf16 v[116:119], v[166:169], v[212:215], v[116:119]
	v_mfma_f32_16x16x32_bf16 v[108:111], v[178:181], v[212:215], v[108:111]
	v_mfma_f32_16x16x32_bf16 v[100:103], v[166:169], v[220:223], v[100:103]
	v_mfma_f32_16x16x32_bf16 v[92:95], v[178:181], v[220:223], v[92:95]
	v_mfma_f32_16x16x32_bf16 v[84:87], v[166:169], v[228:231], v[84:87]
	v_mfma_f32_16x16x32_bf16 v[76:79], v[178:181], v[228:231], v[76:79]
	v_mfma_f32_16x16x32_bf16 v[124:127], v[170:173], v[208:211], v[124:127]
	v_mfma_f32_16x16x32_bf16 v[120:123], v[182:185], v[208:211], v[120:123]
	v_mfma_f32_16x16x32_bf16 v[116:119], v[170:173], v[216:219], v[116:119]
	v_mfma_f32_16x16x32_bf16 v[108:111], v[182:185], v[216:219], v[108:111]
	v_mfma_f32_16x16x32_bf16 v[100:103], v[170:173], v[224:227], v[100:103]
	v_mfma_f32_16x16x32_bf16 v[92:95], v[182:185], v[224:227], v[92:95]
	v_mfma_f32_16x16x32_bf16 v[84:87], v[170:173], v[232:235], v[84:87]
	v_mfma_f32_16x16x32_bf16 v[76:79], v[182:185], v[232:235], v[76:79]
	v_mfma_f32_16x16x32_bf16 v[112:115], v[186:189], v[202:205], v[112:115]
	v_mfma_f32_16x16x32_bf16 v[104:107], v[194:197], v[202:205], v[104:107]
	v_mfma_f32_16x16x32_bf16 v[96:99], v[186:189], v[212:215], v[96:99]
	v_mfma_f32_16x16x32_bf16 v[88:91], v[194:197], v[212:215], v[88:91]
	v_mfma_f32_16x16x32_bf16 v[80:83], v[186:189], v[220:223], v[80:83]
	v_mfma_f32_16x16x32_bf16 v[72:75], v[194:197], v[220:223], v[72:75]
	v_mfma_f32_16x16x32_bf16 v[68:71], v[186:189], v[228:231], v[68:71]
	v_mfma_f32_16x16x32_bf16 v[64:67], v[194:197], v[228:231], v[64:67]
	v_mfma_f32_16x16x32_bf16 v[112:115], v[190:193], v[208:211], v[112:115]
	v_mfma_f32_16x16x32_bf16 v[104:107], v[198:201], v[208:211], v[104:107]
	v_mfma_f32_16x16x32_bf16 v[96:99], v[190:193], v[216:219], v[96:99]
	v_mfma_f32_16x16x32_bf16 v[88:91], v[198:201], v[216:219], v[88:91]
	v_mfma_f32_16x16x32_bf16 v[80:83], v[190:193], v[224:227], v[80:83]
	v_mfma_f32_16x16x32_bf16 v[72:75], v[198:201], v[224:227], v[72:75]
	v_mfma_f32_16x16x32_bf16 v[68:71], v[190:193], v[232:235], v[68:71]
	v_mfma_f32_16x16x32_bf16 v[64:67], v[198:201], v[232:235], v[64:67]
	s_setprio 0
	s_barrier
; #define PG8_STAGE(bufoff, gbase, voff) do { _Pragma("unroll") for (int _i = 0; _i < 2; ++_i) \
;         __builtin_amdgcn_global_load_lds((const unsigned*)((const char*)(gbase) + (voff)[_i]), (LAS unsigned*)(lds + (bufoff) + ldsw + _i * 8192), 16, 0, 0); } while (0)
; #define PG8_LDA(dst, b, h) do { _Pragma("unroll") for (int m = 0; m < 4; ++m) _Pragma("unroll") for (int k = 0; k < 2; ++k) dst[m][k] = *(const LAS bf16x8*)(lds + PG8_SA(b, h) + aoff + m * 2048 + k * 1024); } while (0)
; #define PG8_MMA(ai, bj, At, Bt) do { __builtin_amdgcn_s_setprio(1); _Pragma("unroll") for (int m = 0; m < 4; ++m) _Pragma("unroll") for (int n = 0; n < 2; ++n) _Pragma("unroll") for (int k = 0; k < 2; ++k) \
;         acc[ai][bj][m][n] = __builtin_amdgcn_mfma_f32_16x16x32_bf16(Bt[n][k], At[m][k], acc[ai][bj][m][n], 0, 0, 0); __builtin_amdgcn_s_setprio(0); } while (0)
; #define PG8_WAIT_V(n) asm volatile("s_waitcnt vmcnt(" #n ")" ::: "memory")
; #define PG8_WAIT_L(n) asm volatile("s_waitcnt lgkmcnt(" #n ")" ::: "memory")
; #define PG8_BAR __builtin_amdgcn_s_barrier()
; #define PG8_SCHED __builtin_amdgcn_sched_barrier(0)
; template <class Epi>
; __device__ __forceinline__ void gemm_phase(LAS unsigned char* lds, const Gemm g, const Order& S, const Epi& E) {
;     ...
;             PG8_LDA(At, 1, 1); PG8_STAGE(PG8_SB(1, 0), b3, voffB); PG8_STAGE(PG8_SB(1, 1), b3 + hstepB, voffB); PG8_STAGE(PG8_SA(1, 0), a3, voffA);
;             PG8_WAIT_V(8); PG8_WAIT_L(0); PG8_BAR; PG8_MMA(1, 0, At, B0); PG8_MMA(1, 1, At, B1); PG8_BAR; PG8_SCHED;
;         }
;         if (wr == 0) PG8_BAR;
	s_add_i32 s34, s63, s37
	v_lshl_add_u64 v[144:145], v[144:145], 0, s[12:13]
	s_mov_b32 m0, s34
	ds_read_b128 v[202:205], v165 offset:49152
	ds_read_b128 v[208:211], v165 offset:50176
	ds_read_b128 v[212:215], v165 offset:51200
	ds_read_b128 v[216:219], v165 offset:52224
	ds_read_b128 v[220:223], v165 offset:53248
	ds_read_b128 v[224:227], v165 offset:54272
	ds_read_b128 v[228:231], v165 offset:55296
	ds_read_b128 v[232:235], v165 offset:56320
	global_load_lds_dwordx4 v[144:145], off
	s_add_i32 m0, s34, 0x2000
	s_add_u32 s30, s30, 0x80080
	v_lshl_add_u64 v[144:145], v[174:175], 0, s[12:13]
	s_addc_u32 s31, s31, 0
	s_add_i32 s34, s64, s37
	global_load_lds_dwordx4 v[144:145], off
	v_lshl_add_u64 v[144:145], s[30:31], 0, v[130:131]
	s_mov_b32 m0, s34
	s_nop 0
	global_load_lds_dwordx4 v[144:145], off
	v_lshl_add_u64 v[144:145], s[30:31], 0, v[134:135]
	s_add_i32 m0, s34, 0x2000
	s_nop 0
	global_load_lds_dwordx4 v[144:145], off
	v_lshl_add_u64 v[144:145], v[236:237], 0, s[12:13]
	s_mov_b32 m0, s47
	s_nop 0
	global_load_lds_dwordx4 v[144:145], off
	v_lshl_add_u64 v[144:145], v[238:239], 0, s[12:13]
	s_mov_b32 m0, s48
	s_nop 0
	global_load_lds_dwordx4 v[144:145], off
	s_waitcnt vmcnt(8)
	s_waitcnt lgkmcnt(0)
	s_barrier
	s_setprio 1
	s_waitcnt lgkmcnt(0)
	v_mfma_f32_16x16x32_bf16 v[60:63], v[166:169], v[202:205], v[60:63]
	v_mfma_f32_16x16x32_bf16 v[56:59], v[178:181], v[202:205], v[56:59]
	v_mfma_f32_16x16x32_bf16 v[52:55], v[166:169], v[212:215], v[52:55]
	v_mfma_f32_16x16x32_bf16 v[44:47], v[178:181], v[212:215], v[44:47]
	v_mfma_f32_16x16x32_bf16 v[36:39], v[166:169], v[220:223], v[36:39]
	v_mfma_f32_16x16x32_bf16 v[28:31], v[178:181], v[220:223], v[28:31]
	v_mfma_f32_16x16x32_bf16 v[20:23], v[166:169], v[228:231], v[20:23]
	v_mfma_f32_16x16x32_bf16 v[12:15], v[178:181], v[228:231], v[12:15]
	v_mfma_f32_16x16x32_bf16 v[60:63], v[170:173], v[208:211], v[60:63]
	v_mfma_f32_16x16x32_bf16 v[56:59], v[182:185], v[208:211], v[56:59]
	v_mfma_f32_16x16x32_bf16 v[52:55], v[170:173], v[216:219], v[52:55]
	v_mfma_f32_16x16x32_bf16 v[44:47], v[182:185], v[216:219], v[44:47]
	v_mfma_f32_16x16x32_bf16 v[36:39], v[170:173], v[224:227], v[36:39]
	v_mfma_f32_16x16x32_bf16 v[28:31], v[182:185], v[224:227], v[28:31]
	v_mfma_f32_16x16x32_bf16 v[20:23], v[170:173], v[232:235], v[20:23]
	v_mfma_f32_16x16x32_bf16 v[12:15], v[182:185], v[232:235], v[12:15]
	v_mfma_f32_16x16x32_bf16 v[48:51], v[186:189], v[202:205], v[48:51]
	v_mfma_f32_16x16x32_bf16 v[40:43], v[194:197], v[202:205], v[40:43]
	v_mfma_f32_16x16x32_bf16 v[32:35], v[186:189], v[212:215], v[32:35]
	v_mfma_f32_16x16x32_bf16 v[24:27], v[194:197], v[212:215], v[24:27]
	v_mfma_f32_16x16x32_bf16 v[16:19], v[186:189], v[220:223], v[16:19]
	v_mfma_f32_16x16x32_bf16 v[8:11], v[194:197], v[220:223], v[8:11]
	v_mfma_f32_16x16x32_bf16 v[4:7], v[186:189], v[228:231], v[4:7]
	v_mfma_f32_16x16x32_bf16 v[0:3], v[194:197], v[228:231], v[0:3]
	v_mfma_f32_16x16x32_bf16 v[48:51], v[190:193], v[208:211], v[48:51]
	v_mfma_f32_16x16x32_bf16 v[40:43], v[198:201], v[208:211], v[40:43]
	v_mfma_f32_16x16x32_bf16 v[32:35], v[190:193], v[216:219], v[32:35]
	v_mfma_f32_16x16x32_bf16 v[24:27], v[198:201], v[216:219], v[24:27]
	v_mfma_f32_16x16x32_bf16 v[16:19], v[190:193], v[224:227], v[16:19]
	v_mfma_f32_16x16x32_bf16 v[8:11], v[198:201], v[224:227], v[8:11]
	v_mfma_f32_16x16x32_bf16 v[4:7], v[190:193], v[232:235], v[4:7]
	v_mfma_f32_16x16x32_bf16 v[0:3], v[198:201], v[232:235], v[0:3]
	s_setprio 0
	s_barrier
	s_add_i32 s62, s62, 2
	s_add_u32 s28, s28, 0x100
	s_addc_u32 s29, s29, 0
	s_add_u32 s60, s60, 0x100
	s_addc_u32 s61, s61, 0
	s_cmp_gt_u32 s62, 5
	s_cbranch_scc0 .LBB0_358
	s_and_b64 vcc, exec, s[14:15]
	s_cbranch_vccz .LBB0_361
	s_barrier

; #define PG8_STAGE(bufoff, gbase, voff) do { _Pragma("unroll") for (int _i = 0; _i < 2; ++_i) \
;         __builtin_amdgcn_global_load_lds((const unsigned*)((const char*)(gbase) + (voff)[_i]), (LAS unsigned*)(lds + (bufoff) + ldsw + _i * 8192), 16, 0, 0); } while (0)
; #define PG8_LDA(dst, b, h) do { _Pragma("unroll") for (int m = 0; m < 4; ++m) _Pragma("unroll") for (int k = 0; k < 2; ++k) dst[m][k] = *(const LAS bf16x8*)(lds + PG8_SA(b, h) + aoff + m * 2048 + k * 1024); } while (0)
; #define PG8_LDB(dst, b, h) do { _Pragma("unroll") for (int n = 0; n < 2; ++n) _Pragma("unroll") for (int k = 0; k < 2; ++k) dst[n][k] = *(const LAS bf16x8*)(lds + PG8_SB(b, h) + boff + n * 2048 + k * 1024); } while (0)
; #define PG8_MMA(ai, bj, At, Bt) do { __builtin_amdgcn_s_setprio(1); _Pragma("unroll") for (int m = 0; m < 4; ++m) _Pragma("unroll") for (int n = 0; n < 2; ++n) _Pragma("unroll") for (int k = 0; k < 2; ++k) \
;         acc[ai][bj][m][n] = __builtin_amdgcn_mfma_f32_16x16x32_bf16(Bt[n][k], At[m][k], acc[ai][bj][m][n], 0, 0, 0); __builtin_amdgcn_s_setprio(0); } while (0)
; #define PG8_WAIT_V(n) asm volatile("s_waitcnt vmcnt(" #n ")" ::: "memory")
; #define PG8_WAIT_L(n) asm volatile("s_waitcnt lgkmcnt(" #n ")" ::: "memory")
; #define PG8_BAR __builtin_amdgcn_s_barrier()
; #define PG8_SCHED __builtin_amdgcn_sched_barrier(0)
; template <class Epi>
; __device__ __forceinline__ void gemm_phase(LAS unsigned char* lds, const Gemm g, const Order& S, const Epi& E) {
;     ...
;         for (int t = 0; t < nt; t += 2) {
;             const bool last = (t == nt - 2);
;             const char* a1 = cA + (size_t)(t + 1) * kstep;
;             const char* a2 = last ? nA : cA + (size_t)(t + 2) * kstep; const char* b2 = last ? nB : cB + (size_t)(t + 2) * kstep;
;             const char* a3 = a2 + kstep; const char* b3 = b2 + kstep;
;             PG8_LDB(B0, 0, 0); PG8_LDB(B1, 0, 1); PG8_SCHED; PG8_LDA(At, 0, 0); PG8_STAGE(PG8_SA(1, 1), a1 + hstepA, voffA);
;             PG8_WAIT_V(8); PG8_WAIT_L(0); PG8_BAR; PG8_MMA(0, 0, At, B0); PG8_MMA(0, 1, At, B1); PG8_BAR; PG8_SCHED;
;             PG8_LDA(At, 0, 1); PG8_STAGE(PG8_SB(0, 0), b2, voffB); PG8_STAGE(PG8_SB(0, 1), b2 + hstepB, voffB); PG8_STAGE(PG8_SA(0, 0), a2, voffA);
.LBB0_382:
	ds_read_b128 v[156:159], v147
	ds_read_b128 v[160:163], v147 offset:1024
	ds_read_b128 v[164:167], v147 offset:2048
	ds_read_b128 v[168:171], v147 offset:3072
	ds_read_b128 v[172:175], v148
	ds_read_b128 v[178:181], v148 offset:1024
	ds_read_b128 v[182:185], v148 offset:2048
	ds_read_b128 v[186:189], v148 offset:3072
	s_add_u32 s34, s30, 0xfff80080
	s_addc_u32 s35, s31, -1
	s_cmp_eq_u32 s61, 4
	s_cselect_b32 s37, s21, s35
	s_cselect_b32 s36, s56, s34
	s_cselect_b32 s35, s57, s60
	s_cselect_b32 s34, s58, s59
	v_lshl_add_u64 v[144:145], s[30:31], 0, v[136:137]
	s_add_i32 m0, s8, 0xc000
	ds_read_b128 v[190:193], v149
	ds_read_b128 v[194:197], v149 offset:1024
	ds_read_b128 v[198:201], v149 offset:2048
	ds_read_b128 v[202:205], v149 offset:3072
	ds_read_b128 v[208:211], v149 offset:4096
	ds_read_b128 v[212:215], v149 offset:5120
	ds_read_b128 v[216:219], v149 offset:6144
	ds_read_b128 v[220:223], v149 offset:7168
	global_load_lds_dwordx4 v[144:145], off
	v_lshl_add_u64 v[144:145], s[30:31], 0, v[138:139]
	s_add_i32 m0, s8, 0xe000
	s_nop 0
	global_load_lds_dwordx4 v[144:145], off
	s_waitcnt vmcnt(8)
	s_waitcnt lgkmcnt(0)
	s_barrier
	s_setprio 1
	s_waitcnt lgkmcnt(0)
	v_mfma_f32_16x16x32_bf16 v[124:127], v[156:159], v[190:193], v[124:127]
	v_mfma_f32_16x16x32_bf16 v[120:123], v[164:167], v[190:193], v[120:123]
	v_mfma_f32_16x16x32_bf16 v[116:119], v[156:159], v[198:201], v[116:119]
	v_mfma_f32_16x16x32_bf16 v[108:111], v[164:167], v[198:201], v[108:111]
	v_mfma_f32_16x16x32_bf16 v[100:103], v[156:159], v[208:211], v[100:103]
	v_mfma_f32_16x16x32_bf16 v[92:95], v[164:167], v[208:211], v[92:95]
	v_mfma_f32_16x16x32_bf16 v[84:87], v[156:159], v[216:219], v[84:87]
	v_mfma_f32_16x16x32_bf16 v[76:79], v[164:167], v[216:219], v[76:79]
	v_mfma_f32_16x16x32_bf16 v[124:127], v[160:163], v[194:197], v[124:127]
	v_mfma_f32_16x16x32_bf16 v[120:123], v[168:171], v[194:197], v[120:123]
	v_mfma_f32_16x16x32_bf16 v[116:119], v[160:163], v[202:205], v[116:119]
	v_mfma_f32_16x16x32_bf16 v[108:111], v[168:171], v[202:205], v[108:111]
	v_mfma_f32_16x16x32_bf16 v[100:103], v[160:163], v[212:215], v[100:103]
	v_mfma_f32_16x16x32_bf16 v[92:95], v[168:171], v[212:215], v[92:95]
	v_mfma_f32_16x16x32_bf16 v[84:87], v[160:163], v[220:223], v[84:87]
	v_mfma_f32_16x16x32_bf16 v[76:79], v[168:171], v[220:223], v[76:79]
	v_mfma_f32_16x16x32_bf16 v[112:115], v[172:175], v[190:193], v[112:115]
	v_mfma_f32_16x16x32_bf16 v[104:107], v[182:185], v[190:193], v[104:107]
	v_mfma_f32_16x16x32_bf16 v[96:99], v[172:175], v[198:201], v[96:99]
	v_mfma_f32_16x16x32_bf16 v[88:91], v[182:185], v[198:201], v[88:91]
	v_mfma_f32_16x16x32_bf16 v[80:83], v[172:175], v[208:211], v[80:83]
	v_mfma_f32_16x16x32_bf16 v[72:75], v[182:185], v[208:211], v[72:75]
	v_mfma_f32_16x16x32_bf16 v[68:71], v[172:175], v[216:219], v[68:71]
	v_mfma_f32_16x16x32_bf16 v[64:67], v[182:185], v[216:219], v[64:67]
	v_mfma_f32_16x16x32_bf16 v[112:115], v[178:181], v[194:197], v[112:115]
	v_mfma_f32_16x16x32_bf16 v[104:107], v[186:189], v[194:197], v[104:107]
	v_mfma_f32_16x16x32_bf16 v[96:99], v[178:181], v[202:205], v[96:99]
	v_mfma_f32_16x16x32_bf16 v[88:91], v[186:189], v[202:205], v[88:91]
	v_mfma_f32_16x16x32_bf16 v[80:83], v[178:181], v[212:215], v[80:83]
	v_mfma_f32_16x16x32_bf16 v[72:75], v[186:189], v[212:215], v[72:75]
	v_mfma_f32_16x16x32_bf16 v[68:71], v[178:181], v[220:223], v[68:71]
	v_mfma_f32_16x16x32_bf16 v[64:67], v[186:189], v[220:223], v[64:67]
	s_setprio 0
	s_barrier
	s_add_i32 s62, s49, s40
	v_lshl_add_u64 v[144:145], s[34:35], 0, v[130:131]
	s_mov_b32 m0, s62
	ds_read_b128 v[190:193], v149 offset:16384
	ds_read_b128 v[194:197], v149 offset:17408
	ds_read_b128 v[198:201], v149 offset:18432
	ds_read_b128 v[202:205], v149 offset:19456
	ds_read_b128 v[208:211], v149 offset:20480
	ds_read_b128 v[212:215], v149 offset:21504
	ds_read_b128 v[216:219], v149 offset:22528
	ds_read_b128 v[220:223], v149 offset:23552
	global_load_lds_dwordx4 v[144:145], off
	s_add_i32 m0, s62, 0x2000
	s_add_u32 s62, s34, 0x100000
	v_lshl_add_u64 v[224:225], s[34:35], 0, v[134:135]
	s_addc_u32 s63, s35, 0
	s_add_i32 s64, s50, s40
	global_load_lds_dwordx4 v[224:225], off
	v_lshl_add_u64 v[226:227], s[62:63], 0, v[130:131]
	s_mov_b32 m0, s64
	v_lshl_add_u64 v[228:229], s[36:37], 0, v[132:133]
	global_load_lds_dwordx4 v[226:227], off
	v_lshl_add_u64 v[226:227], s[62:63], 0, v[134:135]
	s_add_i32 m0, s64, 0x2000
	s_nop 0
	global_load_lds_dwordx4 v[226:227], off
	v_lshl_add_u64 v[226:227], s[36:37], 0, v[128:129]
	s_mov_b32 m0, s8
	s_nop 0
	global_load_lds_dwordx4 v[226:227], off
	s_mov_b32 m0, s41
	s_nop 0
	global_load_lds_dwordx4 v[228:229], off
	s_waitcnt vmcnt(8)
	s_waitcnt lgkmcnt(0)
	s_barrier
; #define PG8_STAGE(bufoff, gbase, voff) do { _Pragma("unroll") for (int _i = 0; _i < 2; ++_i) \
;         __builtin_amdgcn_global_load_lds((const unsigned*)((const char*)(gbase) + (voff)[_i]), (LAS unsigned*)(lds + (bufoff) + ldsw + _i * 8192), 16, 0, 0); } while (0)
; #define PG8_LDA(dst, b, h) do { _Pragma("unroll") for (int m = 0; m < 4; ++m) _Pragma("unroll") for (int k = 0; k < 2; ++k) dst[m][k] = *(const LAS bf16x8*)(lds + PG8_SA(b, h) + aoff + m * 2048 + k * 1024); } while (0)
; #define PG8_LDB(dst, b, h) do { _Pragma("unroll") for (int n = 0; n < 2; ++n) _Pragma("unroll") for (int k = 0; k < 2; ++k) dst[n][k] = *(const LAS bf16x8*)(lds + PG8_SB(b, h) + boff + n * 2048 + k * 1024); } while (0)
; #define PG8_MMA(ai, bj, At, Bt) do { __builtin_amdgcn_s_setprio(1); _Pragma("unroll") for (int m = 0; m < 4; ++m) _Pragma("unroll") for (int n = 0; n < 2; ++n) _Pragma("unroll") for (int k = 0; k < 2; ++k) \
;         acc[ai][bj][m][n] = __builtin_amdgcn_mfma_f32_16x16x32_bf16(Bt[n][k], At[m][k], acc[ai][bj][m][n], 0, 0, 0); __builtin_amdgcn_s_setprio(0); } while (0)
; #define PG8_WAIT_V(n) asm volatile("s_waitcnt vmcnt(" #n ")" ::: "memory")
; #define PG8_WAIT_L(n) asm volatile("s_waitcnt lgkmcnt(" #n ")" ::: "memory")
; #define PG8_BAR __builtin_amdgcn_s_barrier()
; #define PG8_SCHED __builtin_amdgcn_sched_barrier(0)
; template <class Epi>
; __device__ __forceinline__ void gemm_phase(LAS unsigned char* lds, const Gemm g, const Order& S, const Epi& E) {
;     ...
;             PG8_WAIT_V(8); PG8_WAIT_L(0); PG8_BAR; PG8_MMA(1, 0, At, B0); PG8_MMA(1, 1, At, B1); PG8_BAR; PG8_SCHED;
;             PG8_LDB(B0, 1, 0); PG8_LDB(B1, 1, 1); PG8_SCHED; PG8_LDA(At, 1, 0); PG8_STAGE(PG8_SA(0, 1), a2 + hstepA, voffA);
;             PG8_WAIT_V(8); PG8_WAIT_L(0); PG8_BAR; PG8_MMA(0, 0, At, B0); PG8_MMA(0, 1, At, B1); PG8_BAR; PG8_SCHED;
	s_setprio 1
	s_waitcnt lgkmcnt(0)
	v_mfma_f32_16x16x32_bf16 v[60:63], v[156:159], v[190:193], v[60:63]
	v_mfma_f32_16x16x32_bf16 v[56:59], v[164:167], v[190:193], v[56:59]
	v_mfma_f32_16x16x32_bf16 v[52:55], v[156:159], v[198:201], v[52:55]
	v_mfma_f32_16x16x32_bf16 v[44:47], v[164:167], v[198:201], v[44:47]
	v_mfma_f32_16x16x32_bf16 v[36:39], v[156:159], v[208:211], v[36:39]
	v_mfma_f32_16x16x32_bf16 v[28:31], v[164:167], v[208:211], v[28:31]
	v_mfma_f32_16x16x32_bf16 v[20:23], v[156:159], v[216:219], v[20:23]
	v_mfma_f32_16x16x32_bf16 v[12:15], v[164:167], v[216:219], v[12:15]
	v_mfma_f32_16x16x32_bf16 v[60:63], v[160:163], v[194:197], v[60:63]
	v_mfma_f32_16x16x32_bf16 v[56:59], v[168:171], v[194:197], v[56:59]
	v_mfma_f32_16x16x32_bf16 v[52:55], v[160:163], v[202:205], v[52:55]
	v_mfma_f32_16x16x32_bf16 v[44:47], v[168:171], v[202:205], v[44:47]
	v_mfma_f32_16x16x32_bf16 v[36:39], v[160:163], v[212:215], v[36:39]
	v_mfma_f32_16x16x32_bf16 v[28:31], v[168:171], v[212:215], v[28:31]
	v_mfma_f32_16x16x32_bf16 v[20:23], v[160:163], v[220:223], v[20:23]
	v_mfma_f32_16x16x32_bf16 v[12:15], v[168:171], v[220:223], v[12:15]
	v_mfma_f32_16x16x32_bf16 v[48:51], v[172:175], v[190:193], v[48:51]
	v_mfma_f32_16x16x32_bf16 v[40:43], v[182:185], v[190:193], v[40:43]
	v_mfma_f32_16x16x32_bf16 v[32:35], v[172:175], v[198:201], v[32:35]
	v_mfma_f32_16x16x32_bf16 v[24:27], v[182:185], v[198:201], v[24:27]
	v_mfma_f32_16x16x32_bf16 v[16:19], v[172:175], v[208:211], v[16:19]
	v_mfma_f32_16x16x32_bf16 v[8:11], v[182:185], v[208:211], v[8:11]
	v_mfma_f32_16x16x32_bf16 v[4:7], v[172:175], v[216:219], v[4:7]
	v_mfma_f32_16x16x32_bf16 v[0:3], v[182:185], v[216:219], v[0:3]
	v_mfma_f32_16x16x32_bf16 v[48:51], v[178:181], v[194:197], v[48:51]
	v_mfma_f32_16x16x32_bf16 v[40:43], v[186:189], v[194:197], v[40:43]
	v_mfma_f32_16x16x32_bf16 v[32:35], v[178:181], v[202:205], v[32:35]
	v_mfma_f32_16x16x32_bf16 v[24:27], v[186:189], v[202:205], v[24:27]
	v_mfma_f32_16x16x32_bf16 v[16:19], v[178:181], v[212:215], v[16:19]
	v_mfma_f32_16x16x32_bf16 v[8:11], v[186:189], v[212:215], v[8:11]
	v_mfma_f32_16x16x32_bf16 v[4:7], v[178:181], v[220:223], v[4:7]
	v_mfma_f32_16x16x32_bf16 v[0:3], v[186:189], v[220:223], v[0:3]
	s_setprio 0
	s_barrier
	s_add_i32 s62, 0, 0x18000
	v_add_u32_e32 v151, s62, v150
	s_add_i32 s63, 0, 0x1c000
	ds_read_b128 v[156:159], v151
	ds_read_b128 v[160:163], v151 offset:1024
	ds_read_b128 v[164:167], v151 offset:2048
	ds_read_b128 v[168:171], v151 offset:3072
	v_add_u32_e32 v151, s63, v150
	ds_read_b128 v[172:175], v151
	ds_read_b128 v[178:181], v151 offset:1024
	ds_read_b128 v[182:185], v151 offset:2048
	ds_read_b128 v[186:189], v151 offset:3072
	s_add_u32 s36, s36, 0x80000
	s_addc_u32 s37, s37, 0
	s_mov_b32 m0, s42
	v_lshl_add_u64 v[230:231], s[36:37], 0, v[128:129]
	ds_read_b128 v[190:193], v149 offset:32768
	ds_read_b128 v[194:197], v149 offset:33792
	ds_read_b128 v[198:201], v149 offset:34816
	ds_read_b128 v[202:205], v149 offset:35840
	ds_read_b128 v[208:211], v149 offset:36864
	ds_read_b128 v[212:215], v149 offset:37888
	ds_read_b128 v[216:219], v149 offset:38912
	ds_read_b128 v[220:223], v149 offset:39936
	global_load_lds_dwordx4 v[230:231], off
	v_lshl_add_u64 v[230:231], s[36:37], 0, v[132:133]
	s_mov_b32 m0, s43
	s_nop 0
	global_load_lds_dwordx4 v[230:231], off
	s_waitcnt vmcnt(8)
	s_waitcnt lgkmcnt(0)
	s_barrier
	s_setprio 1
	s_waitcnt lgkmcnt(0)
	v_mfma_f32_16x16x32_bf16 v[124:127], v[156:159], v[190:193], v[124:127]
	v_mfma_f32_16x16x32_bf16 v[120:123], v[164:167], v[190:193], v[120:123]
	v_mfma_f32_16x16x32_bf16 v[116:119], v[156:159], v[198:201], v[116:119]
	v_mfma_f32_16x16x32_bf16 v[108:111], v[164:167], v[198:201], v[108:111]
	v_mfma_f32_16x16x32_bf16 v[100:103], v[156:159], v[208:211], v[100:103]
	v_mfma_f32_16x16x32_bf16 v[92:95], v[164:167], v[208:211], v[92:95]
	v_mfma_f32_16x16x32_bf16 v[84:87], v[156:159], v[216:219], v[84:87]
	v_mfma_f32_16x16x32_bf16 v[76:79], v[164:167], v[216:219], v[76:79]
	v_mfma_f32_16x16x32_bf16 v[124:127], v[160:163], v[194:197], v[124:127]
	v_mfma_f32_16x16x32_bf16 v[120:123], v[168:171], v[194:197], v[120:123]
	v_mfma_f32_16x16x32_bf16 v[116:119], v[160:163], v[202:205], v[116:119]
	v_mfma_f32_16x16x32_bf16 v[108:111], v[168:171], v[202:205], v[108:111]
	v_mfma_f32_16x16x32_bf16 v[100:103], v[160:163], v[212:215], v[100:103]
	v_mfma_f32_16x16x32_bf16 v[92:95], v[168:171], v[212:215], v[92:95]
	v_mfma_f32_16x16x32_bf16 v[84:87], v[160:163], v[220:223], v[84:87]
	v_mfma_f32_16x16x32_bf16 v[76:79], v[168:171], v[220:223], v[76:79]
	v_mfma_f32_16x16x32_bf16 v[112:115], v[172:175], v[190:193], v[112:115]
	v_mfma_f32_16x16x32_bf16 v[104:107], v[182:185], v[190:193], v[104:107]
	v_mfma_f32_16x16x32_bf16 v[96:99], v[172:175], v[198:201], v[96:99]
	v_mfma_f32_16x16x32_bf16 v[88:91], v[182:185], v[198:201], v[88:91]
	v_mfma_f32_16x16x32_bf16 v[80:83], v[172:175], v[208:211], v[80:83]
	v_mfma_f32_16x16x32_bf16 v[72:75], v[182:185], v[208:211], v[72:75]
	v_mfma_f32_16x16x32_bf16 v[68:71], v[172:175], v[216:219], v[68:71]
	v_mfma_f32_16x16x32_bf16 v[64:67], v[182:185], v[216:219], v[64:67]
	v_mfma_f32_16x16x32_bf16 v[112:115], v[178:181], v[194:197], v[112:115]
	v_mfma_f32_16x16x32_bf16 v[104:107], v[186:189], v[194:197], v[104:107]
	v_mfma_f32_16x16x32_bf16 v[96:99], v[178:181], v[202:205], v[96:99]
	v_mfma_f32_16x16x32_bf16 v[88:91], v[186:189], v[202:205], v[88:91]
	v_mfma_f32_16x16x32_bf16 v[80:83], v[178:181], v[212:215], v[80:83]
	v_mfma_f32_16x16x32_bf16 v[72:75], v[186:189], v[212:215], v[72:75]
	v_mfma_f32_16x16x32_bf16 v[68:71], v[178:181], v[220:223], v[68:71]
	v_mfma_f32_16x16x32_bf16 v[64:67], v[186:189], v[220:223], v[64:67]
	s_setprio 0
	s_barrier
; #define PG8_STAGE(bufoff, gbase, voff) do { _Pragma("unroll") for (int _i = 0; _i < 2; ++_i) \
;         __builtin_amdgcn_global_load_lds((const unsigned*)((const char*)(gbase) + (voff)[_i]), (LAS unsigned*)(lds + (bufoff) + ldsw + _i * 8192), 16, 0, 0); } while (0)
; #define PG8_LDA(dst, b, h) do { _Pragma("unroll") for (int m = 0; m < 4; ++m) _Pragma("unroll") for (int k = 0; k < 2; ++k) dst[m][k] = *(const LAS bf16x8*)(lds + PG8_SA(b, h) + aoff + m * 2048 + k * 1024); } while (0)
; #define PG8_MMA(ai, bj, At, Bt) do { __builtin_amdgcn_s_setprio(1); _Pragma("unroll") for (int m = 0; m < 4; ++m) _Pragma("unroll") for (int n = 0; n < 2; ++n) _Pragma("unroll") for (int k = 0; k < 2; ++k) \
;         acc[ai][bj][m][n] = __builtin_amdgcn_mfma_f32_16x16x32_bf16(Bt[n][k], At[m][k], acc[ai][bj][m][n], 0, 0, 0); __builtin_amdgcn_s_setprio(0); } while (0)
; #define PG8_WAIT_V(n) asm volatile("s_waitcnt vmcnt(" #n ")" ::: "memory")
; #define PG8_WAIT_L(n) asm volatile("s_waitcnt lgkmcnt(" #n ")" ::: "memory")
; #define PG8_BAR __builtin_amdgcn_s_barrier()
; #define PG8_SCHED __builtin_amdgcn_sched_barrier(0)
; template <class Epi>
; __device__ __forceinline__ void gemm_phase(LAS unsigned char* lds, const Gemm g, const Order& S, const Epi& E) {
;     ...
;             PG8_LDA(At, 1, 1); PG8_STAGE(PG8_SB(1, 0), b3, voffB); PG8_STAGE(PG8_SB(1, 1), b3 + hstepB, voffB); PG8_STAGE(PG8_SA(1, 0), a3, voffA);
;             PG8_WAIT_V(8); PG8_WAIT_L(0); PG8_BAR; PG8_MMA(1, 0, At, B0); PG8_MMA(1, 1, At, B1); PG8_BAR; PG8_SCHED;
;         }
;         if (wr == 0) PG8_BAR;
	s_add_i32 s36, s62, s40
	v_lshl_add_u64 v[144:145], v[144:145], 0, s[14:15]
	s_mov_b32 m0, s36
	ds_read_b128 v[190:193], v149 offset:49152
	ds_read_b128 v[194:197], v149 offset:50176
	ds_read_b128 v[198:201], v149 offset:51200
	ds_read_b128 v[202:205], v149 offset:52224
	ds_read_b128 v[208:211], v149 offset:53248
	ds_read_b128 v[212:215], v149 offset:54272
	ds_read_b128 v[216:219], v149 offset:55296
	ds_read_b128 v[220:223], v149 offset:56320
	global_load_lds_dwordx4 v[144:145], off
	s_add_i32 m0, s36, 0x2000
	s_add_u32 s34, s34, 0x100080
	v_lshl_add_u64 v[144:145], v[224:225], 0, s[14:15]
	s_addc_u32 s35, s35, 0
	s_add_i32 s36, s63, s40
	global_load_lds_dwordx4 v[144:145], off
	v_lshl_add_u64 v[144:145], s[34:35], 0, v[130:131]
	s_mov_b32 m0, s36
	s_nop 0
	global_load_lds_dwordx4 v[144:145], off
	v_lshl_add_u64 v[144:145], s[34:35], 0, v[134:135]
	s_add_i32 m0, s36, 0x2000
	s_nop 0
	global_load_lds_dwordx4 v[144:145], off
	v_lshl_add_u64 v[144:145], v[226:227], 0, s[14:15]
	s_mov_b32 m0, s46
	s_nop 0
	global_load_lds_dwordx4 v[144:145], off
	v_lshl_add_u64 v[144:145], v[228:229], 0, s[14:15]
	s_mov_b32 m0, s47
	s_nop 0
	global_load_lds_dwordx4 v[144:145], off
	s_waitcnt vmcnt(8)
	s_waitcnt lgkmcnt(0)
	s_barrier
	s_setprio 1
	s_waitcnt lgkmcnt(0)
	v_mfma_f32_16x16x32_bf16 v[60:63], v[156:159], v[190:193], v[60:63]
	v_mfma_f32_16x16x32_bf16 v[56:59], v[164:167], v[190:193], v[56:59]
	v_mfma_f32_16x16x32_bf16 v[52:55], v[156:159], v[198:201], v[52:55]
	v_mfma_f32_16x16x32_bf16 v[44:47], v[164:167], v[198:201], v[44:47]
	v_mfma_f32_16x16x32_bf16 v[36:39], v[156:159], v[208:211], v[36:39]
	v_mfma_f32_16x16x32_bf16 v[28:31], v[164:167], v[208:211], v[28:31]
	v_mfma_f32_16x16x32_bf16 v[20:23], v[156:159], v[216:219], v[20:23]
	v_mfma_f32_16x16x32_bf16 v[12:15], v[164:167], v[216:219], v[12:15]
	v_mfma_f32_16x16x32_bf16 v[60:63], v[160:163], v[194:197], v[60:63]
	v_mfma_f32_16x16x32_bf16 v[56:59], v[168:171], v[194:197], v[56:59]
	v_mfma_f32_16x16x32_bf16 v[52:55], v[160:163], v[202:205], v[52:55]
	v_mfma_f32_16x16x32_bf16 v[44:47], v[168:171], v[202:205], v[44:47]
	v_mfma_f32_16x16x32_bf16 v[36:39], v[160:163], v[212:215], v[36:39]
	v_mfma_f32_16x16x32_bf16 v[28:31], v[168:171], v[212:215], v[28:31]
	v_mfma_f32_16x16x32_bf16 v[20:23], v[160:163], v[220:223], v[20:23]
	v_mfma_f32_16x16x32_bf16 v[12:15], v[168:171], v[220:223], v[12:15]
	v_mfma_f32_16x16x32_bf16 v[48:51], v[172:175], v[190:193], v[48:51]
	v_mfma_f32_16x16x32_bf16 v[40:43], v[182:185], v[190:193], v[40:43]
	v_mfma_f32_16x16x32_bf16 v[32:35], v[172:175], v[198:201], v[32:35]
	v_mfma_f32_16x16x32_bf16 v[24:27], v[182:185], v[198:201], v[24:27]
	v_mfma_f32_16x16x32_bf16 v[16:19], v[172:175], v[208:211], v[16:19]
	v_mfma_f32_16x16x32_bf16 v[8:11], v[182:185], v[208:211], v[8:11]
	v_mfma_f32_16x16x32_bf16 v[4:7], v[172:175], v[216:219], v[4:7]
	v_mfma_f32_16x16x32_bf16 v[0:3], v[182:185], v[216:219], v[0:3]
	v_mfma_f32_16x16x32_bf16 v[48:51], v[178:181], v[194:197], v[48:51]
	v_mfma_f32_16x16x32_bf16 v[40:43], v[186:189], v[194:197], v[40:43]
	v_mfma_f32_16x16x32_bf16 v[32:35], v[178:181], v[202:205], v[32:35]
	v_mfma_f32_16x16x32_bf16 v[24:27], v[186:189], v[202:205], v[24:27]
	v_mfma_f32_16x16x32_bf16 v[16:19], v[178:181], v[212:215], v[16:19]
	v_mfma_f32_16x16x32_bf16 v[8:11], v[186:189], v[212:215], v[8:11]
	v_mfma_f32_16x16x32_bf16 v[4:7], v[178:181], v[220:223], v[4:7]
	v_mfma_f32_16x16x32_bf16 v[0:3], v[186:189], v[220:223], v[0:3]
	s_setprio 0
	s_barrier
	s_add_i32 s61, s61, 2
	s_add_u32 s30, s30, 0x100
	s_addc_u32 s31, s31, 0
	s_add_u32 s59, s59, 0x100
	s_addc_u32 s60, s60, 0
	s_cmp_gt_u32 s61, 5
	s_cbranch_scc0 .LBB0_382
	s_and_b64 vcc, exec, s[16:17]
	s_cbranch_vccz .LBB0_385
	s_barrier

; #define PG8_STAGE(bufoff, gbase, voff) do { _Pragma("unroll") for (int _i = 0; _i < 2; ++_i) \
;         __builtin_amdgcn_global_load_lds((const unsigned*)((const char*)(gbase) + (voff)[_i]), (LAS unsigned*)(lds + (bufoff) + ldsw + _i * 8192), 16, 0, 0); } while (0)
; #define PG8_LDA(dst, b, h) do { _Pragma("unroll") for (int m = 0; m < 4; ++m) _Pragma("unroll") for (int k = 0; k < 2; ++k) dst[m][k] = *(const LAS bf16x8*)(lds + PG8_SA(b, h) + aoff + m * 2048 + k * 1024); } while (0)
; #define PG8_LDB(dst, b, h) do { _Pragma("unroll") for (int n = 0; n < 2; ++n) _Pragma("unroll") for (int k = 0; k < 2; ++k) dst[n][k] = *(const LAS bf16x8*)(lds + PG8_SB(b, h) + boff + n * 2048 + k * 1024); } while (0)
; #define PG8_MMA(ai, bj, At, Bt) do { __builtin_amdgcn_s_setprio(1); _Pragma("unroll") for (int m = 0; m < 4; ++m) _Pragma("unroll") for (int n = 0; n < 2; ++n) _Pragma("unroll") for (int k = 0; k < 2; ++k) \
;         acc[ai][bj][m][n] = __builtin_amdgcn_mfma_f32_16x16x32_bf16(Bt[n][k], At[m][k], acc[ai][bj][m][n], 0, 0, 0); __builtin_amdgcn_s_setprio(0); } while (0)
; #define PG8_WAIT_V(n) asm volatile("s_waitcnt vmcnt(" #n ")" ::: "memory")
; #define PG8_WAIT_L(n) asm volatile("s_waitcnt lgkmcnt(" #n ")" ::: "memory")
; #define PG8_BAR __builtin_amdgcn_s_barrier()
; #define PG8_SCHED __builtin_amdgcn_sched_barrier(0)
; template <class Epi>
; __device__ __forceinline__ void gemm_phase(LAS unsigned char* lds, const Gemm g, const Order& S, const Epi& E) {
;     ...
;         for (int t = 0; t < nt; t += 2) {
;             const bool last = (t == nt - 2);
;             const char* a1 = cA + (size_t)(t + 1) * kstep;
;             const char* a2 = last ? nA : cA + (size_t)(t + 2) * kstep; const char* b2 = last ? nB : cB + (size_t)(t + 2) * kstep;
;             const char* a3 = a2 + kstep; const char* b3 = b2 + kstep;
;             PG8_LDB(B0, 0, 0); PG8_LDB(B1, 0, 1); PG8_SCHED; PG8_LDA(At, 0, 0); PG8_STAGE(PG8_SA(1, 1), a1 + hstepA, voffA);
;             PG8_WAIT_V(8); PG8_WAIT_L(0); PG8_BAR; PG8_MMA(0, 0, At, B0); PG8_MMA(0, 1, At, B1); PG8_BAR; PG8_SCHED;
;             PG8_LDA(At, 0, 1); PG8_STAGE(PG8_SB(0, 0), b2, voffB); PG8_STAGE(PG8_SB(0, 1), b2 + hstepB, voffB); PG8_STAGE(PG8_SA(0, 0), a2, voffA);
.LBB0_539:
	ds_read_b128 v[128:131], v209
	ds_read_b128 v[132:135], v209 offset:1024
	ds_read_b128 v[136:139], v209 offset:2048
	ds_read_b128 v[140:143], v209 offset:3072
	ds_read_b128 v[144:147], v210
	ds_read_b128 v[148:151], v210 offset:1024
	ds_read_b128 v[152:155], v210 offset:2048
	ds_read_b128 v[156:159], v210 offset:3072
	s_add_u32 s34, s30, 0xfff80080
	s_addc_u32 s35, s31, -1
	s_cmp_eq_u32 s55, 28
	s_cselect_b32 s37, s17, s35
	s_cselect_b32 s36, s19, s34
	s_cselect_b32 s35, s29, s54
	s_cselect_b32 s34, s52, s53
	v_lshl_add_u64 v[218:219], s[30:31], 0, v[186:187]
	s_add_i32 m0, s38, 0xc000
	ds_read_b128 v[160:163], v211
	ds_read_b128 v[164:167], v211 offset:1024
	ds_read_b128 v[168:171], v211 offset:2048
	ds_read_b128 v[172:175], v211 offset:3072
	ds_read_b128 v[194:197], v211 offset:4096
	ds_read_b128 v[198:201], v211 offset:5120
	ds_read_b128 v[202:205], v211 offset:6144
	ds_read_b128 v[214:217], v211 offset:7168
	global_load_lds_dwordx4 v[218:219], off
	v_lshl_add_u64 v[218:219], s[30:31], 0, v[188:189]
	s_add_i32 m0, s38, 0xe000
	s_nop 0
	global_load_lds_dwordx4 v[218:219], off
	s_waitcnt vmcnt(8)
	s_waitcnt lgkmcnt(0)
	s_barrier
	s_setprio 1
	s_waitcnt lgkmcnt(0)
	v_mfma_f32_16x16x32_bf16 v[124:127], v[128:131], v[160:163], v[124:127]
	v_mfma_f32_16x16x32_bf16 v[120:123], v[136:139], v[160:163], v[120:123]
	v_mfma_f32_16x16x32_bf16 v[108:111], v[128:131], v[168:171], v[108:111]
	v_mfma_f32_16x16x32_bf16 v[104:107], v[136:139], v[168:171], v[104:107]
	v_mfma_f32_16x16x32_bf16 v[92:95], v[128:131], v[194:197], v[92:95]
	v_mfma_f32_16x16x32_bf16 v[88:91], v[136:139], v[194:197], v[88:91]
	v_mfma_f32_16x16x32_bf16 v[76:79], v[128:131], v[202:205], v[76:79]
	v_mfma_f32_16x16x32_bf16 v[72:75], v[136:139], v[202:205], v[72:75]
	v_mfma_f32_16x16x32_bf16 v[124:127], v[132:135], v[164:167], v[124:127]
	v_mfma_f32_16x16x32_bf16 v[120:123], v[140:143], v[164:167], v[120:123]
	v_mfma_f32_16x16x32_bf16 v[108:111], v[132:135], v[172:175], v[108:111]
	v_mfma_f32_16x16x32_bf16 v[104:107], v[140:143], v[172:175], v[104:107]
	v_mfma_f32_16x16x32_bf16 v[92:95], v[132:135], v[198:201], v[92:95]
	v_mfma_f32_16x16x32_bf16 v[88:91], v[140:143], v[198:201], v[88:91]
	v_mfma_f32_16x16x32_bf16 v[76:79], v[132:135], v[214:217], v[76:79]
	v_mfma_f32_16x16x32_bf16 v[72:75], v[140:143], v[214:217], v[72:75]
	v_mfma_f32_16x16x32_bf16 v[116:119], v[144:147], v[160:163], v[116:119]
	v_mfma_f32_16x16x32_bf16 v[112:115], v[152:155], v[160:163], v[112:115]
	v_mfma_f32_16x16x32_bf16 v[100:103], v[144:147], v[168:171], v[100:103]
	v_mfma_f32_16x16x32_bf16 v[96:99], v[152:155], v[168:171], v[96:99]
	v_mfma_f32_16x16x32_bf16 v[84:87], v[144:147], v[194:197], v[84:87]
	v_mfma_f32_16x16x32_bf16 v[80:83], v[152:155], v[194:197], v[80:83]
	v_mfma_f32_16x16x32_bf16 v[68:71], v[144:147], v[202:205], v[68:71]
	v_mfma_f32_16x16x32_bf16 v[64:67], v[152:155], v[202:205], v[64:67]
	v_mfma_f32_16x16x32_bf16 v[116:119], v[148:151], v[164:167], v[116:119]
	v_mfma_f32_16x16x32_bf16 v[112:115], v[156:159], v[164:167], v[112:115]
	v_mfma_f32_16x16x32_bf16 v[100:103], v[148:151], v[172:175], v[100:103]
	v_mfma_f32_16x16x32_bf16 v[96:99], v[156:159], v[172:175], v[96:99]
	v_mfma_f32_16x16x32_bf16 v[84:87], v[148:151], v[198:201], v[84:87]
	v_mfma_f32_16x16x32_bf16 v[80:83], v[156:159], v[198:201], v[80:83]
	v_mfma_f32_16x16x32_bf16 v[68:71], v[148:151], v[214:217], v[68:71]
	v_mfma_f32_16x16x32_bf16 v[64:67], v[156:159], v[214:217], v[64:67]
	s_setprio 0
	s_barrier
	s_add_i32 s56, s49, s33
	v_lshl_add_u64 v[218:219], s[34:35], 0, v[180:181]
	s_mov_b32 m0, s56
	ds_read_b128 v[160:163], v211 offset:16384
	ds_read_b128 v[164:167], v211 offset:17408
	ds_read_b128 v[168:171], v211 offset:18432
	ds_read_b128 v[172:175], v211 offset:19456
	ds_read_b128 v[194:197], v211 offset:20480
	ds_read_b128 v[198:201], v211 offset:21504
	ds_read_b128 v[202:205], v211 offset:22528
	ds_read_b128 v[214:217], v211 offset:23552
	global_load_lds_dwordx4 v[218:219], off
	s_add_i32 m0, s56, 0x2000
	s_add_u32 s56, s34, 0x80000
	v_lshl_add_u64 v[220:221], s[34:35], 0, v[184:185]
	s_addc_u32 s57, s35, 0
	s_add_i32 s58, s50, s33
	global_load_lds_dwordx4 v[220:221], off
	v_lshl_add_u64 v[222:223], s[56:57], 0, v[180:181]
	s_mov_b32 m0, s58
	v_lshl_add_u64 v[224:225], s[36:37], 0, v[182:183]
	global_load_lds_dwordx4 v[222:223], off
	v_lshl_add_u64 v[222:223], s[56:57], 0, v[184:185]
	s_add_i32 m0, s58, 0x2000
	s_nop 0
	global_load_lds_dwordx4 v[222:223], off
	v_lshl_add_u64 v[222:223], s[36:37], 0, v[178:179]
	s_mov_b32 m0, s38
	s_nop 0
	global_load_lds_dwordx4 v[222:223], off
	s_mov_b32 m0, s39
	s_nop 0
	global_load_lds_dwordx4 v[224:225], off
	s_waitcnt vmcnt(8)
	s_waitcnt lgkmcnt(0)
	s_barrier
; #define PG8_STAGE(bufoff, gbase, voff) do { _Pragma("unroll") for (int _i = 0; _i < 2; ++_i) \
;         __builtin_amdgcn_global_load_lds((const unsigned*)((const char*)(gbase) + (voff)[_i]), (LAS unsigned*)(lds + (bufoff) + ldsw + _i * 8192), 16, 0, 0); } while (0)
; #define PG8_LDA(dst, b, h) do { _Pragma("unroll") for (int m = 0; m < 4; ++m) _Pragma("unroll") for (int k = 0; k < 2; ++k) dst[m][k] = *(const LAS bf16x8*)(lds + PG8_SA(b, h) + aoff + m * 2048 + k * 1024); } while (0)
; #define PG8_LDB(dst, b, h) do { _Pragma("unroll") for (int n = 0; n < 2; ++n) _Pragma("unroll") for (int k = 0; k < 2; ++k) dst[n][k] = *(const LAS bf16x8*)(lds + PG8_SB(b, h) + boff + n * 2048 + k * 1024); } while (0)
; #define PG8_MMA(ai, bj, At, Bt) do { __builtin_amdgcn_s_setprio(1); _Pragma("unroll") for (int m = 0; m < 4; ++m) _Pragma("unroll") for (int n = 0; n < 2; ++n) _Pragma("unroll") for (int k = 0; k < 2; ++k) \
;         acc[ai][bj][m][n] = __builtin_amdgcn_mfma_f32_16x16x32_bf16(Bt[n][k], At[m][k], acc[ai][bj][m][n], 0, 0, 0); __builtin_amdgcn_s_setprio(0); } while (0)
; #define PG8_WAIT_V(n) asm volatile("s_waitcnt vmcnt(" #n ")" ::: "memory")
; #define PG8_WAIT_L(n) asm volatile("s_waitcnt lgkmcnt(" #n ")" ::: "memory")
; #define PG8_BAR __builtin_amdgcn_s_barrier()
; #define PG8_SCHED __builtin_amdgcn_sched_barrier(0)
; template <class Epi>
; __device__ __forceinline__ void gemm_phase(LAS unsigned char* lds, const Gemm g, const Order& S, const Epi& E) {
;     ...
;             PG8_WAIT_V(8); PG8_WAIT_L(0); PG8_BAR; PG8_MMA(1, 0, At, B0); PG8_MMA(1, 1, At, B1); PG8_BAR; PG8_SCHED;
;             PG8_LDB(B0, 1, 0); PG8_LDB(B1, 1, 1); PG8_SCHED; PG8_LDA(At, 1, 0); PG8_STAGE(PG8_SA(0, 1), a2 + hstepA, voffA);
;             PG8_WAIT_V(8); PG8_WAIT_L(0); PG8_BAR; PG8_MMA(0, 0, At, B0); PG8_MMA(0, 1, At, B1); PG8_BAR; PG8_SCHED;
	s_setprio 1
	s_waitcnt lgkmcnt(0)
	v_mfma_f32_16x16x32_bf16 v[60:63], v[128:131], v[160:163], v[60:63]
	v_mfma_f32_16x16x32_bf16 v[56:59], v[136:139], v[160:163], v[56:59]
	v_mfma_f32_16x16x32_bf16 v[44:47], v[128:131], v[168:171], v[44:47]
	v_mfma_f32_16x16x32_bf16 v[40:43], v[136:139], v[168:171], v[40:43]
	v_mfma_f32_16x16x32_bf16 v[28:31], v[128:131], v[194:197], v[28:31]
	v_mfma_f32_16x16x32_bf16 v[24:27], v[136:139], v[194:197], v[24:27]
	v_mfma_f32_16x16x32_bf16 v[12:15], v[128:131], v[202:205], v[12:15]
	v_mfma_f32_16x16x32_bf16 v[8:11], v[136:139], v[202:205], v[8:11]
	v_mfma_f32_16x16x32_bf16 v[60:63], v[132:135], v[164:167], v[60:63]
	v_mfma_f32_16x16x32_bf16 v[56:59], v[140:143], v[164:167], v[56:59]
	v_mfma_f32_16x16x32_bf16 v[44:47], v[132:135], v[172:175], v[44:47]
	v_mfma_f32_16x16x32_bf16 v[40:43], v[140:143], v[172:175], v[40:43]
	v_mfma_f32_16x16x32_bf16 v[28:31], v[132:135], v[198:201], v[28:31]
	v_mfma_f32_16x16x32_bf16 v[24:27], v[140:143], v[198:201], v[24:27]
	v_mfma_f32_16x16x32_bf16 v[12:15], v[132:135], v[214:217], v[12:15]
	v_mfma_f32_16x16x32_bf16 v[8:11], v[140:143], v[214:217], v[8:11]
	v_mfma_f32_16x16x32_bf16 v[52:55], v[144:147], v[160:163], v[52:55]
	v_mfma_f32_16x16x32_bf16 v[48:51], v[152:155], v[160:163], v[48:51]
	v_mfma_f32_16x16x32_bf16 v[36:39], v[144:147], v[168:171], v[36:39]
	v_mfma_f32_16x16x32_bf16 v[32:35], v[152:155], v[168:171], v[32:35]
	v_mfma_f32_16x16x32_bf16 v[20:23], v[144:147], v[194:197], v[20:23]
	v_mfma_f32_16x16x32_bf16 v[16:19], v[152:155], v[194:197], v[16:19]
	v_mfma_f32_16x16x32_bf16 v[4:7], v[144:147], v[202:205], v[4:7]
	v_mfma_f32_16x16x32_bf16 v[0:3], v[152:155], v[202:205], v[0:3]
	v_mfma_f32_16x16x32_bf16 v[52:55], v[148:151], v[164:167], v[52:55]
	v_mfma_f32_16x16x32_bf16 v[48:51], v[156:159], v[164:167], v[48:51]
	v_mfma_f32_16x16x32_bf16 v[36:39], v[148:151], v[172:175], v[36:39]
	v_mfma_f32_16x16x32_bf16 v[32:35], v[156:159], v[172:175], v[32:35]
	v_mfma_f32_16x16x32_bf16 v[20:23], v[148:151], v[198:201], v[20:23]
	v_mfma_f32_16x16x32_bf16 v[16:19], v[156:159], v[198:201], v[16:19]
	v_mfma_f32_16x16x32_bf16 v[4:7], v[148:151], v[214:217], v[4:7]
	v_mfma_f32_16x16x32_bf16 v[0:3], v[156:159], v[214:217], v[0:3]
	s_setprio 0
	s_barrier
	s_add_i32 s56, 0, 0x18000
	s_add_i32 s57, 0, 0x1c000
	v_add_u32_e32 v140, s56, v207
	v_add_u32_e32 v156, s57, v207
	ds_read_b128 v[128:131], v140
	ds_read_b128 v[132:135], v140 offset:1024
	ds_read_b128 v[136:139], v140 offset:2048
	ds_read_b128 v[140:143], v140 offset:3072
	ds_read_b128 v[144:147], v156
	ds_read_b128 v[148:151], v156 offset:1024
	ds_read_b128 v[152:155], v156 offset:2048
	ds_read_b128 v[156:159], v156 offset:3072
	s_add_u32 s36, s36, 0x80000
	s_addc_u32 s37, s37, 0
	s_mov_b32 m0, s40
	v_lshl_add_u64 v[226:227], s[36:37], 0, v[178:179]
	ds_read_b128 v[160:163], v211 offset:32768
	ds_read_b128 v[164:167], v211 offset:33792
	ds_read_b128 v[168:171], v211 offset:34816
	ds_read_b128 v[172:175], v211 offset:35840
	ds_read_b128 v[194:197], v211 offset:36864
	ds_read_b128 v[198:201], v211 offset:37888
	ds_read_b128 v[202:205], v211 offset:38912
	ds_read_b128 v[214:217], v211 offset:39936
	global_load_lds_dwordx4 v[226:227], off
	v_lshl_add_u64 v[226:227], s[36:37], 0, v[182:183]
	s_mov_b32 m0, s41
	s_nop 0
	global_load_lds_dwordx4 v[226:227], off
	s_waitcnt vmcnt(8)
	s_waitcnt lgkmcnt(0)
	s_barrier
	s_setprio 1
	s_waitcnt lgkmcnt(0)
	v_mfma_f32_16x16x32_bf16 v[124:127], v[128:131], v[160:163], v[124:127]
	v_mfma_f32_16x16x32_bf16 v[120:123], v[136:139], v[160:163], v[120:123]
	v_mfma_f32_16x16x32_bf16 v[108:111], v[128:131], v[168:171], v[108:111]
	v_mfma_f32_16x16x32_bf16 v[104:107], v[136:139], v[168:171], v[104:107]
	v_mfma_f32_16x16x32_bf16 v[92:95], v[128:131], v[194:197], v[92:95]
	v_mfma_f32_16x16x32_bf16 v[88:91], v[136:139], v[194:197], v[88:91]
	v_mfma_f32_16x16x32_bf16 v[76:79], v[128:131], v[202:205], v[76:79]
	v_mfma_f32_16x16x32_bf16 v[72:75], v[136:139], v[202:205], v[72:75]
	v_mfma_f32_16x16x32_bf16 v[124:127], v[132:135], v[164:167], v[124:127]
	v_mfma_f32_16x16x32_bf16 v[120:123], v[140:143], v[164:167], v[120:123]
	v_mfma_f32_16x16x32_bf16 v[108:111], v[132:135], v[172:175], v[108:111]
	v_mfma_f32_16x16x32_bf16 v[104:107], v[140:143], v[172:175], v[104:107]
	v_mfma_f32_16x16x32_bf16 v[92:95], v[132:135], v[198:201], v[92:95]
	v_mfma_f32_16x16x32_bf16 v[88:91], v[140:143], v[198:201], v[88:91]
	v_mfma_f32_16x16x32_bf16 v[76:79], v[132:135], v[214:217], v[76:79]
	v_mfma_f32_16x16x32_bf16 v[72:75], v[140:143], v[214:217], v[72:75]
	v_mfma_f32_16x16x32_bf16 v[116:119], v[144:147], v[160:163], v[116:119]
	v_mfma_f32_16x16x32_bf16 v[112:115], v[152:155], v[160:163], v[112:115]
	v_mfma_f32_16x16x32_bf16 v[100:103], v[144:147], v[168:171], v[100:103]
	v_mfma_f32_16x16x32_bf16 v[96:99], v[152:155], v[168:171], v[96:99]
	v_mfma_f32_16x16x32_bf16 v[84:87], v[144:147], v[194:197], v[84:87]
	v_mfma_f32_16x16x32_bf16 v[80:83], v[152:155], v[194:197], v[80:83]
	v_mfma_f32_16x16x32_bf16 v[68:71], v[144:147], v[202:205], v[68:71]
	v_mfma_f32_16x16x32_bf16 v[64:67], v[152:155], v[202:205], v[64:67]
	v_mfma_f32_16x16x32_bf16 v[116:119], v[148:151], v[164:167], v[116:119]
	v_mfma_f32_16x16x32_bf16 v[112:115], v[156:159], v[164:167], v[112:115]
	v_mfma_f32_16x16x32_bf16 v[100:103], v[148:151], v[172:175], v[100:103]
	v_mfma_f32_16x16x32_bf16 v[96:99], v[156:159], v[172:175], v[96:99]
	v_mfma_f32_16x16x32_bf16 v[84:87], v[148:151], v[198:201], v[84:87]
	v_mfma_f32_16x16x32_bf16 v[80:83], v[156:159], v[198:201], v[80:83]
	v_mfma_f32_16x16x32_bf16 v[68:71], v[148:151], v[214:217], v[68:71]
	v_mfma_f32_16x16x32_bf16 v[64:67], v[156:159], v[214:217], v[64:67]
	s_setprio 0
	s_barrier
; #define PG8_STAGE(bufoff, gbase, voff) do { _Pragma("unroll") for (int _i = 0; _i < 2; ++_i) \
;         __builtin_amdgcn_global_load_lds((const unsigned*)((const char*)(gbase) + (voff)[_i]), (LAS unsigned*)(lds + (bufoff) + ldsw + _i * 8192), 16, 0, 0); } while (0)
; #define PG8_LDA(dst, b, h) do { _Pragma("unroll") for (int m = 0; m < 4; ++m) _Pragma("unroll") for (int k = 0; k < 2; ++k) dst[m][k] = *(const LAS bf16x8*)(lds + PG8_SA(b, h) + aoff + m * 2048 + k * 1024); } while (0)
; #define PG8_MMA(ai, bj, At, Bt) do { __builtin_amdgcn_s_setprio(1); _Pragma("unroll") for (int m = 0; m < 4; ++m) _Pragma("unroll") for (int n = 0; n < 2; ++n) _Pragma("unroll") for (int k = 0; k < 2; ++k) \
;         acc[ai][bj][m][n] = __builtin_amdgcn_mfma_f32_16x16x32_bf16(Bt[n][k], At[m][k], acc[ai][bj][m][n], 0, 0, 0); __builtin_amdgcn_s_setprio(0); } while (0)
; #define PG8_WAIT_V(n) asm volatile("s_waitcnt vmcnt(" #n ")" ::: "memory")
; #define PG8_WAIT_L(n) asm volatile("s_waitcnt lgkmcnt(" #n ")" ::: "memory")
; #define PG8_BAR __builtin_amdgcn_s_barrier()
; #define PG8_SCHED __builtin_amdgcn_sched_barrier(0)
; template <class Epi>
; __device__ __forceinline__ void gemm_phase(LAS unsigned char* lds, const Gemm g, const Order& S, const Epi& E) {
;     ...
;             PG8_LDA(At, 1, 1); PG8_STAGE(PG8_SB(1, 0), b3, voffB); PG8_STAGE(PG8_SB(1, 1), b3 + hstepB, voffB); PG8_STAGE(PG8_SA(1, 0), a3, voffA);
;             PG8_WAIT_V(8); PG8_WAIT_L(0); PG8_BAR; PG8_MMA(1, 0, At, B0); PG8_MMA(1, 1, At, B1); PG8_BAR; PG8_SCHED;
;         }
;         if (wr == 0) PG8_BAR;
	s_add_i32 s36, s56, s33
	v_lshl_add_u64 v[218:219], v[218:219], 0, s[12:13]
	s_mov_b32 m0, s36
	ds_read_b128 v[160:163], v211 offset:49152
	ds_read_b128 v[164:167], v211 offset:50176
	ds_read_b128 v[168:171], v211 offset:51200
	ds_read_b128 v[172:175], v211 offset:52224
	ds_read_b128 v[194:197], v211 offset:53248
	ds_read_b128 v[198:201], v211 offset:54272
	ds_read_b128 v[202:205], v211 offset:55296
	ds_read_b128 v[214:217], v211 offset:56320
	global_load_lds_dwordx4 v[218:219], off
	s_add_i32 m0, s36, 0x2000
	s_add_u32 s34, s34, 0x80080
	v_lshl_add_u64 v[218:219], v[220:221], 0, s[12:13]
	s_addc_u32 s35, s35, 0
	s_add_i32 s36, s57, s33
	global_load_lds_dwordx4 v[218:219], off
	v_lshl_add_u64 v[218:219], s[34:35], 0, v[180:181]
	s_mov_b32 m0, s36
	s_nop 0
	global_load_lds_dwordx4 v[218:219], off
	v_lshl_add_u64 v[218:219], s[34:35], 0, v[184:185]
	s_add_i32 m0, s36, 0x2000
	s_nop 0
	global_load_lds_dwordx4 v[218:219], off
	v_lshl_add_u64 v[218:219], v[222:223], 0, s[12:13]
	s_mov_b32 m0, s43
	s_nop 0
	global_load_lds_dwordx4 v[218:219], off
	v_lshl_add_u64 v[218:219], v[224:225], 0, s[12:13]
	s_mov_b32 m0, s46
	s_nop 0
	global_load_lds_dwordx4 v[218:219], off
	s_waitcnt vmcnt(8)
	s_waitcnt lgkmcnt(0)
	s_barrier
	s_setprio 1
	s_waitcnt lgkmcnt(0)
	v_mfma_f32_16x16x32_bf16 v[60:63], v[128:131], v[160:163], v[60:63]
	v_mfma_f32_16x16x32_bf16 v[56:59], v[136:139], v[160:163], v[56:59]
	v_mfma_f32_16x16x32_bf16 v[44:47], v[128:131], v[168:171], v[44:47]
	v_mfma_f32_16x16x32_bf16 v[40:43], v[136:139], v[168:171], v[40:43]
	v_mfma_f32_16x16x32_bf16 v[28:31], v[128:131], v[194:197], v[28:31]
	v_mfma_f32_16x16x32_bf16 v[24:27], v[136:139], v[194:197], v[24:27]
	v_mfma_f32_16x16x32_bf16 v[12:15], v[128:131], v[202:205], v[12:15]
	v_mfma_f32_16x16x32_bf16 v[8:11], v[136:139], v[202:205], v[8:11]
	v_mfma_f32_16x16x32_bf16 v[60:63], v[132:135], v[164:167], v[60:63]
	v_mfma_f32_16x16x32_bf16 v[56:59], v[140:143], v[164:167], v[56:59]
	v_mfma_f32_16x16x32_bf16 v[44:47], v[132:135], v[172:175], v[44:47]
	v_mfma_f32_16x16x32_bf16 v[40:43], v[140:143], v[172:175], v[40:43]
	v_mfma_f32_16x16x32_bf16 v[28:31], v[132:135], v[198:201], v[28:31]
	v_mfma_f32_16x16x32_bf16 v[24:27], v[140:143], v[198:201], v[24:27]
	v_mfma_f32_16x16x32_bf16 v[12:15], v[132:135], v[214:217], v[12:15]
	v_mfma_f32_16x16x32_bf16 v[8:11], v[140:143], v[214:217], v[8:11]
	v_mfma_f32_16x16x32_bf16 v[52:55], v[144:147], v[160:163], v[52:55]
	v_mfma_f32_16x16x32_bf16 v[48:51], v[152:155], v[160:163], v[48:51]
	v_mfma_f32_16x16x32_bf16 v[36:39], v[144:147], v[168:171], v[36:39]
	v_mfma_f32_16x16x32_bf16 v[32:35], v[152:155], v[168:171], v[32:35]
	v_mfma_f32_16x16x32_bf16 v[20:23], v[144:147], v[194:197], v[20:23]
	v_mfma_f32_16x16x32_bf16 v[16:19], v[152:155], v[194:197], v[16:19]
	v_mfma_f32_16x16x32_bf16 v[4:7], v[144:147], v[202:205], v[4:7]
	v_mfma_f32_16x16x32_bf16 v[0:3], v[152:155], v[202:205], v[0:3]
	v_mfma_f32_16x16x32_bf16 v[52:55], v[148:151], v[164:167], v[52:55]
	v_mfma_f32_16x16x32_bf16 v[48:51], v[156:159], v[164:167], v[48:51]
	v_mfma_f32_16x16x32_bf16 v[36:39], v[148:151], v[172:175], v[36:39]
	v_mfma_f32_16x16x32_bf16 v[32:35], v[156:159], v[172:175], v[32:35]
	v_mfma_f32_16x16x32_bf16 v[20:23], v[148:151], v[198:201], v[20:23]
	v_mfma_f32_16x16x32_bf16 v[16:19], v[156:159], v[198:201], v[16:19]
	v_mfma_f32_16x16x32_bf16 v[4:7], v[148:151], v[214:217], v[4:7]
	v_mfma_f32_16x16x32_bf16 v[0:3], v[156:159], v[214:217], v[0:3]
	s_setprio 0
	s_barrier
	s_add_i32 s55, s55, 2
	s_add_u32 s30, s30, 0x100
	s_addc_u32 s31, s31, 0
	s_add_u32 s53, s53, 0x100
	s_addc_u32 s54, s54, 0
	s_cmp_gt_u32 s55, 29
	s_cbranch_scc0 .LBB0_539
	s_and_b64 vcc, exec, s[14:15]
	s_cbranch_vccz .LBB0_542
	s_barrier

; #define PG8_STAGE(bufoff, gbase, voff) do { _Pragma("unroll") for (int _i = 0; _i < 2; ++_i) \
;         __builtin_amdgcn_global_load_lds((const unsigned*)((const char*)(gbase) + (voff)[_i]), (LAS unsigned*)(lds + (bufoff) + ldsw + _i * 8192), 16, 0, 0); } while (0)
; #define PG8_LDA(dst, b, h) do { _Pragma("unroll") for (int m = 0; m < 4; ++m) _Pragma("unroll") for (int k = 0; k < 2; ++k) dst[m][k] = *(const LAS bf16x8*)(lds + PG8_SA(b, h) + aoff + m * 2048 + k * 1024); } while (0)
; #define PG8_LDB(dst, b, h) do { _Pragma("unroll") for (int n = 0; n < 2; ++n) _Pragma("unroll") for (int k = 0; k < 2; ++k) dst[n][k] = *(const LAS bf16x8*)(lds + PG8_SB(b, h) + boff + n * 2048 + k * 1024); } while (0)
; #define PG8_MMA(ai, bj, At, Bt) do { __builtin_amdgcn_s_setprio(1); _Pragma("unroll") for (int m = 0; m < 4; ++m) _Pragma("unroll") for (int n = 0; n < 2; ++n) _Pragma("unroll") for (int k = 0; k < 2; ++k) \
;         acc[ai][bj][m][n] = __builtin_amdgcn_mfma_f32_16x16x32_bf16(Bt[n][k], At[m][k], acc[ai][bj][m][n], 0, 0, 0); __builtin_amdgcn_s_setprio(0); } while (0)
; #define PG8_WAIT_V(n) asm volatile("s_waitcnt vmcnt(" #n ")" ::: "memory")
; #define PG8_WAIT_L(n) asm volatile("s_waitcnt lgkmcnt(" #n ")" ::: "memory")
; #define PG8_BAR __builtin_amdgcn_s_barrier()
; #define PG8_SCHED __builtin_amdgcn_sched_barrier(0)
; template <class Epi>
; __device__ __forceinline__ void gemm_phase(LAS unsigned char* lds, const Gemm g, const Order& S, const Epi& E) {
;     ...
;         for (int t = 0; t < nt; t += 2) {
;             const bool last = (t == nt - 2);
;             const char* a1 = cA + (size_t)(t + 1) * kstep;
;             const char* a2 = last ? nA : cA + (size_t)(t + 2) * kstep; const char* b2 = last ? nB : cB + (size_t)(t + 2) * kstep;
;             const char* a3 = a2 + kstep; const char* b3 = b2 + kstep;
;             PG8_LDB(B0, 0, 0); PG8_LDB(B1, 0, 1); PG8_SCHED; PG8_LDA(At, 0, 0); PG8_STAGE(PG8_SA(1, 1), a1 + hstepA, voffA);
;             PG8_WAIT_V(8); PG8_WAIT_L(0); PG8_BAR; PG8_MMA(0, 0, At, B0); PG8_MMA(0, 1, At, B1); PG8_BAR; PG8_SCHED;
;             PG8_LDA(At, 0, 1); PG8_STAGE(PG8_SB(0, 0), b2, voffB); PG8_STAGE(PG8_SB(0, 1), b2 + hstepB, voffB); PG8_STAGE(PG8_SA(0, 0), a2, voffA);
.LBB0_661:
	ds_read_b128 v[144:147], v181
	ds_read_b128 v[148:151], v181 offset:1024
	ds_read_b128 v[152:155], v181 offset:2048
	ds_read_b128 v[188:191], v181 offset:3072
	ds_read_b128 v[192:195], v182
	ds_read_b128 v[196:199], v182 offset:1024
	ds_read_b128 v[200:203], v182 offset:2048
	ds_read_b128 v[208:211], v182 offset:3072
	s_add_u32 s42, s40, 0xfff80080
	s_addc_u32 s43, s41, -1
	s_cmp_eq_u32 s81, 28
	s_cselect_b32 s47, s0, s43
	s_cselect_b32 s46, s1, s42
	s_cselect_b32 s43, s2, s39
	s_cselect_b32 s42, s27, s33
	v_lshl_add_u64 v[156:157], s[40:41], 0, v[136:137]
	s_add_i32 m0, s52, 0xc000
	ds_read_b128 v[212:215], v183
	ds_read_b128 v[216:219], v183 offset:1024
	ds_read_b128 v[220:223], v183 offset:2048
	ds_read_b128 v[224:227], v183 offset:3072
	ds_read_b128 v[228:231], v183 offset:4096
	ds_read_b128 v[232:235], v183 offset:5120
	ds_read_b128 v[236:239], v183 offset:6144
	ds_read_b128 v[240:243], v183 offset:7168
	global_load_lds_dwordx4 v[156:157], off
	v_lshl_add_u64 v[156:157], s[40:41], 0, v[138:139]
	s_add_i32 m0, s52, 0xe000
	s_nop 0
	global_load_lds_dwordx4 v[156:157], off
	s_waitcnt vmcnt(8)
	s_waitcnt lgkmcnt(0)
	s_barrier
	s_setprio 1
	s_waitcnt lgkmcnt(0)
	v_mfma_f32_16x16x32_bf16 v[124:127], v[144:147], v[212:215], v[124:127]
	v_mfma_f32_16x16x32_bf16 v[120:123], v[152:155], v[212:215], v[120:123]
	v_mfma_f32_16x16x32_bf16 v[108:111], v[144:147], v[220:223], v[108:111]
	v_mfma_f32_16x16x32_bf16 v[104:107], v[152:155], v[220:223], v[104:107]
	v_mfma_f32_16x16x32_bf16 v[92:95], v[144:147], v[228:231], v[92:95]
	v_mfma_f32_16x16x32_bf16 v[88:91], v[152:155], v[228:231], v[88:91]
	v_mfma_f32_16x16x32_bf16 v[76:79], v[144:147], v[236:239], v[76:79]
	v_mfma_f32_16x16x32_bf16 v[72:75], v[152:155], v[236:239], v[72:75]
	v_mfma_f32_16x16x32_bf16 v[124:127], v[148:151], v[216:219], v[124:127]
	v_mfma_f32_16x16x32_bf16 v[120:123], v[188:191], v[216:219], v[120:123]
	v_mfma_f32_16x16x32_bf16 v[108:111], v[148:151], v[224:227], v[108:111]
	v_mfma_f32_16x16x32_bf16 v[104:107], v[188:191], v[224:227], v[104:107]
	v_mfma_f32_16x16x32_bf16 v[92:95], v[148:151], v[232:235], v[92:95]
	v_mfma_f32_16x16x32_bf16 v[88:91], v[188:191], v[232:235], v[88:91]
	v_mfma_f32_16x16x32_bf16 v[76:79], v[148:151], v[240:243], v[76:79]
	v_mfma_f32_16x16x32_bf16 v[72:75], v[188:191], v[240:243], v[72:75]
	v_mfma_f32_16x16x32_bf16 v[116:119], v[192:195], v[212:215], v[116:119]
	v_mfma_f32_16x16x32_bf16 v[112:115], v[200:203], v[212:215], v[112:115]
	v_mfma_f32_16x16x32_bf16 v[100:103], v[192:195], v[220:223], v[100:103]
	v_mfma_f32_16x16x32_bf16 v[96:99], v[200:203], v[220:223], v[96:99]
	v_mfma_f32_16x16x32_bf16 v[84:87], v[192:195], v[228:231], v[84:87]
	v_mfma_f32_16x16x32_bf16 v[80:83], v[200:203], v[228:231], v[80:83]
	v_mfma_f32_16x16x32_bf16 v[68:71], v[192:195], v[236:239], v[68:71]
	v_mfma_f32_16x16x32_bf16 v[64:67], v[200:203], v[236:239], v[64:67]
	v_mfma_f32_16x16x32_bf16 v[116:119], v[196:199], v[216:219], v[116:119]
	v_mfma_f32_16x16x32_bf16 v[112:115], v[208:211], v[216:219], v[112:115]
	v_mfma_f32_16x16x32_bf16 v[100:103], v[196:199], v[224:227], v[100:103]
	v_mfma_f32_16x16x32_bf16 v[96:99], v[208:211], v[224:227], v[96:99]
	v_mfma_f32_16x16x32_bf16 v[84:87], v[196:199], v[232:235], v[84:87]
	v_mfma_f32_16x16x32_bf16 v[80:83], v[208:211], v[232:235], v[80:83]
	v_mfma_f32_16x16x32_bf16 v[68:71], v[196:199], v[240:243], v[68:71]
	v_mfma_f32_16x16x32_bf16 v[64:67], v[208:211], v[240:243], v[64:67]
	s_setprio 0
	s_barrier
	s_add_i32 s82, s61, s51
	v_lshl_add_u64 v[156:157], s[42:43], 0, v[130:131]
	s_mov_b32 m0, s82
	ds_read_b128 v[212:215], v183 offset:16384
	ds_read_b128 v[216:219], v183 offset:17408
	ds_read_b128 v[220:223], v183 offset:18432
	ds_read_b128 v[224:227], v183 offset:19456
	ds_read_b128 v[228:231], v183 offset:20480
	ds_read_b128 v[232:235], v183 offset:21504
	ds_read_b128 v[236:239], v183 offset:22528
	ds_read_b128 v[240:243], v183 offset:23552
	global_load_lds_dwordx4 v[156:157], off
	s_add_i32 m0, s82, 0x2000
	s_add_u32 s82, s42, 0x80000
	v_lshl_add_u64 v[204:205], s[42:43], 0, v[134:135]
	s_addc_u32 s83, s43, 0
	s_add_i32 s84, s62, s51
	global_load_lds_dwordx4 v[204:205], off
	v_lshl_add_u64 v[244:245], s[82:83], 0, v[130:131]
	s_mov_b32 m0, s84
	v_lshl_add_u64 v[246:247], s[46:47], 0, v[132:133]
	global_load_lds_dwordx4 v[244:245], off
	v_lshl_add_u64 v[244:245], s[82:83], 0, v[134:135]
	s_add_i32 m0, s84, 0x2000
	s_nop 0
	global_load_lds_dwordx4 v[244:245], off
	v_lshl_add_u64 v[244:245], s[46:47], 0, v[128:129]
	s_mov_b32 m0, s52
	s_nop 0
	global_load_lds_dwordx4 v[244:245], off
	s_mov_b32 m0, s53
	s_nop 0
	global_load_lds_dwordx4 v[246:247], off
	s_waitcnt vmcnt(8)
	s_waitcnt lgkmcnt(0)
	s_barrier
; #define PG8_STAGE(bufoff, gbase, voff) do { _Pragma("unroll") for (int _i = 0; _i < 2; ++_i) \
;         __builtin_amdgcn_global_load_lds((const unsigned*)((const char*)(gbase) + (voff)[_i]), (LAS unsigned*)(lds + (bufoff) + ldsw + _i * 8192), 16, 0, 0); } while (0)
; #define PG8_LDA(dst, b, h) do { _Pragma("unroll") for (int m = 0; m < 4; ++m) _Pragma("unroll") for (int k = 0; k < 2; ++k) dst[m][k] = *(const LAS bf16x8*)(lds + PG8_SA(b, h) + aoff + m * 2048 + k * 1024); } while (0)
; #define PG8_LDB(dst, b, h) do { _Pragma("unroll") for (int n = 0; n < 2; ++n) _Pragma("unroll") for (int k = 0; k < 2; ++k) dst[n][k] = *(const LAS bf16x8*)(lds + PG8_SB(b, h) + boff + n * 2048 + k * 1024); } while (0)
; #define PG8_MMA(ai, bj, At, Bt) do { __builtin_amdgcn_s_setprio(1); _Pragma("unroll") for (int m = 0; m < 4; ++m) _Pragma("unroll") for (int n = 0; n < 2; ++n) _Pragma("unroll") for (int k = 0; k < 2; ++k) \
;         acc[ai][bj][m][n] = __builtin_amdgcn_mfma_f32_16x16x32_bf16(Bt[n][k], At[m][k], acc[ai][bj][m][n], 0, 0, 0); __builtin_amdgcn_s_setprio(0); } while (0)
; #define PG8_WAIT_V(n) asm volatile("s_waitcnt vmcnt(" #n ")" ::: "memory")
; #define PG8_WAIT_L(n) asm volatile("s_waitcnt lgkmcnt(" #n ")" ::: "memory")
; #define PG8_BAR __builtin_amdgcn_s_barrier()
; #define PG8_SCHED __builtin_amdgcn_sched_barrier(0)
; template <class Epi>
; __device__ __forceinline__ void gemm_phase(LAS unsigned char* lds, const Gemm g, const Order& S, const Epi& E) {
;     ...
;             PG8_WAIT_V(8); PG8_WAIT_L(0); PG8_BAR; PG8_MMA(1, 0, At, B0); PG8_MMA(1, 1, At, B1); PG8_BAR; PG8_SCHED;
;             PG8_LDB(B0, 1, 0); PG8_LDB(B1, 1, 1); PG8_SCHED; PG8_LDA(At, 1, 0); PG8_STAGE(PG8_SA(0, 1), a2 + hstepA, voffA);
;             PG8_WAIT_V(8); PG8_WAIT_L(0); PG8_BAR; PG8_MMA(0, 0, At, B0); PG8_MMA(0, 1, At, B1); PG8_BAR; PG8_SCHED;
	s_setprio 1
	s_waitcnt lgkmcnt(0)
	v_mfma_f32_16x16x32_bf16 v[60:63], v[144:147], v[212:215], v[60:63]
	v_mfma_f32_16x16x32_bf16 v[56:59], v[152:155], v[212:215], v[56:59]
	v_mfma_f32_16x16x32_bf16 v[44:47], v[144:147], v[220:223], v[44:47]
	v_mfma_f32_16x16x32_bf16 v[40:43], v[152:155], v[220:223], v[40:43]
	v_mfma_f32_16x16x32_bf16 v[28:31], v[144:147], v[228:231], v[28:31]
	v_mfma_f32_16x16x32_bf16 v[24:27], v[152:155], v[228:231], v[24:27]
	v_mfma_f32_16x16x32_bf16 v[12:15], v[144:147], v[236:239], v[12:15]
	v_mfma_f32_16x16x32_bf16 v[8:11], v[152:155], v[236:239], v[8:11]
	v_mfma_f32_16x16x32_bf16 v[60:63], v[148:151], v[216:219], v[60:63]
	v_mfma_f32_16x16x32_bf16 v[56:59], v[188:191], v[216:219], v[56:59]
	v_mfma_f32_16x16x32_bf16 v[44:47], v[148:151], v[224:227], v[44:47]
	v_mfma_f32_16x16x32_bf16 v[40:43], v[188:191], v[224:227], v[40:43]
	v_mfma_f32_16x16x32_bf16 v[28:31], v[148:151], v[232:235], v[28:31]
	v_mfma_f32_16x16x32_bf16 v[24:27], v[188:191], v[232:235], v[24:27]
	v_mfma_f32_16x16x32_bf16 v[12:15], v[148:151], v[240:243], v[12:15]
	v_mfma_f32_16x16x32_bf16 v[8:11], v[188:191], v[240:243], v[8:11]
	v_mfma_f32_16x16x32_bf16 v[52:55], v[192:195], v[212:215], v[52:55]
	v_mfma_f32_16x16x32_bf16 v[48:51], v[200:203], v[212:215], v[48:51]
	v_mfma_f32_16x16x32_bf16 v[36:39], v[192:195], v[220:223], v[36:39]
	v_mfma_f32_16x16x32_bf16 v[32:35], v[200:203], v[220:223], v[32:35]
	v_mfma_f32_16x16x32_bf16 v[20:23], v[192:195], v[228:231], v[20:23]
	v_mfma_f32_16x16x32_bf16 v[16:19], v[200:203], v[228:231], v[16:19]
	v_mfma_f32_16x16x32_bf16 v[4:7], v[192:195], v[236:239], v[4:7]
	v_mfma_f32_16x16x32_bf16 v[0:3], v[200:203], v[236:239], v[0:3]
	v_mfma_f32_16x16x32_bf16 v[52:55], v[196:199], v[216:219], v[52:55]
	v_mfma_f32_16x16x32_bf16 v[48:51], v[208:211], v[216:219], v[48:51]
	v_mfma_f32_16x16x32_bf16 v[36:39], v[196:199], v[224:227], v[36:39]
	v_mfma_f32_16x16x32_bf16 v[32:35], v[208:211], v[224:227], v[32:35]
	v_mfma_f32_16x16x32_bf16 v[20:23], v[196:199], v[232:235], v[20:23]
	v_mfma_f32_16x16x32_bf16 v[16:19], v[208:211], v[232:235], v[16:19]
	v_mfma_f32_16x16x32_bf16 v[4:7], v[196:199], v[240:243], v[4:7]
	v_mfma_f32_16x16x32_bf16 v[0:3], v[208:211], v[240:243], v[0:3]
	s_setprio 0
	s_barrier
	s_add_i32 s82, 0, 0x18000
	s_add_i32 s83, 0, 0x1c000
	v_add_u32_e32 v188, s82, v159
	v_add_u32_e32 v207, s83, v159
	ds_read_b128 v[144:147], v188
	ds_read_b128 v[148:151], v188 offset:1024
	ds_read_b128 v[152:155], v188 offset:2048
	ds_read_b128 v[188:191], v188 offset:3072
	ds_read_b128 v[192:195], v207
	ds_read_b128 v[196:199], v207 offset:1024
	ds_read_b128 v[200:203], v207 offset:2048
	ds_read_b128 v[208:211], v207 offset:3072
	s_add_u32 s46, s46, 0x80000
	s_addc_u32 s47, s47, 0
	s_mov_b32 m0, s54
	v_lshl_add_u64 v[248:249], s[46:47], 0, v[128:129]
	ds_read_b128 v[212:215], v183 offset:32768
	ds_read_b128 v[216:219], v183 offset:33792
	ds_read_b128 v[220:223], v183 offset:34816
	ds_read_b128 v[224:227], v183 offset:35840
	ds_read_b128 v[228:231], v183 offset:36864
	ds_read_b128 v[232:235], v183 offset:37888
	ds_read_b128 v[236:239], v183 offset:38912
	ds_read_b128 v[240:243], v183 offset:39936
	global_load_lds_dwordx4 v[248:249], off
	v_lshl_add_u64 v[248:249], s[46:47], 0, v[132:133]
	s_mov_b32 m0, s55
	s_nop 0
	global_load_lds_dwordx4 v[248:249], off
	s_waitcnt vmcnt(8)
	s_waitcnt lgkmcnt(0)
	s_barrier
	s_setprio 1
	s_waitcnt lgkmcnt(0)
	v_mfma_f32_16x16x32_bf16 v[124:127], v[144:147], v[212:215], v[124:127]
	v_mfma_f32_16x16x32_bf16 v[120:123], v[152:155], v[212:215], v[120:123]
	v_mfma_f32_16x16x32_bf16 v[108:111], v[144:147], v[220:223], v[108:111]
	v_mfma_f32_16x16x32_bf16 v[104:107], v[152:155], v[220:223], v[104:107]
	v_mfma_f32_16x16x32_bf16 v[92:95], v[144:147], v[228:231], v[92:95]
	v_mfma_f32_16x16x32_bf16 v[88:91], v[152:155], v[228:231], v[88:91]
	v_mfma_f32_16x16x32_bf16 v[76:79], v[144:147], v[236:239], v[76:79]
	v_mfma_f32_16x16x32_bf16 v[72:75], v[152:155], v[236:239], v[72:75]
	v_mfma_f32_16x16x32_bf16 v[124:127], v[148:151], v[216:219], v[124:127]
	v_mfma_f32_16x16x32_bf16 v[120:123], v[188:191], v[216:219], v[120:123]
	v_mfma_f32_16x16x32_bf16 v[108:111], v[148:151], v[224:227], v[108:111]
	v_mfma_f32_16x16x32_bf16 v[104:107], v[188:191], v[224:227], v[104:107]
	v_mfma_f32_16x16x32_bf16 v[92:95], v[148:151], v[232:235], v[92:95]
	v_mfma_f32_16x16x32_bf16 v[88:91], v[188:191], v[232:235], v[88:91]
	v_mfma_f32_16x16x32_bf16 v[76:79], v[148:151], v[240:243], v[76:79]
	v_mfma_f32_16x16x32_bf16 v[72:75], v[188:191], v[240:243], v[72:75]
	v_mfma_f32_16x16x32_bf16 v[116:119], v[192:195], v[212:215], v[116:119]
	v_mfma_f32_16x16x32_bf16 v[112:115], v[200:203], v[212:215], v[112:115]
	v_mfma_f32_16x16x32_bf16 v[100:103], v[192:195], v[220:223], v[100:103]
	v_mfma_f32_16x16x32_bf16 v[96:99], v[200:203], v[220:223], v[96:99]
	v_mfma_f32_16x16x32_bf16 v[84:87], v[192:195], v[228:231], v[84:87]
	v_mfma_f32_16x16x32_bf16 v[80:83], v[200:203], v[228:231], v[80:83]
	v_mfma_f32_16x16x32_bf16 v[68:71], v[192:195], v[236:239], v[68:71]
	v_mfma_f32_16x16x32_bf16 v[64:67], v[200:203], v[236:239], v[64:67]
	v_mfma_f32_16x16x32_bf16 v[116:119], v[196:199], v[216:219], v[116:119]
	v_mfma_f32_16x16x32_bf16 v[112:115], v[208:211], v[216:219], v[112:115]
	v_mfma_f32_16x16x32_bf16 v[100:103], v[196:199], v[224:227], v[100:103]
	v_mfma_f32_16x16x32_bf16 v[96:99], v[208:211], v[224:227], v[96:99]
	v_mfma_f32_16x16x32_bf16 v[84:87], v[196:199], v[232:235], v[84:87]
	v_mfma_f32_16x16x32_bf16 v[80:83], v[208:211], v[232:235], v[80:83]
	v_mfma_f32_16x16x32_bf16 v[68:71], v[196:199], v[240:243], v[68:71]
	v_mfma_f32_16x16x32_bf16 v[64:67], v[208:211], v[240:243], v[64:67]
	s_setprio 0
	s_barrier
; #define PG8_STAGE(bufoff, gbase, voff) do { _Pragma("unroll") for (int _i = 0; _i < 2; ++_i) \
;         __builtin_amdgcn_global_load_lds((const unsigned*)((const char*)(gbase) + (voff)[_i]), (LAS unsigned*)(lds + (bufoff) + ldsw + _i * 8192), 16, 0, 0); } while (0)
; #define PG8_LDA(dst, b, h) do { _Pragma("unroll") for (int m = 0; m < 4; ++m) _Pragma("unroll") for (int k = 0; k < 2; ++k) dst[m][k] = *(const LAS bf16x8*)(lds + PG8_SA(b, h) + aoff + m * 2048 + k * 1024); } while (0)
; #define PG8_MMA(ai, bj, At, Bt) do { __builtin_amdgcn_s_setprio(1); _Pragma("unroll") for (int m = 0; m < 4; ++m) _Pragma("unroll") for (int n = 0; n < 2; ++n) _Pragma("unroll") for (int k = 0; k < 2; ++k) \
;         acc[ai][bj][m][n] = __builtin_amdgcn_mfma_f32_16x16x32_bf16(Bt[n][k], At[m][k], acc[ai][bj][m][n], 0, 0, 0); __builtin_amdgcn_s_setprio(0); } while (0)
; #define PG8_WAIT_V(n) asm volatile("s_waitcnt vmcnt(" #n ")" ::: "memory")
; #define PG8_WAIT_L(n) asm volatile("s_waitcnt lgkmcnt(" #n ")" ::: "memory")
; #define PG8_BAR __builtin_amdgcn_s_barrier()
; #define PG8_SCHED __builtin_amdgcn_sched_barrier(0)
; template <class Epi>
; __device__ __forceinline__ void gemm_phase(LAS unsigned char* lds, const Gemm g, const Order& S, const Epi& E) {
;     ...
;             PG8_LDA(At, 1, 1); PG8_STAGE(PG8_SB(1, 0), b3, voffB); PG8_STAGE(PG8_SB(1, 1), b3 + hstepB, voffB); PG8_STAGE(PG8_SA(1, 0), a3, voffA);
;             PG8_WAIT_V(8); PG8_WAIT_L(0); PG8_BAR; PG8_MMA(1, 0, At, B0); PG8_MMA(1, 1, At, B1); PG8_BAR; PG8_SCHED;
;         }
;         if (wr == 0) PG8_BAR;
	s_add_i32 s46, s82, s51
	v_lshl_add_u64 v[156:157], v[156:157], 0, s[12:13]
	s_mov_b32 m0, s46
	ds_read_b128 v[212:215], v183 offset:49152
	ds_read_b128 v[216:219], v183 offset:50176
	ds_read_b128 v[220:223], v183 offset:51200
	ds_read_b128 v[224:227], v183 offset:52224
	ds_read_b128 v[228:231], v183 offset:53248
	ds_read_b128 v[232:235], v183 offset:54272
	ds_read_b128 v[236:239], v183 offset:55296
	ds_read_b128 v[240:243], v183 offset:56320
	global_load_lds_dwordx4 v[156:157], off
	s_add_i32 m0, s46, 0x2000
	s_add_u32 s42, s42, 0x80080
	v_lshl_add_u64 v[156:157], v[204:205], 0, s[12:13]
	s_addc_u32 s43, s43, 0
	s_add_i32 s46, s83, s51
	global_load_lds_dwordx4 v[156:157], off
	v_lshl_add_u64 v[156:157], s[42:43], 0, v[130:131]
	s_mov_b32 m0, s46
	s_nop 0
	global_load_lds_dwordx4 v[156:157], off
	v_lshl_add_u64 v[156:157], s[42:43], 0, v[134:135]
	s_add_i32 m0, s46, 0x2000
	s_nop 0
	global_load_lds_dwordx4 v[156:157], off
	v_lshl_add_u64 v[156:157], v[244:245], 0, s[12:13]
	s_mov_b32 m0, s57
	s_nop 0
	global_load_lds_dwordx4 v[156:157], off
	v_lshl_add_u64 v[156:157], v[246:247], 0, s[12:13]
	s_mov_b32 m0, s58
	s_nop 0
	global_load_lds_dwordx4 v[156:157], off
	s_waitcnt vmcnt(8)
	s_waitcnt lgkmcnt(0)
	s_barrier
	s_setprio 1
	s_waitcnt lgkmcnt(0)
	v_mfma_f32_16x16x32_bf16 v[60:63], v[144:147], v[212:215], v[60:63]
	v_mfma_f32_16x16x32_bf16 v[56:59], v[152:155], v[212:215], v[56:59]
	v_mfma_f32_16x16x32_bf16 v[44:47], v[144:147], v[220:223], v[44:47]
	v_mfma_f32_16x16x32_bf16 v[40:43], v[152:155], v[220:223], v[40:43]
	v_mfma_f32_16x16x32_bf16 v[28:31], v[144:147], v[228:231], v[28:31]
	v_mfma_f32_16x16x32_bf16 v[24:27], v[152:155], v[228:231], v[24:27]
	v_mfma_f32_16x16x32_bf16 v[12:15], v[144:147], v[236:239], v[12:15]
	v_mfma_f32_16x16x32_bf16 v[8:11], v[152:155], v[236:239], v[8:11]
	v_mfma_f32_16x16x32_bf16 v[60:63], v[148:151], v[216:219], v[60:63]
	v_mfma_f32_16x16x32_bf16 v[56:59], v[188:191], v[216:219], v[56:59]
	v_mfma_f32_16x16x32_bf16 v[44:47], v[148:151], v[224:227], v[44:47]
	v_mfma_f32_16x16x32_bf16 v[40:43], v[188:191], v[224:227], v[40:43]
	v_mfma_f32_16x16x32_bf16 v[28:31], v[148:151], v[232:235], v[28:31]
	v_mfma_f32_16x16x32_bf16 v[24:27], v[188:191], v[232:235], v[24:27]
	v_mfma_f32_16x16x32_bf16 v[12:15], v[148:151], v[240:243], v[12:15]
	v_mfma_f32_16x16x32_bf16 v[8:11], v[188:191], v[240:243], v[8:11]
	v_mfma_f32_16x16x32_bf16 v[52:55], v[192:195], v[212:215], v[52:55]
	v_mfma_f32_16x16x32_bf16 v[48:51], v[200:203], v[212:215], v[48:51]
	v_mfma_f32_16x16x32_bf16 v[36:39], v[192:195], v[220:223], v[36:39]
	v_mfma_f32_16x16x32_bf16 v[32:35], v[200:203], v[220:223], v[32:35]
	v_mfma_f32_16x16x32_bf16 v[20:23], v[192:195], v[228:231], v[20:23]
	v_mfma_f32_16x16x32_bf16 v[16:19], v[200:203], v[228:231], v[16:19]
	v_mfma_f32_16x16x32_bf16 v[4:7], v[192:195], v[236:239], v[4:7]
	v_mfma_f32_16x16x32_bf16 v[0:3], v[200:203], v[236:239], v[0:3]
	v_mfma_f32_16x16x32_bf16 v[52:55], v[196:199], v[216:219], v[52:55]
	v_mfma_f32_16x16x32_bf16 v[48:51], v[208:211], v[216:219], v[48:51]
	v_mfma_f32_16x16x32_bf16 v[36:39], v[196:199], v[224:227], v[36:39]
	v_mfma_f32_16x16x32_bf16 v[32:35], v[208:211], v[224:227], v[32:35]
	v_mfma_f32_16x16x32_bf16 v[20:23], v[196:199], v[232:235], v[20:23]
	v_mfma_f32_16x16x32_bf16 v[16:19], v[208:211], v[232:235], v[16:19]
	v_mfma_f32_16x16x32_bf16 v[4:7], v[196:199], v[240:243], v[4:7]
	v_mfma_f32_16x16x32_bf16 v[0:3], v[208:211], v[240:243], v[0:3]
	s_setprio 0
	s_barrier
	s_add_i32 s81, s81, 2
	s_add_u32 s40, s40, 0x100
	s_addc_u32 s41, s41, 0
	s_add_u32 s33, s33, 0x100
	s_addc_u32 s39, s39, 0
	s_cmp_gt_u32 s81, 29
	s_cbranch_scc0 .LBB0_661
	s_and_b64 vcc, exec, s[14:15]
	s_cbranch_vccz .LBB0_664
	s_barrier

; #define PG8_STAGE(bufoff, gbase, voff) do { _Pragma("unroll") for (int _i = 0; _i < 2; ++_i) \
;         __builtin_amdgcn_global_load_lds((const unsigned*)((const char*)(gbase) + (voff)[_i]), (LAS unsigned*)(lds + (bufoff) + ldsw + _i * 8192), 16, 0, 0); } while (0)
; #define PG8_LDA(dst, b, h) do { _Pragma("unroll") for (int m = 0; m < 4; ++m) _Pragma("unroll") for (int k = 0; k < 2; ++k) dst[m][k] = *(const LAS bf16x8*)(lds + PG8_SA(b, h) + aoff + m * 2048 + k * 1024); } while (0)
; #define PG8_LDB(dst, b, h) do { _Pragma("unroll") for (int n = 0; n < 2; ++n) _Pragma("unroll") for (int k = 0; k < 2; ++k) dst[n][k] = *(const LAS bf16x8*)(lds + PG8_SB(b, h) + boff + n * 2048 + k * 1024); } while (0)
; #define PG8_MMA(ai, bj, At, Bt) do { __builtin_amdgcn_s_setprio(1); _Pragma("unroll") for (int m = 0; m < 4; ++m) _Pragma("unroll") for (int n = 0; n < 2; ++n) _Pragma("unroll") for (int k = 0; k < 2; ++k) \
;         acc[ai][bj][m][n] = __builtin_amdgcn_mfma_f32_16x16x32_bf16(Bt[n][k], At[m][k], acc[ai][bj][m][n], 0, 0, 0); __builtin_amdgcn_s_setprio(0); } while (0)
; #define PG8_WAIT_V(n) asm volatile("s_waitcnt vmcnt(" #n ")" ::: "memory")
; #define PG8_WAIT_L(n) asm volatile("s_waitcnt lgkmcnt(" #n ")" ::: "memory")
; #define PG8_BAR __builtin_amdgcn_s_barrier()
; #define PG8_SCHED __builtin_amdgcn_sched_barrier(0)
; template <class Epi>
; __device__ __forceinline__ void gemm_phase(LAS unsigned char* lds, const Gemm g, const Order& S, const Epi& E) {
;     ...
;         for (int t = 0; t < nt; t += 2) {
;             const bool last = (t == nt - 2);
;             const char* a1 = cA + (size_t)(t + 1) * kstep;
;             const char* a2 = last ? nA : cA + (size_t)(t + 2) * kstep; const char* b2 = last ? nB : cB + (size_t)(t + 2) * kstep;
;             const char* a3 = a2 + kstep; const char* b3 = b2 + kstep;
;             PG8_LDB(B0, 0, 0); PG8_LDB(B1, 0, 1); PG8_SCHED; PG8_LDA(At, 0, 0); PG8_STAGE(PG8_SA(1, 1), a1 + hstepA, voffA);
;             PG8_WAIT_V(8); PG8_WAIT_L(0); PG8_BAR; PG8_MMA(0, 0, At, B0); PG8_MMA(0, 1, At, B1); PG8_BAR; PG8_SCHED;
;             PG8_LDA(At, 0, 1); PG8_STAGE(PG8_SB(0, 0), b2, voffB); PG8_STAGE(PG8_SB(0, 1), b2 + hstepB, voffB); PG8_STAGE(PG8_SA(0, 0), a2, voffA);
.LBB0_774:
	ds_read_b128 v[128:131], v190
	ds_read_b128 v[132:135], v190 offset:1024
	ds_read_b128 v[136:139], v190 offset:2048
	ds_read_b128 v[140:143], v190 offset:3072
	ds_read_b128 v[144:147], v191
	ds_read_b128 v[148:151], v191 offset:1024
	ds_read_b128 v[168:171], v191 offset:2048
	ds_read_b128 v[172:175], v191 offset:3072
	s_add_u32 s36, s34, 0xfffc0080
	s_addc_u32 s37, s35, -1
	s_cmp_eq_u32 s59, 12
	s_cselect_b32 s39, s17, s37
	s_cselect_b32 s38, s31, s36
	s_cselect_b32 s37, s55, s58
	s_cselect_b32 s36, s56, s57
	v_lshl_add_u64 v[186:187], s[34:35], 0, v[160:161]
	s_add_i32 m0, s40, 0xc000
	ds_read_b128 v[178:181], v192
	ds_read_b128 v[182:185], v192 offset:1024
	ds_read_b128 v[194:197], v192 offset:2048
	ds_read_b128 v[198:201], v192 offset:3072
	ds_read_b128 v[202:205], v192 offset:4096
	ds_read_b128 v[208:211], v192 offset:5120
	ds_read_b128 v[212:215], v192 offset:6144
	ds_read_b128 v[216:219], v192 offset:7168
	global_load_lds_dwordx4 v[186:187], off
	v_lshl_add_u64 v[186:187], s[34:35], 0, v[162:163]
	s_add_i32 m0, s40, 0xe000
	s_nop 0
	global_load_lds_dwordx4 v[186:187], off
	s_waitcnt vmcnt(8)
	s_waitcnt lgkmcnt(0)
	s_barrier
	s_setprio 1
	s_waitcnt lgkmcnt(0)
	v_mfma_f32_16x16x32_bf16 v[124:127], v[128:131], v[178:181], v[124:127]
	v_mfma_f32_16x16x32_bf16 v[120:123], v[136:139], v[178:181], v[120:123]
	v_mfma_f32_16x16x32_bf16 v[108:111], v[128:131], v[194:197], v[108:111]
	v_mfma_f32_16x16x32_bf16 v[104:107], v[136:139], v[194:197], v[104:107]
	v_mfma_f32_16x16x32_bf16 v[92:95], v[128:131], v[202:205], v[92:95]
	v_mfma_f32_16x16x32_bf16 v[88:91], v[136:139], v[202:205], v[88:91]
	v_mfma_f32_16x16x32_bf16 v[76:79], v[128:131], v[212:215], v[76:79]
	v_mfma_f32_16x16x32_bf16 v[72:75], v[136:139], v[212:215], v[72:75]
	v_mfma_f32_16x16x32_bf16 v[124:127], v[132:135], v[182:185], v[124:127]
	v_mfma_f32_16x16x32_bf16 v[120:123], v[140:143], v[182:185], v[120:123]
	v_mfma_f32_16x16x32_bf16 v[108:111], v[132:135], v[198:201], v[108:111]
	v_mfma_f32_16x16x32_bf16 v[104:107], v[140:143], v[198:201], v[104:107]
	v_mfma_f32_16x16x32_bf16 v[92:95], v[132:135], v[208:211], v[92:95]
	v_mfma_f32_16x16x32_bf16 v[88:91], v[140:143], v[208:211], v[88:91]
	v_mfma_f32_16x16x32_bf16 v[76:79], v[132:135], v[216:219], v[76:79]
	v_mfma_f32_16x16x32_bf16 v[72:75], v[140:143], v[216:219], v[72:75]
	v_mfma_f32_16x16x32_bf16 v[116:119], v[144:147], v[178:181], v[116:119]
	v_mfma_f32_16x16x32_bf16 v[112:115], v[168:171], v[178:181], v[112:115]
	v_mfma_f32_16x16x32_bf16 v[100:103], v[144:147], v[194:197], v[100:103]
	v_mfma_f32_16x16x32_bf16 v[96:99], v[168:171], v[194:197], v[96:99]
	v_mfma_f32_16x16x32_bf16 v[84:87], v[144:147], v[202:205], v[84:87]
	v_mfma_f32_16x16x32_bf16 v[80:83], v[168:171], v[202:205], v[80:83]
	v_mfma_f32_16x16x32_bf16 v[68:71], v[144:147], v[212:215], v[68:71]
	v_mfma_f32_16x16x32_bf16 v[64:67], v[168:171], v[212:215], v[64:67]
	v_mfma_f32_16x16x32_bf16 v[116:119], v[148:151], v[182:185], v[116:119]
	v_mfma_f32_16x16x32_bf16 v[112:115], v[172:175], v[182:185], v[112:115]
	v_mfma_f32_16x16x32_bf16 v[100:103], v[148:151], v[198:201], v[100:103]
	v_mfma_f32_16x16x32_bf16 v[96:99], v[172:175], v[198:201], v[96:99]
	v_mfma_f32_16x16x32_bf16 v[84:87], v[148:151], v[208:211], v[84:87]
	v_mfma_f32_16x16x32_bf16 v[80:83], v[172:175], v[208:211], v[80:83]
	v_mfma_f32_16x16x32_bf16 v[68:71], v[148:151], v[216:219], v[68:71]
	v_mfma_f32_16x16x32_bf16 v[64:67], v[172:175], v[216:219], v[64:67]
	s_setprio 0
	s_barrier
	s_add_i32 s60, s51, s33
	v_lshl_add_u64 v[186:187], s[36:37], 0, v[154:155]
	s_mov_b32 m0, s60
	ds_read_b128 v[178:181], v192 offset:16384
	ds_read_b128 v[182:185], v192 offset:17408
	ds_read_b128 v[194:197], v192 offset:18432
	ds_read_b128 v[198:201], v192 offset:19456
	ds_read_b128 v[202:205], v192 offset:20480
	ds_read_b128 v[208:211], v192 offset:21504
	ds_read_b128 v[212:215], v192 offset:22528
	ds_read_b128 v[216:219], v192 offset:23552
	global_load_lds_dwordx4 v[186:187], off
	s_add_i32 m0, s60, 0x2000
	s_add_u32 s60, s36, 0x40000
	v_lshl_add_u64 v[220:221], s[36:37], 0, v[158:159]
	s_addc_u32 s61, s37, 0
	s_add_i32 s62, s52, s33
	global_load_lds_dwordx4 v[220:221], off
	v_lshl_add_u64 v[222:223], s[60:61], 0, v[154:155]
	s_mov_b32 m0, s62
	v_lshl_add_u64 v[224:225], s[38:39], 0, v[156:157]
	global_load_lds_dwordx4 v[222:223], off
	v_lshl_add_u64 v[222:223], s[60:61], 0, v[158:159]
	s_add_i32 m0, s62, 0x2000
	s_nop 0
	global_load_lds_dwordx4 v[222:223], off
	v_lshl_add_u64 v[222:223], s[38:39], 0, v[152:153]
	s_mov_b32 m0, s40
	s_nop 0
	global_load_lds_dwordx4 v[222:223], off
	s_mov_b32 m0, s41
	s_nop 0
	global_load_lds_dwordx4 v[224:225], off
	s_waitcnt vmcnt(8)
	s_waitcnt lgkmcnt(0)
	s_barrier
; #define PG8_STAGE(bufoff, gbase, voff) do { _Pragma("unroll") for (int _i = 0; _i < 2; ++_i) \
;         __builtin_amdgcn_global_load_lds((const unsigned*)((const char*)(gbase) + (voff)[_i]), (LAS unsigned*)(lds + (bufoff) + ldsw + _i * 8192), 16, 0, 0); } while (0)
; #define PG8_LDA(dst, b, h) do { _Pragma("unroll") for (int m = 0; m < 4; ++m) _Pragma("unroll") for (int k = 0; k < 2; ++k) dst[m][k] = *(const LAS bf16x8*)(lds + PG8_SA(b, h) + aoff + m * 2048 + k * 1024); } while (0)
; #define PG8_LDB(dst, b, h) do { _Pragma("unroll") for (int n = 0; n < 2; ++n) _Pragma("unroll") for (int k = 0; k < 2; ++k) dst[n][k] = *(const LAS bf16x8*)(lds + PG8_SB(b, h) + boff + n * 2048 + k * 1024); } while (0)
; #define PG8_MMA(ai, bj, At, Bt) do { __builtin_amdgcn_s_setprio(1); _Pragma("unroll") for (int m = 0; m < 4; ++m) _Pragma("unroll") for (int n = 0; n < 2; ++n) _Pragma("unroll") for (int k = 0; k < 2; ++k) \
;         acc[ai][bj][m][n] = __builtin_amdgcn_mfma_f32_16x16x32_bf16(Bt[n][k], At[m][k], acc[ai][bj][m][n], 0, 0, 0); __builtin_amdgcn_s_setprio(0); } while (0)
; #define PG8_WAIT_V(n) asm volatile("s_waitcnt vmcnt(" #n ")" ::: "memory")
; #define PG8_WAIT_L(n) asm volatile("s_waitcnt lgkmcnt(" #n ")" ::: "memory")
; #define PG8_BAR __builtin_amdgcn_s_barrier()
; #define PG8_SCHED __builtin_amdgcn_sched_barrier(0)
; template <class Epi>
; __device__ __forceinline__ void gemm_phase(LAS unsigned char* lds, const Gemm g, const Order& S, const Epi& E) {
;     ...
;             PG8_WAIT_V(8); PG8_WAIT_L(0); PG8_BAR; PG8_MMA(1, 0, At, B0); PG8_MMA(1, 1, At, B1); PG8_BAR; PG8_SCHED;
;             PG8_LDB(B0, 1, 0); PG8_LDB(B1, 1, 1); PG8_SCHED; PG8_LDA(At, 1, 0); PG8_STAGE(PG8_SA(0, 1), a2 + hstepA, voffA);
;             PG8_WAIT_V(8); PG8_WAIT_L(0); PG8_BAR; PG8_MMA(0, 0, At, B0); PG8_MMA(0, 1, At, B1); PG8_BAR; PG8_SCHED;
	s_setprio 1
	s_waitcnt lgkmcnt(0)
	v_mfma_f32_16x16x32_bf16 v[60:63], v[128:131], v[178:181], v[60:63]
	v_mfma_f32_16x16x32_bf16 v[56:59], v[136:139], v[178:181], v[56:59]
	v_mfma_f32_16x16x32_bf16 v[44:47], v[128:131], v[194:197], v[44:47]
	v_mfma_f32_16x16x32_bf16 v[40:43], v[136:139], v[194:197], v[40:43]
	v_mfma_f32_16x16x32_bf16 v[28:31], v[128:131], v[202:205], v[28:31]
	v_mfma_f32_16x16x32_bf16 v[24:27], v[136:139], v[202:205], v[24:27]
	v_mfma_f32_16x16x32_bf16 v[12:15], v[128:131], v[212:215], v[12:15]
	v_mfma_f32_16x16x32_bf16 v[8:11], v[136:139], v[212:215], v[8:11]
	v_mfma_f32_16x16x32_bf16 v[60:63], v[132:135], v[182:185], v[60:63]
	v_mfma_f32_16x16x32_bf16 v[56:59], v[140:143], v[182:185], v[56:59]
	v_mfma_f32_16x16x32_bf16 v[44:47], v[132:135], v[198:201], v[44:47]
	v_mfma_f32_16x16x32_bf16 v[40:43], v[140:143], v[198:201], v[40:43]
	v_mfma_f32_16x16x32_bf16 v[28:31], v[132:135], v[208:211], v[28:31]
	v_mfma_f32_16x16x32_bf16 v[24:27], v[140:143], v[208:211], v[24:27]
	v_mfma_f32_16x16x32_bf16 v[12:15], v[132:135], v[216:219], v[12:15]
	v_mfma_f32_16x16x32_bf16 v[8:11], v[140:143], v[216:219], v[8:11]
	v_mfma_f32_16x16x32_bf16 v[52:55], v[144:147], v[178:181], v[52:55]
	v_mfma_f32_16x16x32_bf16 v[48:51], v[168:171], v[178:181], v[48:51]
	v_mfma_f32_16x16x32_bf16 v[36:39], v[144:147], v[194:197], v[36:39]
	v_mfma_f32_16x16x32_bf16 v[32:35], v[168:171], v[194:197], v[32:35]
	v_mfma_f32_16x16x32_bf16 v[20:23], v[144:147], v[202:205], v[20:23]
	v_mfma_f32_16x16x32_bf16 v[16:19], v[168:171], v[202:205], v[16:19]
	v_mfma_f32_16x16x32_bf16 v[4:7], v[144:147], v[212:215], v[4:7]
	v_mfma_f32_16x16x32_bf16 v[0:3], v[168:171], v[212:215], v[0:3]
	v_mfma_f32_16x16x32_bf16 v[52:55], v[148:151], v[182:185], v[52:55]
	v_mfma_f32_16x16x32_bf16 v[48:51], v[172:175], v[182:185], v[48:51]
	v_mfma_f32_16x16x32_bf16 v[36:39], v[148:151], v[198:201], v[36:39]
	v_mfma_f32_16x16x32_bf16 v[32:35], v[172:175], v[198:201], v[32:35]
	v_mfma_f32_16x16x32_bf16 v[20:23], v[148:151], v[208:211], v[20:23]
	v_mfma_f32_16x16x32_bf16 v[16:19], v[172:175], v[208:211], v[16:19]
	v_mfma_f32_16x16x32_bf16 v[4:7], v[148:151], v[216:219], v[4:7]
	v_mfma_f32_16x16x32_bf16 v[0:3], v[172:175], v[216:219], v[0:3]
	s_setprio 0
	s_barrier
	s_add_i32 s60, 0, 0x18000
	s_add_i32 s61, 0, 0x1c000
	v_add_u32_e32 v140, s60, v188
	v_add_u32_e32 v172, s61, v188
	ds_read_b128 v[128:131], v140
	ds_read_b128 v[132:135], v140 offset:1024
	ds_read_b128 v[136:139], v140 offset:2048
	ds_read_b128 v[140:143], v140 offset:3072
	ds_read_b128 v[144:147], v172
	ds_read_b128 v[148:151], v172 offset:1024
	ds_read_b128 v[168:171], v172 offset:2048
	ds_read_b128 v[172:175], v172 offset:3072
	s_add_u32 s38, s38, 0x40000
	s_addc_u32 s39, s39, 0
	s_mov_b32 m0, s42
	v_lshl_add_u64 v[226:227], s[38:39], 0, v[152:153]
	ds_read_b128 v[178:181], v192 offset:32768
	ds_read_b128 v[182:185], v192 offset:33792
	ds_read_b128 v[194:197], v192 offset:34816
	ds_read_b128 v[198:201], v192 offset:35840
	ds_read_b128 v[202:205], v192 offset:36864
	ds_read_b128 v[208:211], v192 offset:37888
	ds_read_b128 v[212:215], v192 offset:38912
	ds_read_b128 v[216:219], v192 offset:39936
	global_load_lds_dwordx4 v[226:227], off
	v_lshl_add_u64 v[226:227], s[38:39], 0, v[156:157]
	s_mov_b32 m0, s43
	s_nop 0
	global_load_lds_dwordx4 v[226:227], off
	s_waitcnt vmcnt(8)
	s_waitcnt lgkmcnt(0)
	s_barrier
	s_setprio 1
	s_waitcnt lgkmcnt(0)
	v_mfma_f32_16x16x32_bf16 v[124:127], v[128:131], v[178:181], v[124:127]
	v_mfma_f32_16x16x32_bf16 v[120:123], v[136:139], v[178:181], v[120:123]
	v_mfma_f32_16x16x32_bf16 v[108:111], v[128:131], v[194:197], v[108:111]
	v_mfma_f32_16x16x32_bf16 v[104:107], v[136:139], v[194:197], v[104:107]
	v_mfma_f32_16x16x32_bf16 v[92:95], v[128:131], v[202:205], v[92:95]
	v_mfma_f32_16x16x32_bf16 v[88:91], v[136:139], v[202:205], v[88:91]
	v_mfma_f32_16x16x32_bf16 v[76:79], v[128:131], v[212:215], v[76:79]
	v_mfma_f32_16x16x32_bf16 v[72:75], v[136:139], v[212:215], v[72:75]
	v_mfma_f32_16x16x32_bf16 v[124:127], v[132:135], v[182:185], v[124:127]
	v_mfma_f32_16x16x32_bf16 v[120:123], v[140:143], v[182:185], v[120:123]
	v_mfma_f32_16x16x32_bf16 v[108:111], v[132:135], v[198:201], v[108:111]
	v_mfma_f32_16x16x32_bf16 v[104:107], v[140:143], v[198:201], v[104:107]
	v_mfma_f32_16x16x32_bf16 v[92:95], v[132:135], v[208:211], v[92:95]
	v_mfma_f32_16x16x32_bf16 v[88:91], v[140:143], v[208:211], v[88:91]
	v_mfma_f32_16x16x32_bf16 v[76:79], v[132:135], v[216:219], v[76:79]
	v_mfma_f32_16x16x32_bf16 v[72:75], v[140:143], v[216:219], v[72:75]
	v_mfma_f32_16x16x32_bf16 v[116:119], v[144:147], v[178:181], v[116:119]
	v_mfma_f32_16x16x32_bf16 v[112:115], v[168:171], v[178:181], v[112:115]
	v_mfma_f32_16x16x32_bf16 v[100:103], v[144:147], v[194:197], v[100:103]
	v_mfma_f32_16x16x32_bf16 v[96:99], v[168:171], v[194:197], v[96:99]
	v_mfma_f32_16x16x32_bf16 v[84:87], v[144:147], v[202:205], v[84:87]
	v_mfma_f32_16x16x32_bf16 v[80:83], v[168:171], v[202:205], v[80:83]
	v_mfma_f32_16x16x32_bf16 v[68:71], v[144:147], v[212:215], v[68:71]
	v_mfma_f32_16x16x32_bf16 v[64:67], v[168:171], v[212:215], v[64:67]
	v_mfma_f32_16x16x32_bf16 v[116:119], v[148:151], v[182:185], v[116:119]
	v_mfma_f32_16x16x32_bf16 v[112:115], v[172:175], v[182:185], v[112:115]
	v_mfma_f32_16x16x32_bf16 v[100:103], v[148:151], v[198:201], v[100:103]
	v_mfma_f32_16x16x32_bf16 v[96:99], v[172:175], v[198:201], v[96:99]
	v_mfma_f32_16x16x32_bf16 v[84:87], v[148:151], v[208:211], v[84:87]
	v_mfma_f32_16x16x32_bf16 v[80:83], v[172:175], v[208:211], v[80:83]
	v_mfma_f32_16x16x32_bf16 v[68:71], v[148:151], v[216:219], v[68:71]
	v_mfma_f32_16x16x32_bf16 v[64:67], v[172:175], v[216:219], v[64:67]
	s_setprio 0
	s_barrier
; #define PG8_STAGE(bufoff, gbase, voff) do { _Pragma("unroll") for (int _i = 0; _i < 2; ++_i) \
;         __builtin_amdgcn_global_load_lds((const unsigned*)((const char*)(gbase) + (voff)[_i]), (LAS unsigned*)(lds + (bufoff) + ldsw + _i * 8192), 16, 0, 0); } while (0)
; #define PG8_LDA(dst, b, h) do { _Pragma("unroll") for (int m = 0; m < 4; ++m) _Pragma("unroll") for (int k = 0; k < 2; ++k) dst[m][k] = *(const LAS bf16x8*)(lds + PG8_SA(b, h) + aoff + m * 2048 + k * 1024); } while (0)
; #define PG8_MMA(ai, bj, At, Bt) do { __builtin_amdgcn_s_setprio(1); _Pragma("unroll") for (int m = 0; m < 4; ++m) _Pragma("unroll") for (int n = 0; n < 2; ++n) _Pragma("unroll") for (int k = 0; k < 2; ++k) \
;         acc[ai][bj][m][n] = __builtin_amdgcn_mfma_f32_16x16x32_bf16(Bt[n][k], At[m][k], acc[ai][bj][m][n], 0, 0, 0); __builtin_amdgcn_s_setprio(0); } while (0)
; #define PG8_WAIT_V(n) asm volatile("s_waitcnt vmcnt(" #n ")" ::: "memory")
; #define PG8_WAIT_L(n) asm volatile("s_waitcnt lgkmcnt(" #n ")" ::: "memory")
; #define PG8_BAR __builtin_amdgcn_s_barrier()
; #define PG8_SCHED __builtin_amdgcn_sched_barrier(0)
; template <class Epi>
; __device__ __forceinline__ void gemm_phase(LAS unsigned char* lds, const Gemm g, const Order& S, const Epi& E) {
;     ...
;             PG8_LDA(At, 1, 1); PG8_STAGE(PG8_SB(1, 0), b3, voffB); PG8_STAGE(PG8_SB(1, 1), b3 + hstepB, voffB); PG8_STAGE(PG8_SA(1, 0), a3, voffA);
;             PG8_WAIT_V(8); PG8_WAIT_L(0); PG8_BAR; PG8_MMA(1, 0, At, B0); PG8_MMA(1, 1, At, B1); PG8_BAR; PG8_SCHED;
;         }
;         if (wr == 0) PG8_BAR;
	s_add_i32 s38, s60, s33
	v_lshl_add_u64 v[186:187], v[186:187], 0, s[12:13]
	s_mov_b32 m0, s38
	ds_read_b128 v[178:181], v192 offset:49152
	ds_read_b128 v[182:185], v192 offset:50176
	ds_read_b128 v[194:197], v192 offset:51200
	ds_read_b128 v[198:201], v192 offset:52224
	ds_read_b128 v[202:205], v192 offset:53248
	ds_read_b128 v[208:211], v192 offset:54272
	ds_read_b128 v[212:215], v192 offset:55296
	ds_read_b128 v[216:219], v192 offset:56320
	global_load_lds_dwordx4 v[186:187], off
	s_add_i32 m0, s38, 0x2000
	s_add_u32 s36, s36, 0x40080
	v_lshl_add_u64 v[186:187], v[220:221], 0, s[12:13]
	s_addc_u32 s37, s37, 0
	s_add_i32 s38, s61, s33
	global_load_lds_dwordx4 v[186:187], off
	v_lshl_add_u64 v[186:187], s[36:37], 0, v[154:155]
	s_mov_b32 m0, s38
	s_nop 0
	global_load_lds_dwordx4 v[186:187], off
	v_lshl_add_u64 v[186:187], s[36:37], 0, v[158:159]
	s_add_i32 m0, s38, 0x2000
	s_nop 0
	global_load_lds_dwordx4 v[186:187], off
	v_lshl_add_u64 v[186:187], v[222:223], 0, s[12:13]
	s_mov_b32 m0, s47
	s_nop 0
	global_load_lds_dwordx4 v[186:187], off
	v_lshl_add_u64 v[186:187], v[224:225], 0, s[12:13]
	s_mov_b32 m0, s48
	s_nop 0
	global_load_lds_dwordx4 v[186:187], off
	s_waitcnt vmcnt(8)
	s_waitcnt lgkmcnt(0)
	s_barrier
	s_setprio 1
	s_waitcnt lgkmcnt(0)
	v_mfma_f32_16x16x32_bf16 v[60:63], v[128:131], v[178:181], v[60:63]
	v_mfma_f32_16x16x32_bf16 v[56:59], v[136:139], v[178:181], v[56:59]
	v_mfma_f32_16x16x32_bf16 v[44:47], v[128:131], v[194:197], v[44:47]
	v_mfma_f32_16x16x32_bf16 v[40:43], v[136:139], v[194:197], v[40:43]
	v_mfma_f32_16x16x32_bf16 v[28:31], v[128:131], v[202:205], v[28:31]
	v_mfma_f32_16x16x32_bf16 v[24:27], v[136:139], v[202:205], v[24:27]
	v_mfma_f32_16x16x32_bf16 v[12:15], v[128:131], v[212:215], v[12:15]
	v_mfma_f32_16x16x32_bf16 v[8:11], v[136:139], v[212:215], v[8:11]
	v_mfma_f32_16x16x32_bf16 v[60:63], v[132:135], v[182:185], v[60:63]
	v_mfma_f32_16x16x32_bf16 v[56:59], v[140:143], v[182:185], v[56:59]
	v_mfma_f32_16x16x32_bf16 v[44:47], v[132:135], v[198:201], v[44:47]
	v_mfma_f32_16x16x32_bf16 v[40:43], v[140:143], v[198:201], v[40:43]
	v_mfma_f32_16x16x32_bf16 v[28:31], v[132:135], v[208:211], v[28:31]
	v_mfma_f32_16x16x32_bf16 v[24:27], v[140:143], v[208:211], v[24:27]
	v_mfma_f32_16x16x32_bf16 v[12:15], v[132:135], v[216:219], v[12:15]
	v_mfma_f32_16x16x32_bf16 v[8:11], v[140:143], v[216:219], v[8:11]
	v_mfma_f32_16x16x32_bf16 v[52:55], v[144:147], v[178:181], v[52:55]
	v_mfma_f32_16x16x32_bf16 v[48:51], v[168:171], v[178:181], v[48:51]
	v_mfma_f32_16x16x32_bf16 v[36:39], v[144:147], v[194:197], v[36:39]
	v_mfma_f32_16x16x32_bf16 v[32:35], v[168:171], v[194:197], v[32:35]
	v_mfma_f32_16x16x32_bf16 v[20:23], v[144:147], v[202:205], v[20:23]
	v_mfma_f32_16x16x32_bf16 v[16:19], v[168:171], v[202:205], v[16:19]
	v_mfma_f32_16x16x32_bf16 v[4:7], v[144:147], v[212:215], v[4:7]
	v_mfma_f32_16x16x32_bf16 v[0:3], v[168:171], v[212:215], v[0:3]
	v_mfma_f32_16x16x32_bf16 v[52:55], v[148:151], v[182:185], v[52:55]
	v_mfma_f32_16x16x32_bf16 v[48:51], v[172:175], v[182:185], v[48:51]
	v_mfma_f32_16x16x32_bf16 v[36:39], v[148:151], v[198:201], v[36:39]
	v_mfma_f32_16x16x32_bf16 v[32:35], v[172:175], v[198:201], v[32:35]
	v_mfma_f32_16x16x32_bf16 v[20:23], v[148:151], v[208:211], v[20:23]
	v_mfma_f32_16x16x32_bf16 v[16:19], v[172:175], v[208:211], v[16:19]
	v_mfma_f32_16x16x32_bf16 v[4:7], v[148:151], v[216:219], v[4:7]
	v_mfma_f32_16x16x32_bf16 v[0:3], v[172:175], v[216:219], v[0:3]
	s_setprio 0
	s_barrier
	s_add_i32 s59, s59, 2
	s_add_u32 s34, s34, 0x100
	s_addc_u32 s35, s35, 0
	s_add_u32 s57, s57, 0x100
	s_addc_u32 s58, s58, 0
	s_cmp_gt_u32 s59, 13
	s_cbranch_scc0 .LBB0_774
	s_and_b64 vcc, exec, s[14:15]
	s_cbranch_vccz .LBB0_777
	s_barrier

; #define PG8_STAGE(bufoff, gbase, voff) do { _Pragma("unroll") for (int _i = 0; _i < 2; ++_i) \
;         __builtin_amdgcn_global_load_lds((const unsigned*)((const char*)(gbase) + (voff)[_i]), (LAS unsigned*)(lds + (bufoff) + ldsw + _i * 8192), 16, 0, 0); } while (0)
; #define PG8_LDA(dst, b, h) do { _Pragma("unroll") for (int m = 0; m < 4; ++m) _Pragma("unroll") for (int k = 0; k < 2; ++k) dst[m][k] = *(const LAS bf16x8*)(lds + PG8_SA(b, h) + aoff + m * 2048 + k * 1024); } while (0)
; #define PG8_LDB(dst, b, h) do { _Pragma("unroll") for (int n = 0; n < 2; ++n) _Pragma("unroll") for (int k = 0; k < 2; ++k) dst[n][k] = *(const LAS bf16x8*)(lds + PG8_SB(b, h) + boff + n * 2048 + k * 1024); } while (0)
; #define PG8_MMA(ai, bj, At, Bt) do { __builtin_amdgcn_s_setprio(1); _Pragma("unroll") for (int m = 0; m < 4; ++m) _Pragma("unroll") for (int n = 0; n < 2; ++n) _Pragma("unroll") for (int k = 0; k < 2; ++k) \
;         acc[ai][bj][m][n] = __builtin_amdgcn_mfma_f32_16x16x32_bf16(Bt[n][k], At[m][k], acc[ai][bj][m][n], 0, 0, 0); __builtin_amdgcn_s_setprio(0); } while (0)
; #define PG8_WAIT_V(n) asm volatile("s_waitcnt vmcnt(" #n ")" ::: "memory")
; #define PG8_WAIT_L(n) asm volatile("s_waitcnt lgkmcnt(" #n ")" ::: "memory")
; #define PG8_BAR __builtin_amdgcn_s_barrier()
; #define PG8_SCHED __builtin_amdgcn_sched_barrier(0)
; template <class Epi>
; __device__ __forceinline__ void gemm_phase(LAS unsigned char* lds, const Gemm g, const Order& S, const Epi& E) {
;     ...
;         for (int t = 0; t < nt; t += 2) {
;             const bool last = (t == nt - 2);
;             const char* a1 = cA + (size_t)(t + 1) * kstep;
;             const char* a2 = last ? nA : cA + (size_t)(t + 2) * kstep; const char* b2 = last ? nB : cB + (size_t)(t + 2) * kstep;
;             const char* a3 = a2 + kstep; const char* b3 = b2 + kstep;
;             PG8_LDB(B0, 0, 0); PG8_LDB(B1, 0, 1); PG8_SCHED; PG8_LDA(At, 0, 0); PG8_STAGE(PG8_SA(1, 1), a1 + hstepA, voffA);
;             PG8_WAIT_V(8); PG8_WAIT_L(0); PG8_BAR; PG8_MMA(0, 0, At, B0); PG8_MMA(0, 1, At, B1); PG8_BAR; PG8_SCHED;
;             PG8_LDA(At, 0, 1); PG8_STAGE(PG8_SB(0, 0), b2, voffB); PG8_STAGE(PG8_SB(0, 1), b2 + hstepB, voffB); PG8_STAGE(PG8_SA(0, 0), a2, voffA);
.LBB0_861:
	ds_read_b128 v[128:131], v189
	ds_read_b128 v[132:135], v189 offset:1024
	ds_read_b128 v[136:139], v189 offset:2048
	ds_read_b128 v[140:143], v189 offset:3072
	ds_read_b128 v[164:167], v191
	ds_read_b128 v[168:171], v191 offset:1024
	ds_read_b128 v[172:175], v191 offset:2048
	ds_read_b128 v[178:181], v191 offset:3072
	s_add_u32 s16, s14, 0xfff80080
	s_addc_u32 s17, s15, -1
	s_cmp_eq_u32 s90, 28
	s_cselect_b32 s19, s47, s17
	s_cselect_b32 s18, s49, s16
	s_cselect_b32 s17, s84, s89
	s_cselect_b32 s16, s85, s88
	v_lshl_add_u64 v[204:205], s[14:15], 0, v[156:157]
	s_add_i32 m0, s62, 0xc000
	ds_read_b128 v[182:185], v193
	ds_read_b128 v[196:199], v193 offset:1024
	ds_read_b128 v[200:203], v193 offset:2048
	ds_read_b128 v[208:211], v193 offset:3072
	ds_read_b128 v[212:215], v193 offset:4096
	ds_read_b128 v[216:219], v193 offset:5120
	ds_read_b128 v[220:223], v193 offset:6144
	ds_read_b128 v[224:227], v193 offset:7168
	global_load_lds_dwordx4 v[204:205], off
	v_lshl_add_u64 v[204:205], s[14:15], 0, v[158:159]
	s_add_i32 m0, s62, 0xe000
	s_nop 0
	global_load_lds_dwordx4 v[204:205], off
	s_waitcnt vmcnt(8)
	s_waitcnt lgkmcnt(0)
	s_barrier
	s_setprio 1
	s_waitcnt lgkmcnt(0)
	v_mfma_f32_16x16x32_bf16 v[84:87], v[128:131], v[182:185], v[84:87]
	v_mfma_f32_16x16x32_bf16 v[80:83], v[136:139], v[182:185], v[80:83]
	v_mfma_f32_16x16x32_bf16 v[124:127], v[128:131], v[200:203], v[124:127]
	v_mfma_f32_16x16x32_bf16 v[104:107], v[136:139], v[200:203], v[104:107]
	v_mfma_f32_16x16x32_bf16 v[120:123], v[128:131], v[212:215], v[120:123]
	v_mfma_f32_16x16x32_bf16 v[100:103], v[136:139], v[212:215], v[100:103]
	v_mfma_f32_16x16x32_bf16 v[68:71], v[128:131], v[220:223], v[68:71]
	v_mfma_f32_16x16x32_bf16 v[64:67], v[136:139], v[220:223], v[64:67]
	v_mfma_f32_16x16x32_bf16 v[84:87], v[132:135], v[196:199], v[84:87]
	v_mfma_f32_16x16x32_bf16 v[80:83], v[140:143], v[196:199], v[80:83]
	v_mfma_f32_16x16x32_bf16 v[124:127], v[132:135], v[208:211], v[124:127]
	v_mfma_f32_16x16x32_bf16 v[104:107], v[140:143], v[208:211], v[104:107]
	v_mfma_f32_16x16x32_bf16 v[120:123], v[132:135], v[216:219], v[120:123]
	v_mfma_f32_16x16x32_bf16 v[100:103], v[140:143], v[216:219], v[100:103]
	v_mfma_f32_16x16x32_bf16 v[68:71], v[132:135], v[224:227], v[68:71]
	v_mfma_f32_16x16x32_bf16 v[64:67], v[140:143], v[224:227], v[64:67]
	v_mfma_f32_16x16x32_bf16 v[76:79], v[164:167], v[182:185], v[76:79]
	v_mfma_f32_16x16x32_bf16 v[72:75], v[172:175], v[182:185], v[72:75]
	v_mfma_f32_16x16x32_bf16 v[116:119], v[164:167], v[200:203], v[116:119]
	v_mfma_f32_16x16x32_bf16 v[96:99], v[172:175], v[200:203], v[96:99]
	v_mfma_f32_16x16x32_bf16 v[112:115], v[164:167], v[212:215], v[112:115]
	v_mfma_f32_16x16x32_bf16 v[92:95], v[172:175], v[212:215], v[92:95]
	v_mfma_f32_16x16x32_bf16 v[108:111], v[164:167], v[220:223], v[108:111]
	v_mfma_f32_16x16x32_bf16 v[88:91], v[172:175], v[220:223], v[88:91]
	v_mfma_f32_16x16x32_bf16 v[76:79], v[168:171], v[196:199], v[76:79]
	v_mfma_f32_16x16x32_bf16 v[72:75], v[178:181], v[196:199], v[72:75]
	v_mfma_f32_16x16x32_bf16 v[116:119], v[168:171], v[208:211], v[116:119]
	v_mfma_f32_16x16x32_bf16 v[96:99], v[178:181], v[208:211], v[96:99]
	v_mfma_f32_16x16x32_bf16 v[112:115], v[168:171], v[216:219], v[112:115]
	v_mfma_f32_16x16x32_bf16 v[92:95], v[178:181], v[216:219], v[92:95]
	v_mfma_f32_16x16x32_bf16 v[108:111], v[168:171], v[224:227], v[108:111]
	v_mfma_f32_16x16x32_bf16 v[88:91], v[178:181], v[224:227], v[88:91]
	s_setprio 0
	s_barrier
	s_add_i32 s91, s78, s43
	v_lshl_add_u64 v[204:205], s[16:17], 0, v[148:149]
	s_mov_b32 m0, s91
	ds_read_b128 v[182:185], v193 offset:16384
	ds_read_b128 v[196:199], v193 offset:17408
	ds_read_b128 v[200:203], v193 offset:18432
	ds_read_b128 v[208:211], v193 offset:19456
	ds_read_b128 v[212:215], v193 offset:20480
	ds_read_b128 v[216:219], v193 offset:21504
	ds_read_b128 v[220:223], v193 offset:22528
	ds_read_b128 v[224:227], v193 offset:23552
	global_load_lds_dwordx4 v[204:205], off
	s_add_i32 m0, s91, 0x2000
	s_add_u32 s92, s16, 0x80000
	v_lshl_add_u64 v[228:229], s[16:17], 0, v[144:145]
	s_addc_u32 s93, s17, 0
	s_add_i32 s91, s79, s43
	global_load_lds_dwordx4 v[228:229], off
	v_lshl_add_u64 v[230:231], s[92:93], 0, v[148:149]
	s_mov_b32 m0, s91
	v_lshl_add_u64 v[232:233], s[18:19], 0, v[146:147]
	global_load_lds_dwordx4 v[230:231], off
	v_lshl_add_u64 v[230:231], s[92:93], 0, v[144:145]
	s_add_i32 m0, s91, 0x2000
	s_nop 0
	global_load_lds_dwordx4 v[230:231], off
	v_lshl_add_u64 v[230:231], s[18:19], 0, v[150:151]
	s_mov_b32 m0, s62
	s_nop 0
	global_load_lds_dwordx4 v[230:231], off
	s_mov_b32 m0, s63
	s_nop 0
	global_load_lds_dwordx4 v[232:233], off
	s_waitcnt vmcnt(8)
	s_waitcnt lgkmcnt(0)
	s_barrier
; #define PG8_STAGE(bufoff, gbase, voff) do { _Pragma("unroll") for (int _i = 0; _i < 2; ++_i) \
;         __builtin_amdgcn_global_load_lds((const unsigned*)((const char*)(gbase) + (voff)[_i]), (LAS unsigned*)(lds + (bufoff) + ldsw + _i * 8192), 16, 0, 0); } while (0)
; #define PG8_LDA(dst, b, h) do { _Pragma("unroll") for (int m = 0; m < 4; ++m) _Pragma("unroll") for (int k = 0; k < 2; ++k) dst[m][k] = *(const LAS bf16x8*)(lds + PG8_SA(b, h) + aoff + m * 2048 + k * 1024); } while (0)
; #define PG8_LDB(dst, b, h) do { _Pragma("unroll") for (int n = 0; n < 2; ++n) _Pragma("unroll") for (int k = 0; k < 2; ++k) dst[n][k] = *(const LAS bf16x8*)(lds + PG8_SB(b, h) + boff + n * 2048 + k * 1024); } while (0)
; #define PG8_MMA(ai, bj, At, Bt) do { __builtin_amdgcn_s_setprio(1); _Pragma("unroll") for (int m = 0; m < 4; ++m) _Pragma("unroll") for (int n = 0; n < 2; ++n) _Pragma("unroll") for (int k = 0; k < 2; ++k) \
;         acc[ai][bj][m][n] = __builtin_amdgcn_mfma_f32_16x16x32_bf16(Bt[n][k], At[m][k], acc[ai][bj][m][n], 0, 0, 0); __builtin_amdgcn_s_setprio(0); } while (0)
; #define PG8_WAIT_V(n) asm volatile("s_waitcnt vmcnt(" #n ")" ::: "memory")
; #define PG8_WAIT_L(n) asm volatile("s_waitcnt lgkmcnt(" #n ")" ::: "memory")
; #define PG8_BAR __builtin_amdgcn_s_barrier()
; #define PG8_SCHED __builtin_amdgcn_sched_barrier(0)
; template <class Epi>
; __device__ __forceinline__ void gemm_phase(LAS unsigned char* lds, const Gemm g, const Order& S, const Epi& E) {
;     ...
;             PG8_WAIT_V(8); PG8_WAIT_L(0); PG8_BAR; PG8_MMA(1, 0, At, B0); PG8_MMA(1, 1, At, B1); PG8_BAR; PG8_SCHED;
;             PG8_LDB(B0, 1, 0); PG8_LDB(B1, 1, 1); PG8_SCHED; PG8_LDA(At, 1, 0); PG8_STAGE(PG8_SA(0, 1), a2 + hstepA, voffA);
;             PG8_WAIT_V(8); PG8_WAIT_L(0); PG8_BAR; PG8_MMA(0, 0, At, B0); PG8_MMA(0, 1, At, B1); PG8_BAR; PG8_SCHED;
	s_setprio 1
	s_waitcnt lgkmcnt(0)
	v_mfma_f32_16x16x32_bf16 v[24:27], v[128:131], v[182:185], v[24:27]
	v_mfma_f32_16x16x32_bf16 v[16:19], v[136:139], v[182:185], v[16:19]
	v_mfma_f32_16x16x32_bf16 v[60:63], v[128:131], v[200:203], v[60:63]
	v_mfma_f32_16x16x32_bf16 v[40:43], v[136:139], v[200:203], v[40:43]
	v_mfma_f32_16x16x32_bf16 v[56:59], v[128:131], v[212:215], v[56:59]
	v_mfma_f32_16x16x32_bf16 v[36:39], v[136:139], v[212:215], v[36:39]
	v_mfma_f32_16x16x32_bf16 v[4:7], v[128:131], v[220:223], v[4:7]
	v_mfma_f32_16x16x32_bf16 v[0:3], v[136:139], v[220:223], v[0:3]
	v_mfma_f32_16x16x32_bf16 v[24:27], v[132:135], v[196:199], v[24:27]
	v_mfma_f32_16x16x32_bf16 v[16:19], v[140:143], v[196:199], v[16:19]
	v_mfma_f32_16x16x32_bf16 v[60:63], v[132:135], v[208:211], v[60:63]
	v_mfma_f32_16x16x32_bf16 v[40:43], v[140:143], v[208:211], v[40:43]
	v_mfma_f32_16x16x32_bf16 v[56:59], v[132:135], v[216:219], v[56:59]
	v_mfma_f32_16x16x32_bf16 v[36:39], v[140:143], v[216:219], v[36:39]
	v_mfma_f32_16x16x32_bf16 v[4:7], v[132:135], v[224:227], v[4:7]
	v_mfma_f32_16x16x32_bf16 v[0:3], v[140:143], v[224:227], v[0:3]
	v_mfma_f32_16x16x32_bf16 v[12:15], v[164:167], v[182:185], v[12:15]
	v_mfma_f32_16x16x32_bf16 v[8:11], v[172:175], v[182:185], v[8:11]
	v_mfma_f32_16x16x32_bf16 v[52:55], v[164:167], v[200:203], v[52:55]
	v_mfma_f32_16x16x32_bf16 v[32:35], v[172:175], v[200:203], v[32:35]
	v_mfma_f32_16x16x32_bf16 v[48:51], v[164:167], v[212:215], v[48:51]
	v_mfma_f32_16x16x32_bf16 v[28:31], v[172:175], v[212:215], v[28:31]
	v_mfma_f32_16x16x32_bf16 v[44:47], v[164:167], v[220:223], v[44:47]
	v_mfma_f32_16x16x32_bf16 v[20:23], v[172:175], v[220:223], v[20:23]
	v_mfma_f32_16x16x32_bf16 v[12:15], v[168:171], v[196:199], v[12:15]
	v_mfma_f32_16x16x32_bf16 v[8:11], v[178:181], v[196:199], v[8:11]
	v_mfma_f32_16x16x32_bf16 v[52:55], v[168:171], v[208:211], v[52:55]
	v_mfma_f32_16x16x32_bf16 v[32:35], v[178:181], v[208:211], v[32:35]
	v_mfma_f32_16x16x32_bf16 v[48:51], v[168:171], v[216:219], v[48:51]
	v_mfma_f32_16x16x32_bf16 v[28:31], v[178:181], v[216:219], v[28:31]
	v_mfma_f32_16x16x32_bf16 v[44:47], v[168:171], v[224:227], v[44:47]
	v_mfma_f32_16x16x32_bf16 v[20:23], v[178:181], v[224:227], v[20:23]
	s_setprio 0
	s_barrier
	s_add_i32 s91, 0, 0x18000
	s_add_i32 s92, 0, 0x1c000
	v_add_u32_e32 v140, s91, v177
	v_add_u32_e32 v178, s92, v177
	ds_read_b128 v[128:131], v140
	ds_read_b128 v[132:135], v140 offset:1024
	ds_read_b128 v[136:139], v140 offset:2048
	ds_read_b128 v[140:143], v140 offset:3072
	ds_read_b128 v[164:167], v178
	ds_read_b128 v[168:171], v178 offset:1024
	ds_read_b128 v[172:175], v178 offset:2048
	ds_read_b128 v[178:181], v178 offset:3072
	s_add_u32 s18, s18, 0x80000
	s_addc_u32 s19, s19, 0
	s_mov_b32 m0, s64
	v_lshl_add_u64 v[234:235], s[18:19], 0, v[150:151]
	ds_read_b128 v[182:185], v193 offset:32768
	ds_read_b128 v[196:199], v193 offset:33792
	ds_read_b128 v[200:203], v193 offset:34816
	ds_read_b128 v[208:211], v193 offset:35840
	ds_read_b128 v[212:215], v193 offset:36864
	ds_read_b128 v[216:219], v193 offset:37888
	ds_read_b128 v[220:223], v193 offset:38912
	ds_read_b128 v[224:227], v193 offset:39936
	global_load_lds_dwordx4 v[234:235], off
	v_lshl_add_u64 v[234:235], s[18:19], 0, v[146:147]
	s_mov_b32 m0, s65
	s_nop 0
	global_load_lds_dwordx4 v[234:235], off
	s_waitcnt vmcnt(8)
	s_waitcnt lgkmcnt(0)
	s_barrier
	s_setprio 1
	s_waitcnt lgkmcnt(0)
	v_mfma_f32_16x16x32_bf16 v[84:87], v[128:131], v[182:185], v[84:87]
	v_mfma_f32_16x16x32_bf16 v[80:83], v[136:139], v[182:185], v[80:83]
	v_mfma_f32_16x16x32_bf16 v[124:127], v[128:131], v[200:203], v[124:127]
	v_mfma_f32_16x16x32_bf16 v[104:107], v[136:139], v[200:203], v[104:107]
	v_mfma_f32_16x16x32_bf16 v[120:123], v[128:131], v[212:215], v[120:123]
	v_mfma_f32_16x16x32_bf16 v[100:103], v[136:139], v[212:215], v[100:103]
	v_mfma_f32_16x16x32_bf16 v[68:71], v[128:131], v[220:223], v[68:71]
	v_mfma_f32_16x16x32_bf16 v[64:67], v[136:139], v[220:223], v[64:67]
	v_mfma_f32_16x16x32_bf16 v[84:87], v[132:135], v[196:199], v[84:87]
	v_mfma_f32_16x16x32_bf16 v[80:83], v[140:143], v[196:199], v[80:83]
	v_mfma_f32_16x16x32_bf16 v[124:127], v[132:135], v[208:211], v[124:127]
	v_mfma_f32_16x16x32_bf16 v[104:107], v[140:143], v[208:211], v[104:107]
	v_mfma_f32_16x16x32_bf16 v[120:123], v[132:135], v[216:219], v[120:123]
	v_mfma_f32_16x16x32_bf16 v[100:103], v[140:143], v[216:219], v[100:103]
	v_mfma_f32_16x16x32_bf16 v[68:71], v[132:135], v[224:227], v[68:71]
	v_mfma_f32_16x16x32_bf16 v[64:67], v[140:143], v[224:227], v[64:67]
	v_mfma_f32_16x16x32_bf16 v[76:79], v[164:167], v[182:185], v[76:79]
	v_mfma_f32_16x16x32_bf16 v[72:75], v[172:175], v[182:185], v[72:75]
	v_mfma_f32_16x16x32_bf16 v[116:119], v[164:167], v[200:203], v[116:119]
	v_mfma_f32_16x16x32_bf16 v[96:99], v[172:175], v[200:203], v[96:99]
	v_mfma_f32_16x16x32_bf16 v[112:115], v[164:167], v[212:215], v[112:115]
	v_mfma_f32_16x16x32_bf16 v[92:95], v[172:175], v[212:215], v[92:95]
	v_mfma_f32_16x16x32_bf16 v[108:111], v[164:167], v[220:223], v[108:111]
	v_mfma_f32_16x16x32_bf16 v[88:91], v[172:175], v[220:223], v[88:91]
	v_mfma_f32_16x16x32_bf16 v[76:79], v[168:171], v[196:199], v[76:79]
	v_mfma_f32_16x16x32_bf16 v[72:75], v[178:181], v[196:199], v[72:75]
	v_mfma_f32_16x16x32_bf16 v[116:119], v[168:171], v[208:211], v[116:119]
	v_mfma_f32_16x16x32_bf16 v[96:99], v[178:181], v[208:211], v[96:99]
	v_mfma_f32_16x16x32_bf16 v[112:115], v[168:171], v[216:219], v[112:115]
	v_mfma_f32_16x16x32_bf16 v[92:95], v[178:181], v[216:219], v[92:95]
	v_mfma_f32_16x16x32_bf16 v[108:111], v[168:171], v[224:227], v[108:111]
	v_mfma_f32_16x16x32_bf16 v[88:91], v[178:181], v[224:227], v[88:91]
	s_setprio 0
	s_barrier
; #define PG8_STAGE(bufoff, gbase, voff) do { _Pragma("unroll") for (int _i = 0; _i < 2; ++_i) \
;         __builtin_amdgcn_global_load_lds((const unsigned*)((const char*)(gbase) + (voff)[_i]), (LAS unsigned*)(lds + (bufoff) + ldsw + _i * 8192), 16, 0, 0); } while (0)
; #define PG8_LDA(dst, b, h) do { _Pragma("unroll") for (int m = 0; m < 4; ++m) _Pragma("unroll") for (int k = 0; k < 2; ++k) dst[m][k] = *(const LAS bf16x8*)(lds + PG8_SA(b, h) + aoff + m * 2048 + k * 1024); } while (0)
; #define PG8_MMA(ai, bj, At, Bt) do { __builtin_amdgcn_s_setprio(1); _Pragma("unroll") for (int m = 0; m < 4; ++m) _Pragma("unroll") for (int n = 0; n < 2; ++n) _Pragma("unroll") for (int k = 0; k < 2; ++k) \
;         acc[ai][bj][m][n] = __builtin_amdgcn_mfma_f32_16x16x32_bf16(Bt[n][k], At[m][k], acc[ai][bj][m][n], 0, 0, 0); __builtin_amdgcn_s_setprio(0); } while (0)
; #define PG8_WAIT_V(n) asm volatile("s_waitcnt vmcnt(" #n ")" ::: "memory")
; #define PG8_WAIT_L(n) asm volatile("s_waitcnt lgkmcnt(" #n ")" ::: "memory")
; #define PG8_BAR __builtin_amdgcn_s_barrier()
; #define PG8_SCHED __builtin_amdgcn_sched_barrier(0)
; template <class Epi>
; __device__ __forceinline__ void gemm_phase(LAS unsigned char* lds, const Gemm g, const Order& S, const Epi& E) {
;     ...
;             PG8_LDA(At, 1, 1); PG8_STAGE(PG8_SB(1, 0), b3, voffB); PG8_STAGE(PG8_SB(1, 1), b3 + hstepB, voffB); PG8_STAGE(PG8_SA(1, 0), a3, voffA);
;             PG8_WAIT_V(8); PG8_WAIT_L(0); PG8_BAR; PG8_MMA(1, 0, At, B0); PG8_MMA(1, 1, At, B1); PG8_BAR; PG8_SCHED;
;         }
;         if (wr == 0) PG8_BAR;
	s_add_i32 s18, s91, s43
	v_lshl_add_u64 v[204:205], v[204:205], 0, s[34:35]
	s_mov_b32 m0, s18
	ds_read_b128 v[182:185], v193 offset:49152
	ds_read_b128 v[196:199], v193 offset:50176
	ds_read_b128 v[200:203], v193 offset:51200
	ds_read_b128 v[208:211], v193 offset:52224
	ds_read_b128 v[212:215], v193 offset:53248
	ds_read_b128 v[216:219], v193 offset:54272
	ds_read_b128 v[220:223], v193 offset:55296
	ds_read_b128 v[224:227], v193 offset:56320
	global_load_lds_dwordx4 v[204:205], off
	s_add_i32 m0, s18, 0x2000
	s_add_u32 s16, s16, 0x80080
	v_lshl_add_u64 v[204:205], v[228:229], 0, s[34:35]
	s_addc_u32 s17, s17, 0
	s_add_i32 s18, s92, s43
	global_load_lds_dwordx4 v[204:205], off
	v_lshl_add_u64 v[204:205], s[16:17], 0, v[148:149]
	s_mov_b32 m0, s18
	s_nop 0
	global_load_lds_dwordx4 v[204:205], off
	v_lshl_add_u64 v[204:205], s[16:17], 0, v[144:145]
	s_add_i32 m0, s18, 0x2000
	s_nop 0
	global_load_lds_dwordx4 v[204:205], off
	v_lshl_add_u64 v[204:205], v[230:231], 0, s[34:35]
	s_mov_b32 m0, s66
	s_nop 0
	global_load_lds_dwordx4 v[204:205], off
	v_lshl_add_u64 v[204:205], v[232:233], 0, s[34:35]
	s_mov_b32 m0, s67
	s_nop 0
	global_load_lds_dwordx4 v[204:205], off
	s_waitcnt vmcnt(8)
	s_waitcnt lgkmcnt(0)
	s_barrier
	s_setprio 1
	s_waitcnt lgkmcnt(0)
	v_mfma_f32_16x16x32_bf16 v[24:27], v[128:131], v[182:185], v[24:27]
	v_mfma_f32_16x16x32_bf16 v[16:19], v[136:139], v[182:185], v[16:19]
	v_mfma_f32_16x16x32_bf16 v[60:63], v[128:131], v[200:203], v[60:63]
	v_mfma_f32_16x16x32_bf16 v[40:43], v[136:139], v[200:203], v[40:43]
	v_mfma_f32_16x16x32_bf16 v[56:59], v[128:131], v[212:215], v[56:59]
	v_mfma_f32_16x16x32_bf16 v[36:39], v[136:139], v[212:215], v[36:39]
	v_mfma_f32_16x16x32_bf16 v[4:7], v[128:131], v[220:223], v[4:7]
	v_mfma_f32_16x16x32_bf16 v[0:3], v[136:139], v[220:223], v[0:3]
	v_mfma_f32_16x16x32_bf16 v[24:27], v[132:135], v[196:199], v[24:27]
	v_mfma_f32_16x16x32_bf16 v[16:19], v[140:143], v[196:199], v[16:19]
	v_mfma_f32_16x16x32_bf16 v[60:63], v[132:135], v[208:211], v[60:63]
	v_mfma_f32_16x16x32_bf16 v[40:43], v[140:143], v[208:211], v[40:43]
	v_mfma_f32_16x16x32_bf16 v[56:59], v[132:135], v[216:219], v[56:59]
	v_mfma_f32_16x16x32_bf16 v[36:39], v[140:143], v[216:219], v[36:39]
	v_mfma_f32_16x16x32_bf16 v[4:7], v[132:135], v[224:227], v[4:7]
	v_mfma_f32_16x16x32_bf16 v[0:3], v[140:143], v[224:227], v[0:3]
	v_mfma_f32_16x16x32_bf16 v[12:15], v[164:167], v[182:185], v[12:15]
	v_mfma_f32_16x16x32_bf16 v[8:11], v[172:175], v[182:185], v[8:11]
	v_mfma_f32_16x16x32_bf16 v[52:55], v[164:167], v[200:203], v[52:55]
	v_mfma_f32_16x16x32_bf16 v[32:35], v[172:175], v[200:203], v[32:35]
	v_mfma_f32_16x16x32_bf16 v[48:51], v[164:167], v[212:215], v[48:51]
	v_mfma_f32_16x16x32_bf16 v[28:31], v[172:175], v[212:215], v[28:31]
	v_mfma_f32_16x16x32_bf16 v[44:47], v[164:167], v[220:223], v[44:47]
	v_mfma_f32_16x16x32_bf16 v[20:23], v[172:175], v[220:223], v[20:23]
	v_mfma_f32_16x16x32_bf16 v[12:15], v[168:171], v[196:199], v[12:15]
	v_mfma_f32_16x16x32_bf16 v[8:11], v[178:181], v[196:199], v[8:11]
	v_mfma_f32_16x16x32_bf16 v[52:55], v[168:171], v[208:211], v[52:55]
	v_mfma_f32_16x16x32_bf16 v[32:35], v[178:181], v[208:211], v[32:35]
	v_mfma_f32_16x16x32_bf16 v[48:51], v[168:171], v[216:219], v[48:51]
	v_mfma_f32_16x16x32_bf16 v[28:31], v[178:181], v[216:219], v[28:31]
	v_mfma_f32_16x16x32_bf16 v[44:47], v[168:171], v[224:227], v[44:47]
	v_mfma_f32_16x16x32_bf16 v[20:23], v[178:181], v[224:227], v[20:23]
	s_setprio 0
	s_barrier
	s_add_i32 s90, s90, 2
	s_add_u32 s14, s14, 0x100
	s_addc_u32 s15, s15, 0
	s_add_u32 s88, s88, 0x100
	s_addc_u32 s89, s89, 0
	s_cmp_gt_u32 s90, 29
	s_cbranch_scc0 .LBB0_861
	s_and_b64 vcc, exec, s[36:37]
	s_cbranch_vccz .LBB0_864
	s_barrier

; #define PG8_STAGE(bufoff, gbase, voff) do { _Pragma("unroll") for (int _i = 0; _i < 2; ++_i) \
;         __builtin_amdgcn_global_load_lds((const unsigned*)((const char*)(gbase) + (voff)[_i]), (LAS unsigned*)(lds + (bufoff) + ldsw + _i * 8192), 16, 0, 0); } while (0)
; #define PG8_LDA(dst, b, h) do { _Pragma("unroll") for (int m = 0; m < 4; ++m) _Pragma("unroll") for (int k = 0; k < 2; ++k) dst[m][k] = *(const LAS bf16x8*)(lds + PG8_SA(b, h) + aoff + m * 2048 + k * 1024); } while (0)
; #define PG8_LDB(dst, b, h) do { _Pragma("unroll") for (int n = 0; n < 2; ++n) _Pragma("unroll") for (int k = 0; k < 2; ++k) dst[n][k] = *(const LAS bf16x8*)(lds + PG8_SB(b, h) + boff + n * 2048 + k * 1024); } while (0)
; #define PG8_MMA(ai, bj, At, Bt) do { __builtin_amdgcn_s_setprio(1); _Pragma("unroll") for (int m = 0; m < 4; ++m) _Pragma("unroll") for (int n = 0; n < 2; ++n) _Pragma("unroll") for (int k = 0; k < 2; ++k) \
;         acc[ai][bj][m][n] = __builtin_amdgcn_mfma_f32_16x16x32_bf16(Bt[n][k], At[m][k], acc[ai][bj][m][n], 0, 0, 0); __builtin_amdgcn_s_setprio(0); } while (0)
; #define PG8_WAIT_V(n) asm volatile("s_waitcnt vmcnt(" #n ")" ::: "memory")
; #define PG8_WAIT_L(n) asm volatile("s_waitcnt lgkmcnt(" #n ")" ::: "memory")
; #define PG8_BAR __builtin_amdgcn_s_barrier()
; #define PG8_SCHED __builtin_amdgcn_sched_barrier(0)
; template <class Epi>
; __device__ __forceinline__ void gemm_phase(LAS unsigned char* lds, const Gemm g, const Order& S, const Epi& E) {
;     ...
;         for (int t = 0; t < nt; t += 2) {
;             const bool last = (t == nt - 2);
;             const char* a1 = cA + (size_t)(t + 1) * kstep;
;             const char* a2 = last ? nA : cA + (size_t)(t + 2) * kstep; const char* b2 = last ? nB : cB + (size_t)(t + 2) * kstep;
;             const char* a3 = a2 + kstep; const char* b3 = b2 + kstep;
;             PG8_LDB(B0, 0, 0); PG8_LDB(B1, 0, 1); PG8_SCHED; PG8_LDA(At, 0, 0); PG8_STAGE(PG8_SA(1, 1), a1 + hstepA, voffA);
;             PG8_WAIT_V(8); PG8_WAIT_L(0); PG8_BAR; PG8_MMA(0, 0, At, B0); PG8_MMA(0, 1, At, B1); PG8_BAR; PG8_SCHED;
;             PG8_LDA(At, 0, 1); PG8_STAGE(PG8_SB(0, 0), b2, voffB); PG8_STAGE(PG8_SB(0, 1), b2 + hstepB, voffB); PG8_STAGE(PG8_SA(0, 0), a2, voffA);
.LBB0_1023:
	ds_read_b128 v[144:147], v159
	ds_read_b128 v[148:151], v159 offset:1024
	ds_read_b128 v[152:155], v159 offset:2048
	ds_read_b128 v[162:165], v159 offset:3072
	ds_read_b128 v[166:169], v160
	ds_read_b128 v[170:173], v160 offset:1024
	ds_read_b128 v[178:181], v160 offset:2048
	ds_read_b128 v[182:185], v160 offset:3072
	s_add_u32 s34, s30, 0xffea0080
	s_addc_u32 s35, s31, -1
	s_cmpk_eq_i32 s63, 0x54
	s_cselect_b32 s37, s57, s35
	s_cselect_b32 s36, s58, s34
	s_cselect_b32 s35, s59, s62
	s_cselect_b32 s34, s60, s61
	v_lshl_add_u64 v[174:175], s[30:31], 0, v[136:137]
	s_add_i32 m0, s41, 0xc000
	ds_read_b128 v[186:189], v161
	ds_read_b128 v[190:193], v161 offset:1024
	ds_read_b128 v[194:197], v161 offset:2048
	ds_read_b128 v[198:201], v161 offset:3072
	ds_read_b128 v[202:205], v161 offset:4096
	ds_read_b128 v[208:211], v161 offset:5120
	ds_read_b128 v[212:215], v161 offset:6144
	ds_read_b128 v[216:219], v161 offset:7168
	global_load_lds_dwordx4 v[174:175], off
	v_lshl_add_u64 v[174:175], s[30:31], 0, v[138:139]
	s_add_i32 m0, s41, 0xe000
	s_nop 0
	global_load_lds_dwordx4 v[174:175], off
	s_waitcnt vmcnt(8)
	s_waitcnt lgkmcnt(0)
	s_barrier
	s_setprio 1
	s_waitcnt lgkmcnt(0)
	v_mfma_f32_16x16x32_bf16 v[124:127], v[144:147], v[186:189], v[124:127]
	v_mfma_f32_16x16x32_bf16 v[120:123], v[152:155], v[186:189], v[120:123]
	v_mfma_f32_16x16x32_bf16 v[112:115], v[144:147], v[194:197], v[112:115]
	v_mfma_f32_16x16x32_bf16 v[104:107], v[152:155], v[194:197], v[104:107]
	v_mfma_f32_16x16x32_bf16 v[96:99], v[144:147], v[202:205], v[96:99]
	v_mfma_f32_16x16x32_bf16 v[88:91], v[152:155], v[202:205], v[88:91]
	v_mfma_f32_16x16x32_bf16 v[80:83], v[144:147], v[212:215], v[80:83]
	v_mfma_f32_16x16x32_bf16 v[72:75], v[152:155], v[212:215], v[72:75]
	v_mfma_f32_16x16x32_bf16 v[124:127], v[148:151], v[190:193], v[124:127]
	v_mfma_f32_16x16x32_bf16 v[120:123], v[162:165], v[190:193], v[120:123]
	v_mfma_f32_16x16x32_bf16 v[112:115], v[148:151], v[198:201], v[112:115]
	v_mfma_f32_16x16x32_bf16 v[104:107], v[162:165], v[198:201], v[104:107]
	v_mfma_f32_16x16x32_bf16 v[96:99], v[148:151], v[208:211], v[96:99]
	v_mfma_f32_16x16x32_bf16 v[88:91], v[162:165], v[208:211], v[88:91]
	v_mfma_f32_16x16x32_bf16 v[80:83], v[148:151], v[216:219], v[80:83]
	v_mfma_f32_16x16x32_bf16 v[72:75], v[162:165], v[216:219], v[72:75]
	v_mfma_f32_16x16x32_bf16 v[116:119], v[166:169], v[186:189], v[116:119]
	v_mfma_f32_16x16x32_bf16 v[108:111], v[178:181], v[186:189], v[108:111]
	v_mfma_f32_16x16x32_bf16 v[100:103], v[166:169], v[194:197], v[100:103]
	v_mfma_f32_16x16x32_bf16 v[92:95], v[178:181], v[194:197], v[92:95]
	v_mfma_f32_16x16x32_bf16 v[84:87], v[166:169], v[202:205], v[84:87]
	v_mfma_f32_16x16x32_bf16 v[76:79], v[178:181], v[202:205], v[76:79]
	v_mfma_f32_16x16x32_bf16 v[68:71], v[166:169], v[212:215], v[68:71]
	v_mfma_f32_16x16x32_bf16 v[64:67], v[178:181], v[212:215], v[64:67]
	v_mfma_f32_16x16x32_bf16 v[116:119], v[170:173], v[190:193], v[116:119]
	v_mfma_f32_16x16x32_bf16 v[108:111], v[182:185], v[190:193], v[108:111]
	v_mfma_f32_16x16x32_bf16 v[100:103], v[170:173], v[198:201], v[100:103]
	v_mfma_f32_16x16x32_bf16 v[92:95], v[182:185], v[198:201], v[92:95]
	v_mfma_f32_16x16x32_bf16 v[84:87], v[170:173], v[208:211], v[84:87]
	v_mfma_f32_16x16x32_bf16 v[76:79], v[182:185], v[208:211], v[76:79]
	v_mfma_f32_16x16x32_bf16 v[68:71], v[170:173], v[216:219], v[68:71]
	v_mfma_f32_16x16x32_bf16 v[64:67], v[182:185], v[216:219], v[64:67]
	s_setprio 0
	s_barrier
	s_add_i32 s64, s51, s40
	v_lshl_add_u64 v[174:175], s[34:35], 0, v[130:131]
	s_mov_b32 m0, s64
	ds_read_b128 v[186:189], v161 offset:16384
	ds_read_b128 v[190:193], v161 offset:17408
	ds_read_b128 v[194:197], v161 offset:18432
	ds_read_b128 v[198:201], v161 offset:19456
	ds_read_b128 v[202:205], v161 offset:20480
	ds_read_b128 v[208:211], v161 offset:21504
	ds_read_b128 v[212:215], v161 offset:22528
	ds_read_b128 v[216:219], v161 offset:23552
	global_load_lds_dwordx4 v[174:175], off
	s_add_i32 m0, s64, 0x2000
	s_add_u32 s64, s34, 0x160000
	v_lshl_add_u64 v[220:221], s[34:35], 0, v[134:135]
	s_addc_u32 s65, s35, 0
	s_add_i32 s66, s52, s40
	global_load_lds_dwordx4 v[220:221], off
	v_lshl_add_u64 v[222:223], s[64:65], 0, v[130:131]
	s_mov_b32 m0, s66
	v_lshl_add_u64 v[224:225], s[36:37], 0, v[132:133]
	global_load_lds_dwordx4 v[222:223], off
	v_lshl_add_u64 v[222:223], s[64:65], 0, v[134:135]
	s_add_i32 m0, s66, 0x2000
	s_nop 0
	global_load_lds_dwordx4 v[222:223], off
	v_lshl_add_u64 v[222:223], s[36:37], 0, v[128:129]
	s_mov_b32 m0, s41
	s_nop 0
	global_load_lds_dwordx4 v[222:223], off
	s_mov_b32 m0, s42
	s_nop 0
	global_load_lds_dwordx4 v[224:225], off
	s_waitcnt vmcnt(8)
	s_waitcnt lgkmcnt(0)
	s_barrier
; #define PG8_STAGE(bufoff, gbase, voff) do { _Pragma("unroll") for (int _i = 0; _i < 2; ++_i) \
;         __builtin_amdgcn_global_load_lds((const unsigned*)((const char*)(gbase) + (voff)[_i]), (LAS unsigned*)(lds + (bufoff) + ldsw + _i * 8192), 16, 0, 0); } while (0)
; #define PG8_LDA(dst, b, h) do { _Pragma("unroll") for (int m = 0; m < 4; ++m) _Pragma("unroll") for (int k = 0; k < 2; ++k) dst[m][k] = *(const LAS bf16x8*)(lds + PG8_SA(b, h) + aoff + m * 2048 + k * 1024); } while (0)
; #define PG8_LDB(dst, b, h) do { _Pragma("unroll") for (int n = 0; n < 2; ++n) _Pragma("unroll") for (int k = 0; k < 2; ++k) dst[n][k] = *(const LAS bf16x8*)(lds + PG8_SB(b, h) + boff + n * 2048 + k * 1024); } while (0)
; #define PG8_MMA(ai, bj, At, Bt) do { __builtin_amdgcn_s_setprio(1); _Pragma("unroll") for (int m = 0; m < 4; ++m) _Pragma("unroll") for (int n = 0; n < 2; ++n) _Pragma("unroll") for (int k = 0; k < 2; ++k) \
;         acc[ai][bj][m][n] = __builtin_amdgcn_mfma_f32_16x16x32_bf16(Bt[n][k], At[m][k], acc[ai][bj][m][n], 0, 0, 0); __builtin_amdgcn_s_setprio(0); } while (0)
; #define PG8_WAIT_V(n) asm volatile("s_waitcnt vmcnt(" #n ")" ::: "memory")
; #define PG8_WAIT_L(n) asm volatile("s_waitcnt lgkmcnt(" #n ")" ::: "memory")
; #define PG8_BAR __builtin_amdgcn_s_barrier()
; #define PG8_SCHED __builtin_amdgcn_sched_barrier(0)
; template <class Epi>
; __device__ __forceinline__ void gemm_phase(LAS unsigned char* lds, const Gemm g, const Order& S, const Epi& E) {
;     ...
;             PG8_WAIT_V(8); PG8_WAIT_L(0); PG8_BAR; PG8_MMA(1, 0, At, B0); PG8_MMA(1, 1, At, B1); PG8_BAR; PG8_SCHED;
;             PG8_LDB(B0, 1, 0); PG8_LDB(B1, 1, 1); PG8_SCHED; PG8_LDA(At, 1, 0); PG8_STAGE(PG8_SA(0, 1), a2 + hstepA, voffA);
;             PG8_WAIT_V(8); PG8_WAIT_L(0); PG8_BAR; PG8_MMA(0, 0, At, B0); PG8_MMA(0, 1, At, B1); PG8_BAR; PG8_SCHED;
	s_setprio 1
	s_waitcnt lgkmcnt(0)
	v_mfma_f32_16x16x32_bf16 v[60:63], v[144:147], v[186:189], v[60:63]
	v_mfma_f32_16x16x32_bf16 v[56:59], v[152:155], v[186:189], v[56:59]
	v_mfma_f32_16x16x32_bf16 v[48:51], v[144:147], v[194:197], v[48:51]
	v_mfma_f32_16x16x32_bf16 v[40:43], v[152:155], v[194:197], v[40:43]
	v_mfma_f32_16x16x32_bf16 v[32:35], v[144:147], v[202:205], v[32:35]
	v_mfma_f32_16x16x32_bf16 v[24:27], v[152:155], v[202:205], v[24:27]
	v_mfma_f32_16x16x32_bf16 v[16:19], v[144:147], v[212:215], v[16:19]
	v_mfma_f32_16x16x32_bf16 v[8:11], v[152:155], v[212:215], v[8:11]
	v_mfma_f32_16x16x32_bf16 v[60:63], v[148:151], v[190:193], v[60:63]
	v_mfma_f32_16x16x32_bf16 v[56:59], v[162:165], v[190:193], v[56:59]
	v_mfma_f32_16x16x32_bf16 v[48:51], v[148:151], v[198:201], v[48:51]
	v_mfma_f32_16x16x32_bf16 v[40:43], v[162:165], v[198:201], v[40:43]
	v_mfma_f32_16x16x32_bf16 v[32:35], v[148:151], v[208:211], v[32:35]
	v_mfma_f32_16x16x32_bf16 v[24:27], v[162:165], v[208:211], v[24:27]
	v_mfma_f32_16x16x32_bf16 v[16:19], v[148:151], v[216:219], v[16:19]
	v_mfma_f32_16x16x32_bf16 v[8:11], v[162:165], v[216:219], v[8:11]
	v_mfma_f32_16x16x32_bf16 v[52:55], v[166:169], v[186:189], v[52:55]
	v_mfma_f32_16x16x32_bf16 v[44:47], v[178:181], v[186:189], v[44:47]
	v_mfma_f32_16x16x32_bf16 v[36:39], v[166:169], v[194:197], v[36:39]
	v_mfma_f32_16x16x32_bf16 v[28:31], v[178:181], v[194:197], v[28:31]
	v_mfma_f32_16x16x32_bf16 v[20:23], v[166:169], v[202:205], v[20:23]
	v_mfma_f32_16x16x32_bf16 v[12:15], v[178:181], v[202:205], v[12:15]
	v_mfma_f32_16x16x32_bf16 v[4:7], v[166:169], v[212:215], v[4:7]
	v_mfma_f32_16x16x32_bf16 v[0:3], v[178:181], v[212:215], v[0:3]
	v_mfma_f32_16x16x32_bf16 v[52:55], v[170:173], v[190:193], v[52:55]
	v_mfma_f32_16x16x32_bf16 v[44:47], v[182:185], v[190:193], v[44:47]
	v_mfma_f32_16x16x32_bf16 v[36:39], v[170:173], v[198:201], v[36:39]
	v_mfma_f32_16x16x32_bf16 v[28:31], v[182:185], v[198:201], v[28:31]
	v_mfma_f32_16x16x32_bf16 v[20:23], v[170:173], v[208:211], v[20:23]
	v_mfma_f32_16x16x32_bf16 v[12:15], v[182:185], v[208:211], v[12:15]
	v_mfma_f32_16x16x32_bf16 v[4:7], v[170:173], v[216:219], v[4:7]
	v_mfma_f32_16x16x32_bf16 v[0:3], v[182:185], v[216:219], v[0:3]
	s_setprio 0
	s_barrier
	s_add_i32 s64, 0, 0x18000
	s_add_i32 s65, 0, 0x1c000
	v_add_u32_e32 v162, s64, v157
	v_add_u32_e32 v177, s65, v157
	ds_read_b128 v[144:147], v162
	ds_read_b128 v[148:151], v162 offset:1024
	ds_read_b128 v[152:155], v162 offset:2048
	ds_read_b128 v[162:165], v162 offset:3072
	ds_read_b128 v[166:169], v177
	ds_read_b128 v[170:173], v177 offset:1024
	ds_read_b128 v[178:181], v177 offset:2048
	ds_read_b128 v[182:185], v177 offset:3072
	s_add_u32 s36, s36, 0x160000
	s_addc_u32 s37, s37, 0
	s_mov_b32 m0, s43
	v_lshl_add_u64 v[226:227], s[36:37], 0, v[128:129]
	ds_read_b128 v[186:189], v161 offset:32768
	ds_read_b128 v[190:193], v161 offset:33792
	ds_read_b128 v[194:197], v161 offset:34816
	ds_read_b128 v[198:201], v161 offset:35840
	ds_read_b128 v[202:205], v161 offset:36864
	ds_read_b128 v[208:211], v161 offset:37888
	ds_read_b128 v[212:215], v161 offset:38912
	ds_read_b128 v[216:219], v161 offset:39936
	global_load_lds_dwordx4 v[226:227], off
	v_lshl_add_u64 v[226:227], s[36:37], 0, v[132:133]
	s_mov_b32 m0, s46
	s_nop 0
	global_load_lds_dwordx4 v[226:227], off
	s_waitcnt vmcnt(8)
	s_waitcnt lgkmcnt(0)
	s_barrier
	s_setprio 1
	s_waitcnt lgkmcnt(0)
	v_mfma_f32_16x16x32_bf16 v[124:127], v[144:147], v[186:189], v[124:127]
	v_mfma_f32_16x16x32_bf16 v[120:123], v[152:155], v[186:189], v[120:123]
	v_mfma_f32_16x16x32_bf16 v[112:115], v[144:147], v[194:197], v[112:115]
	v_mfma_f32_16x16x32_bf16 v[104:107], v[152:155], v[194:197], v[104:107]
	v_mfma_f32_16x16x32_bf16 v[96:99], v[144:147], v[202:205], v[96:99]
	v_mfma_f32_16x16x32_bf16 v[88:91], v[152:155], v[202:205], v[88:91]
	v_mfma_f32_16x16x32_bf16 v[80:83], v[144:147], v[212:215], v[80:83]
	v_mfma_f32_16x16x32_bf16 v[72:75], v[152:155], v[212:215], v[72:75]
	v_mfma_f32_16x16x32_bf16 v[124:127], v[148:151], v[190:193], v[124:127]
	v_mfma_f32_16x16x32_bf16 v[120:123], v[162:165], v[190:193], v[120:123]
	v_mfma_f32_16x16x32_bf16 v[112:115], v[148:151], v[198:201], v[112:115]
	v_mfma_f32_16x16x32_bf16 v[104:107], v[162:165], v[198:201], v[104:107]
	v_mfma_f32_16x16x32_bf16 v[96:99], v[148:151], v[208:211], v[96:99]
	v_mfma_f32_16x16x32_bf16 v[88:91], v[162:165], v[208:211], v[88:91]
	v_mfma_f32_16x16x32_bf16 v[80:83], v[148:151], v[216:219], v[80:83]
	v_mfma_f32_16x16x32_bf16 v[72:75], v[162:165], v[216:219], v[72:75]
	v_mfma_f32_16x16x32_bf16 v[116:119], v[166:169], v[186:189], v[116:119]
	v_mfma_f32_16x16x32_bf16 v[108:111], v[178:181], v[186:189], v[108:111]
	v_mfma_f32_16x16x32_bf16 v[100:103], v[166:169], v[194:197], v[100:103]
	v_mfma_f32_16x16x32_bf16 v[92:95], v[178:181], v[194:197], v[92:95]
	v_mfma_f32_16x16x32_bf16 v[84:87], v[166:169], v[202:205], v[84:87]
	v_mfma_f32_16x16x32_bf16 v[76:79], v[178:181], v[202:205], v[76:79]
	v_mfma_f32_16x16x32_bf16 v[68:71], v[166:169], v[212:215], v[68:71]
	v_mfma_f32_16x16x32_bf16 v[64:67], v[178:181], v[212:215], v[64:67]
	v_mfma_f32_16x16x32_bf16 v[116:119], v[170:173], v[190:193], v[116:119]
	v_mfma_f32_16x16x32_bf16 v[108:111], v[182:185], v[190:193], v[108:111]
	v_mfma_f32_16x16x32_bf16 v[100:103], v[170:173], v[198:201], v[100:103]
	v_mfma_f32_16x16x32_bf16 v[92:95], v[182:185], v[198:201], v[92:95]
	v_mfma_f32_16x16x32_bf16 v[84:87], v[170:173], v[208:211], v[84:87]
	v_mfma_f32_16x16x32_bf16 v[76:79], v[182:185], v[208:211], v[76:79]
	v_mfma_f32_16x16x32_bf16 v[68:71], v[170:173], v[216:219], v[68:71]
	v_mfma_f32_16x16x32_bf16 v[64:67], v[182:185], v[216:219], v[64:67]
	s_setprio 0
	s_barrier
; #define PG8_STAGE(bufoff, gbase, voff) do { _Pragma("unroll") for (int _i = 0; _i < 2; ++_i) \
;         __builtin_amdgcn_global_load_lds((const unsigned*)((const char*)(gbase) + (voff)[_i]), (LAS unsigned*)(lds + (bufoff) + ldsw + _i * 8192), 16, 0, 0); } while (0)
; #define PG8_LDA(dst, b, h) do { _Pragma("unroll") for (int m = 0; m < 4; ++m) _Pragma("unroll") for (int k = 0; k < 2; ++k) dst[m][k] = *(const LAS bf16x8*)(lds + PG8_SA(b, h) + aoff + m * 2048 + k * 1024); } while (0)
; #define PG8_MMA(ai, bj, At, Bt) do { __builtin_amdgcn_s_setprio(1); _Pragma("unroll") for (int m = 0; m < 4; ++m) _Pragma("unroll") for (int n = 0; n < 2; ++n) _Pragma("unroll") for (int k = 0; k < 2; ++k) \
;         acc[ai][bj][m][n] = __builtin_amdgcn_mfma_f32_16x16x32_bf16(Bt[n][k], At[m][k], acc[ai][bj][m][n], 0, 0, 0); __builtin_amdgcn_s_setprio(0); } while (0)
; #define PG8_WAIT_V(n) asm volatile("s_waitcnt vmcnt(" #n ")" ::: "memory")
; #define PG8_WAIT_L(n) asm volatile("s_waitcnt lgkmcnt(" #n ")" ::: "memory")
; #define PG8_BAR __builtin_amdgcn_s_barrier()
; #define PG8_SCHED __builtin_amdgcn_sched_barrier(0)
; template <class Epi>
; __device__ __forceinline__ void gemm_phase(LAS unsigned char* lds, const Gemm g, const Order& S, const Epi& E) {
;     ...
;             PG8_LDA(At, 1, 1); PG8_STAGE(PG8_SB(1, 0), b3, voffB); PG8_STAGE(PG8_SB(1, 1), b3 + hstepB, voffB); PG8_STAGE(PG8_SA(1, 0), a3, voffA);
;             PG8_WAIT_V(8); PG8_WAIT_L(0); PG8_BAR; PG8_MMA(1, 0, At, B0); PG8_MMA(1, 1, At, B1); PG8_BAR; PG8_SCHED;
;         }
;         if (wr == 0) PG8_BAR;
	s_add_i32 s36, s64, s40
	v_lshl_add_u64 v[174:175], v[174:175], 0, s[10:11]
	s_mov_b32 m0, s36
	ds_read_b128 v[186:189], v161 offset:49152
	ds_read_b128 v[190:193], v161 offset:50176
	ds_read_b128 v[194:197], v161 offset:51200
	ds_read_b128 v[198:201], v161 offset:52224
	ds_read_b128 v[202:205], v161 offset:53248
	ds_read_b128 v[208:211], v161 offset:54272
	ds_read_b128 v[212:215], v161 offset:55296
	ds_read_b128 v[216:219], v161 offset:56320
	global_load_lds_dwordx4 v[174:175], off
	s_add_i32 m0, s36, 0x2000
	s_add_u32 s34, s34, 0x160080
	v_lshl_add_u64 v[174:175], v[220:221], 0, s[10:11]
	s_addc_u32 s35, s35, 0
	s_add_i32 s36, s65, s40
	global_load_lds_dwordx4 v[174:175], off
	v_lshl_add_u64 v[174:175], s[34:35], 0, v[130:131]
	s_mov_b32 m0, s36
	s_nop 0
	global_load_lds_dwordx4 v[174:175], off
	v_lshl_add_u64 v[174:175], s[34:35], 0, v[134:135]
	s_add_i32 m0, s36, 0x2000
	s_nop 0
	global_load_lds_dwordx4 v[174:175], off
	v_lshl_add_u64 v[174:175], v[222:223], 0, s[10:11]
	s_mov_b32 m0, s48
	s_nop 0
	global_load_lds_dwordx4 v[174:175], off
	v_lshl_add_u64 v[174:175], v[224:225], 0, s[10:11]
	s_mov_b32 m0, s49
	s_nop 0
	global_load_lds_dwordx4 v[174:175], off
	s_waitcnt vmcnt(8)
	s_waitcnt lgkmcnt(0)
	s_barrier
	s_setprio 1
	s_waitcnt lgkmcnt(0)
	v_mfma_f32_16x16x32_bf16 v[60:63], v[144:147], v[186:189], v[60:63]
	v_mfma_f32_16x16x32_bf16 v[56:59], v[152:155], v[186:189], v[56:59]
	v_mfma_f32_16x16x32_bf16 v[48:51], v[144:147], v[194:197], v[48:51]
	v_mfma_f32_16x16x32_bf16 v[40:43], v[152:155], v[194:197], v[40:43]
	v_mfma_f32_16x16x32_bf16 v[32:35], v[144:147], v[202:205], v[32:35]
	v_mfma_f32_16x16x32_bf16 v[24:27], v[152:155], v[202:205], v[24:27]
	v_mfma_f32_16x16x32_bf16 v[16:19], v[144:147], v[212:215], v[16:19]
	v_mfma_f32_16x16x32_bf16 v[8:11], v[152:155], v[212:215], v[8:11]
	v_mfma_f32_16x16x32_bf16 v[60:63], v[148:151], v[190:193], v[60:63]
	v_mfma_f32_16x16x32_bf16 v[56:59], v[162:165], v[190:193], v[56:59]
	v_mfma_f32_16x16x32_bf16 v[48:51], v[148:151], v[198:201], v[48:51]
	v_mfma_f32_16x16x32_bf16 v[40:43], v[162:165], v[198:201], v[40:43]
	v_mfma_f32_16x16x32_bf16 v[32:35], v[148:151], v[208:211], v[32:35]
	v_mfma_f32_16x16x32_bf16 v[24:27], v[162:165], v[208:211], v[24:27]
	v_mfma_f32_16x16x32_bf16 v[16:19], v[148:151], v[216:219], v[16:19]
	v_mfma_f32_16x16x32_bf16 v[8:11], v[162:165], v[216:219], v[8:11]
	v_mfma_f32_16x16x32_bf16 v[52:55], v[166:169], v[186:189], v[52:55]
	v_mfma_f32_16x16x32_bf16 v[44:47], v[178:181], v[186:189], v[44:47]
	v_mfma_f32_16x16x32_bf16 v[36:39], v[166:169], v[194:197], v[36:39]
	v_mfma_f32_16x16x32_bf16 v[28:31], v[178:181], v[194:197], v[28:31]
	v_mfma_f32_16x16x32_bf16 v[20:23], v[166:169], v[202:205], v[20:23]
	v_mfma_f32_16x16x32_bf16 v[12:15], v[178:181], v[202:205], v[12:15]
	v_mfma_f32_16x16x32_bf16 v[4:7], v[166:169], v[212:215], v[4:7]
	v_mfma_f32_16x16x32_bf16 v[0:3], v[178:181], v[212:215], v[0:3]
	v_mfma_f32_16x16x32_bf16 v[52:55], v[170:173], v[190:193], v[52:55]
	v_mfma_f32_16x16x32_bf16 v[44:47], v[182:185], v[190:193], v[44:47]
	v_mfma_f32_16x16x32_bf16 v[36:39], v[170:173], v[198:201], v[36:39]
	v_mfma_f32_16x16x32_bf16 v[28:31], v[182:185], v[198:201], v[28:31]
	v_mfma_f32_16x16x32_bf16 v[20:23], v[170:173], v[208:211], v[20:23]
	v_mfma_f32_16x16x32_bf16 v[12:15], v[182:185], v[208:211], v[12:15]
	v_mfma_f32_16x16x32_bf16 v[4:7], v[170:173], v[216:219], v[4:7]
	v_mfma_f32_16x16x32_bf16 v[0:3], v[182:185], v[216:219], v[0:3]
	s_setprio 0
	s_barrier
	s_add_i32 s63, s63, 2
	s_add_u32 s30, s30, 0x100
	s_addc_u32 s31, s31, 0
	s_add_u32 s61, s61, 0x100
	s_addc_u32 s62, s62, 0
	s_cmpk_gt_u32 s63, 0x55
	s_cbranch_scc0 .LBB0_1023
	s_and_b64 vcc, exec, s[12:13]
	s_cbranch_vccz .LBB0_1026
	s_barrier
